# mid-block s_setprio 0/1 pairs removed from the K-loops
# baseline (speedup 1.0000x reference)
; #define PG8_STAGE(bufoff, gbase, voff) do { _Pragma("unroll") for (int _i = 0; _i < 2; ++_i) \
;         __builtin_amdgcn_global_load_lds((const unsigned*)((const char*)(gbase) + (voff)[_i]), (PG8_LAS unsigned*)(lds + (bufoff) + ldsw + _i * 8192), 16, 0, 0); } while (0)
; #define PG8_LDA(dst, b, h) do { _Pragma("unroll") for (int m = 0; m < 4; ++m) _Pragma("unroll") for (int k = 0; k < 2; ++k) dst[m][k] = *(const PG8_LAS bf16x8*)(lds + PG8_SA(b, h) + aoff + m * 2048 + k * 1024); } while (0)
; #define PG8_LDB(dst, b, h) do { _Pragma("unroll") for (int n = 0; n < 2; ++n) _Pragma("unroll") for (int k = 0; k < 2; ++k) dst[n][k] = *(const PG8_LAS bf16x8*)(lds + PG8_SB(b, h) + boff + n * 2048 + k * 1024); } while (0)
; #define PG8_MMA(ai, bj, At, Bt) do { __builtin_amdgcn_s_setprio(1); _Pragma("unroll") for (int m = 0; m < 4; ++m) _Pragma("unroll") for (int n = 0; n < 2; ++n) _Pragma("unroll") for (int k = 0; k < 2; ++k) \
;         acc[ai][bj][m][n] = __builtin_amdgcn_mfma_f32_16x16x32_bf16(Bt[n][k], At[m][k], acc[ai][bj][m][n], 0, 0, 0); __builtin_amdgcn_s_setprio(0); } while (0)
; #define PG8_WAIT_V(n) asm volatile("s_waitcnt vmcnt(" #n ")" ::: "memory")
; #define PG8_WAIT_L(n) asm volatile("s_waitcnt lgkmcnt(" #n ")" ::: "memory")
; #define PG8_BAR __builtin_amdgcn_s_barrier()
; #define PG8_SCHED __builtin_amdgcn_sched_barrier(0)
; template <class Epi, class Sched, bool ALIGN_EPI = false, bool SP2 = false>
; __device__ __forceinline__ void gemm_phase(PG8_LAS unsigned char* lds, const Gemm g, const Sched& S, const Epi& E) {
;     ...
;             const bool last = (t == nt - 2);
;             const char* a1 = cA + (size_t)(t + 1) * kstep;
;             const char* a2 = last ? nA : cA + (size_t)(t + 2) * kstep; const char* b2 = last ? nB : cB + (size_t)(t + 2) * kstep;
;             const char* a3 = a2 + kstep; const char* b3 = b2 + kstep;
;             if (last && has_next) S.a_ready(nxt);
;             if constexpr (SP2) {
;             PG8_LDB(B0, 0, 0); PG8_LDB(B1, 0, 1); PG8_SCHED; PG8_LDA(At, 0, 0); PG8_STAGE(PG8_SA(1, 1), a1 + hstep, voffA);
;             PG8_WAIT_V(8); PG8_WAIT_L(0); PG8_BAR; PG8_MMA(0, 0, At, B0); PG8_MMA(0, 1, At, B1); PG8_BAR; PG8_SCHED;
;             PG8_LDA(At, 0, 1); PG8_STAGE(PG8_SB(0, 0), b2, voffB); PG8_STAGE(PG8_SB(0, 1), b2 + hstep, voffB); PG8_STAGE(PG8_SA(0, 0), a2, voffA);
.LBB0_194:
	ds_read_b128 v[152:155], v149
	ds_read_b128 v[156:159], v149 offset:1024
	ds_read_b128 v[162:165], v149 offset:2048
	ds_read_b128 v[166:169], v149 offset:3072
	ds_read_b128 v[170:173], v150
	ds_read_b128 v[174:177], v150 offset:1024
	ds_read_b128 v[178:181], v150 offset:2048
	ds_read_b128 v[182:185], v150 offset:3072
	s_add_u32 s40, s38, 0xfffc0080
	s_addc_u32 s41, s39, -1
	s_cmp_eq_u32 s78, 12
	s_cselect_b32 s53, s19, s41
	s_cselect_b32 s52, s72, s40
	s_cselect_b32 s41, s17, s77
	s_cselect_b32 s40, s73, s76
	v_lshl_add_u64 v[144:145], s[38:39], 0, v[136:137]
	s_add_i32 m0, s37, 0xc000
	ds_read_b128 v[186:189], v151
	ds_read_b128 v[190:193], v151 offset:1024
	ds_read_b128 v[194:197], v151 offset:2048
	ds_read_b128 v[198:201], v151 offset:3072
	ds_read_b128 v[202:205], v151 offset:4096
	ds_read_b128 v[206:209], v151 offset:5120
	ds_read_b128 v[210:213], v151 offset:6144
	ds_read_b128 v[214:217], v151 offset:7168
	global_load_lds_dwordx4 v[144:145], off
	v_lshl_add_u64 v[144:145], s[38:39], 0, v[138:139]
	s_add_i32 m0, s37, 0xe000
	s_nop 0
	global_load_lds_dwordx4 v[144:145], off
	s_waitcnt vmcnt(8)
	s_waitcnt lgkmcnt(0)
	s_barrier
	s_setprio 1
	s_waitcnt lgkmcnt(0)
	v_mfma_f32_16x16x32_bf16 v[124:127], v[152:155], v[186:189], v[124:127]
	v_mfma_f32_16x16x32_bf16 v[116:119], v[162:165], v[186:189], v[116:119]
	v_mfma_f32_16x16x32_bf16 v[108:111], v[152:155], v[194:197], v[108:111]
	v_mfma_f32_16x16x32_bf16 v[100:103], v[162:165], v[194:197], v[100:103]
	v_mfma_f32_16x16x32_bf16 v[92:95], v[152:155], v[202:205], v[92:95]
	v_mfma_f32_16x16x32_bf16 v[84:87], v[162:165], v[202:205], v[84:87]
	v_mfma_f32_16x16x32_bf16 v[76:79], v[152:155], v[210:213], v[76:79]
	v_mfma_f32_16x16x32_bf16 v[68:71], v[162:165], v[210:213], v[68:71]
	v_mfma_f32_16x16x32_bf16 v[124:127], v[156:159], v[190:193], v[124:127]
	v_mfma_f32_16x16x32_bf16 v[116:119], v[166:169], v[190:193], v[116:119]
	v_mfma_f32_16x16x32_bf16 v[108:111], v[156:159], v[198:201], v[108:111]
	v_mfma_f32_16x16x32_bf16 v[100:103], v[166:169], v[198:201], v[100:103]
	v_mfma_f32_16x16x32_bf16 v[92:95], v[156:159], v[206:209], v[92:95]
	v_mfma_f32_16x16x32_bf16 v[84:87], v[166:169], v[206:209], v[84:87]
	v_mfma_f32_16x16x32_bf16 v[76:79], v[156:159], v[214:217], v[76:79]
	v_mfma_f32_16x16x32_bf16 v[68:71], v[166:169], v[214:217], v[68:71]
	v_mfma_f32_16x16x32_bf16 v[120:123], v[170:173], v[186:189], v[120:123]
	v_mfma_f32_16x16x32_bf16 v[112:115], v[178:181], v[186:189], v[112:115]
	v_mfma_f32_16x16x32_bf16 v[104:107], v[170:173], v[194:197], v[104:107]
	v_mfma_f32_16x16x32_bf16 v[96:99], v[178:181], v[194:197], v[96:99]
	v_mfma_f32_16x16x32_bf16 v[88:91], v[170:173], v[202:205], v[88:91]
	v_mfma_f32_16x16x32_bf16 v[80:83], v[178:181], v[202:205], v[80:83]
	v_mfma_f32_16x16x32_bf16 v[72:75], v[170:173], v[210:213], v[72:75]
	v_mfma_f32_16x16x32_bf16 v[64:67], v[178:181], v[210:213], v[64:67]
	v_mfma_f32_16x16x32_bf16 v[120:123], v[174:177], v[190:193], v[120:123]
	v_mfma_f32_16x16x32_bf16 v[112:115], v[182:185], v[190:193], v[112:115]
	v_mfma_f32_16x16x32_bf16 v[104:107], v[174:177], v[198:201], v[104:107]
	v_mfma_f32_16x16x32_bf16 v[96:99], v[182:185], v[198:201], v[96:99]
	v_mfma_f32_16x16x32_bf16 v[88:91], v[174:177], v[206:209], v[88:91]
	v_mfma_f32_16x16x32_bf16 v[80:83], v[182:185], v[206:209], v[80:83]
	v_mfma_f32_16x16x32_bf16 v[72:75], v[174:177], v[214:217], v[72:75]
	v_mfma_f32_16x16x32_bf16 v[64:67], v[182:185], v[214:217], v[64:67]
	s_setprio 0
	s_barrier
	s_add_i32 s79, s66, s3
	v_lshl_add_u64 v[144:145], s[40:41], 0, v[132:133]
	s_mov_b32 m0, s79
	ds_read_b128 v[186:189], v151 offset:16384
	ds_read_b128 v[190:193], v151 offset:17408
	ds_read_b128 v[194:197], v151 offset:18432
	ds_read_b128 v[198:201], v151 offset:19456
	ds_read_b128 v[202:205], v151 offset:20480
	ds_read_b128 v[206:209], v151 offset:21504
	ds_read_b128 v[210:213], v151 offset:22528
	ds_read_b128 v[214:217], v151 offset:23552
	global_load_lds_dwordx4 v[144:145], off
	s_add_i32 m0, s79, 0x2000
	s_add_u32 s80, s40, 0x40000
	v_lshl_add_u64 v[218:219], s[40:41], 0, v[128:129]
	s_addc_u32 s81, s41, 0
	s_add_i32 s79, s67, s3
	global_load_lds_dwordx4 v[218:219], off
	v_lshl_add_u64 v[220:221], s[80:81], 0, v[132:133]
	s_mov_b32 m0, s79
	v_lshl_add_u64 v[222:223], s[52:53], 0, v[130:131]
	global_load_lds_dwordx4 v[220:221], off
	v_lshl_add_u64 v[220:221], s[80:81], 0, v[128:129]
	s_add_i32 m0, s79, 0x2000
	s_nop 0
	global_load_lds_dwordx4 v[220:221], off
	v_lshl_add_u64 v[220:221], s[52:53], 0, v[134:135]
	s_mov_b32 m0, s37
	s_nop 0
	global_load_lds_dwordx4 v[220:221], off
	s_mov_b32 m0, s56
	s_nop 0
	global_load_lds_dwordx4 v[222:223], off
	s_waitcnt vmcnt(8)
	s_waitcnt lgkmcnt(0)
	s_barrier
; #define PG8_STAGE(bufoff, gbase, voff) do { _Pragma("unroll") for (int _i = 0; _i < 2; ++_i) \
;         __builtin_amdgcn_global_load_lds((const unsigned*)((const char*)(gbase) + (voff)[_i]), (PG8_LAS unsigned*)(lds + (bufoff) + ldsw + _i * 8192), 16, 0, 0); } while (0)
; #define PG8_LDA(dst, b, h) do { _Pragma("unroll") for (int m = 0; m < 4; ++m) _Pragma("unroll") for (int k = 0; k < 2; ++k) dst[m][k] = *(const PG8_LAS bf16x8*)(lds + PG8_SA(b, h) + aoff + m * 2048 + k * 1024); } while (0)
; #define PG8_LDB(dst, b, h) do { _Pragma("unroll") for (int n = 0; n < 2; ++n) _Pragma("unroll") for (int k = 0; k < 2; ++k) dst[n][k] = *(const PG8_LAS bf16x8*)(lds + PG8_SB(b, h) + boff + n * 2048 + k * 1024); } while (0)
; #define PG8_MMA(ai, bj, At, Bt) do { __builtin_amdgcn_s_setprio(1); _Pragma("unroll") for (int m = 0; m < 4; ++m) _Pragma("unroll") for (int n = 0; n < 2; ++n) _Pragma("unroll") for (int k = 0; k < 2; ++k) \
;         acc[ai][bj][m][n] = __builtin_amdgcn_mfma_f32_16x16x32_bf16(Bt[n][k], At[m][k], acc[ai][bj][m][n], 0, 0, 0); __builtin_amdgcn_s_setprio(0); } while (0)
; #define PG8_WAIT_V(n) asm volatile("s_waitcnt vmcnt(" #n ")" ::: "memory")
; #define PG8_WAIT_L(n) asm volatile("s_waitcnt lgkmcnt(" #n ")" ::: "memory")
; #define PG8_BAR __builtin_amdgcn_s_barrier()
; #define PG8_SCHED __builtin_amdgcn_sched_barrier(0)
; template <class Epi, class Sched, bool ALIGN_EPI = false, bool SP2 = false>
; __device__ __forceinline__ void gemm_phase(PG8_LAS unsigned char* lds, const Gemm g, const Sched& S, const Epi& E) {
;     ...
;             PG8_LDA(At, 0, 1); PG8_STAGE(PG8_SB(0, 0), b2, voffB); PG8_STAGE(PG8_SB(0, 1), b2 + hstep, voffB); PG8_STAGE(PG8_SA(0, 0), a2, voffA);
;             PG8_WAIT_V(8); PG8_WAIT_L(0); PG8_BAR; PG8_MMA(1, 0, At, B0); PG8_MMA(1, 1, At, B1); PG8_BAR; PG8_SCHED;
;             PG8_LDB(B0, 1, 0); PG8_LDB(B1, 1, 1); PG8_SCHED; PG8_LDA(At, 1, 0); PG8_STAGE(PG8_SA(0, 1), a2 + hstep, voffA);
;             PG8_WAIT_V(8); PG8_WAIT_L(0); PG8_BAR; PG8_MMA(0, 0, At, B0); PG8_MMA(0, 1, At, B1); PG8_BAR; PG8_SCHED;
	s_setprio 1
	s_waitcnt lgkmcnt(0)
	v_mfma_f32_16x16x32_bf16 v[60:63], v[152:155], v[186:189], v[60:63]
	v_mfma_f32_16x16x32_bf16 v[52:55], v[162:165], v[186:189], v[52:55]
	v_mfma_f32_16x16x32_bf16 v[44:47], v[152:155], v[194:197], v[44:47]
	v_mfma_f32_16x16x32_bf16 v[36:39], v[162:165], v[194:197], v[36:39]
	v_mfma_f32_16x16x32_bf16 v[28:31], v[152:155], v[202:205], v[28:31]
	v_mfma_f32_16x16x32_bf16 v[20:23], v[162:165], v[202:205], v[20:23]
	v_mfma_f32_16x16x32_bf16 v[12:15], v[152:155], v[210:213], v[12:15]
	v_mfma_f32_16x16x32_bf16 v[4:7], v[162:165], v[210:213], v[4:7]
	v_mfma_f32_16x16x32_bf16 v[60:63], v[156:159], v[190:193], v[60:63]
	v_mfma_f32_16x16x32_bf16 v[52:55], v[166:169], v[190:193], v[52:55]
	v_mfma_f32_16x16x32_bf16 v[44:47], v[156:159], v[198:201], v[44:47]
	v_mfma_f32_16x16x32_bf16 v[36:39], v[166:169], v[198:201], v[36:39]
	v_mfma_f32_16x16x32_bf16 v[28:31], v[156:159], v[206:209], v[28:31]
	v_mfma_f32_16x16x32_bf16 v[20:23], v[166:169], v[206:209], v[20:23]
	v_mfma_f32_16x16x32_bf16 v[12:15], v[156:159], v[214:217], v[12:15]
	v_mfma_f32_16x16x32_bf16 v[4:7], v[166:169], v[214:217], v[4:7]
	v_mfma_f32_16x16x32_bf16 v[56:59], v[170:173], v[186:189], v[56:59]
	v_mfma_f32_16x16x32_bf16 v[48:51], v[178:181], v[186:189], v[48:51]
	v_mfma_f32_16x16x32_bf16 v[40:43], v[170:173], v[194:197], v[40:43]
	v_mfma_f32_16x16x32_bf16 v[32:35], v[178:181], v[194:197], v[32:35]
	v_mfma_f32_16x16x32_bf16 v[24:27], v[170:173], v[202:205], v[24:27]
	v_mfma_f32_16x16x32_bf16 v[16:19], v[178:181], v[202:205], v[16:19]
	v_mfma_f32_16x16x32_bf16 v[8:11], v[170:173], v[210:213], v[8:11]
	v_mfma_f32_16x16x32_bf16 v[0:3], v[178:181], v[210:213], v[0:3]
	v_mfma_f32_16x16x32_bf16 v[56:59], v[174:177], v[190:193], v[56:59]
	v_mfma_f32_16x16x32_bf16 v[48:51], v[182:185], v[190:193], v[48:51]
	v_mfma_f32_16x16x32_bf16 v[40:43], v[174:177], v[198:201], v[40:43]
	v_mfma_f32_16x16x32_bf16 v[32:35], v[182:185], v[198:201], v[32:35]
	v_mfma_f32_16x16x32_bf16 v[24:27], v[174:177], v[206:209], v[24:27]
	v_mfma_f32_16x16x32_bf16 v[16:19], v[182:185], v[206:209], v[16:19]
	v_mfma_f32_16x16x32_bf16 v[8:11], v[174:177], v[214:217], v[8:11]
	v_mfma_f32_16x16x32_bf16 v[0:3], v[182:185], v[214:217], v[0:3]
	s_setprio 0
	s_barrier
	s_add_i32 s79, 0, 0x18000
	v_add_u32_e32 v161, s79, v147
	s_add_i32 s80, 0, 0x1c000
	ds_read_b128 v[152:155], v161
	ds_read_b128 v[156:159], v161 offset:1024
	ds_read_b128 v[162:165], v161 offset:2048
	ds_read_b128 v[166:169], v161 offset:3072
	v_add_u32_e32 v161, s80, v147
	ds_read_b128 v[170:173], v161
	ds_read_b128 v[174:177], v161 offset:1024
	ds_read_b128 v[178:181], v161 offset:2048
	ds_read_b128 v[182:185], v161 offset:3072
	s_add_u32 s52, s52, 0x40000
	s_addc_u32 s53, s53, 0
	s_mov_b32 m0, s57
	v_lshl_add_u64 v[224:225], s[52:53], 0, v[134:135]
	ds_read_b128 v[186:189], v151 offset:32768
	ds_read_b128 v[190:193], v151 offset:33792
	ds_read_b128 v[194:197], v151 offset:34816
	ds_read_b128 v[198:201], v151 offset:35840
	ds_read_b128 v[202:205], v151 offset:36864
	ds_read_b128 v[206:209], v151 offset:37888
	ds_read_b128 v[210:213], v151 offset:38912
	ds_read_b128 v[214:217], v151 offset:39936
	global_load_lds_dwordx4 v[224:225], off
	v_lshl_add_u64 v[224:225], s[52:53], 0, v[130:131]
	s_mov_b32 m0, s58
	s_nop 0
	global_load_lds_dwordx4 v[224:225], off
	s_waitcnt vmcnt(8)
	s_waitcnt lgkmcnt(0)
	s_barrier
	s_setprio 1
	s_waitcnt lgkmcnt(0)
	v_mfma_f32_16x16x32_bf16 v[124:127], v[152:155], v[186:189], v[124:127]
	v_mfma_f32_16x16x32_bf16 v[116:119], v[162:165], v[186:189], v[116:119]
	v_mfma_f32_16x16x32_bf16 v[108:111], v[152:155], v[194:197], v[108:111]
	v_mfma_f32_16x16x32_bf16 v[100:103], v[162:165], v[194:197], v[100:103]
	v_mfma_f32_16x16x32_bf16 v[92:95], v[152:155], v[202:205], v[92:95]
	v_mfma_f32_16x16x32_bf16 v[84:87], v[162:165], v[202:205], v[84:87]
	v_mfma_f32_16x16x32_bf16 v[76:79], v[152:155], v[210:213], v[76:79]
	v_mfma_f32_16x16x32_bf16 v[68:71], v[162:165], v[210:213], v[68:71]
	v_mfma_f32_16x16x32_bf16 v[124:127], v[156:159], v[190:193], v[124:127]
	v_mfma_f32_16x16x32_bf16 v[116:119], v[166:169], v[190:193], v[116:119]
	v_mfma_f32_16x16x32_bf16 v[108:111], v[156:159], v[198:201], v[108:111]
	v_mfma_f32_16x16x32_bf16 v[100:103], v[166:169], v[198:201], v[100:103]
	v_mfma_f32_16x16x32_bf16 v[92:95], v[156:159], v[206:209], v[92:95]
	v_mfma_f32_16x16x32_bf16 v[84:87], v[166:169], v[206:209], v[84:87]
	v_mfma_f32_16x16x32_bf16 v[76:79], v[156:159], v[214:217], v[76:79]
	v_mfma_f32_16x16x32_bf16 v[68:71], v[166:169], v[214:217], v[68:71]
	v_mfma_f32_16x16x32_bf16 v[120:123], v[170:173], v[186:189], v[120:123]
	v_mfma_f32_16x16x32_bf16 v[112:115], v[178:181], v[186:189], v[112:115]
	v_mfma_f32_16x16x32_bf16 v[104:107], v[170:173], v[194:197], v[104:107]
	v_mfma_f32_16x16x32_bf16 v[96:99], v[178:181], v[194:197], v[96:99]
	v_mfma_f32_16x16x32_bf16 v[88:91], v[170:173], v[202:205], v[88:91]
	v_mfma_f32_16x16x32_bf16 v[80:83], v[178:181], v[202:205], v[80:83]
	v_mfma_f32_16x16x32_bf16 v[72:75], v[170:173], v[210:213], v[72:75]
	v_mfma_f32_16x16x32_bf16 v[64:67], v[178:181], v[210:213], v[64:67]
	v_mfma_f32_16x16x32_bf16 v[120:123], v[174:177], v[190:193], v[120:123]
	v_mfma_f32_16x16x32_bf16 v[112:115], v[182:185], v[190:193], v[112:115]
	v_mfma_f32_16x16x32_bf16 v[104:107], v[174:177], v[198:201], v[104:107]
	v_mfma_f32_16x16x32_bf16 v[96:99], v[182:185], v[198:201], v[96:99]
	v_mfma_f32_16x16x32_bf16 v[88:91], v[174:177], v[206:209], v[88:91]
	v_mfma_f32_16x16x32_bf16 v[80:83], v[182:185], v[206:209], v[80:83]
	v_mfma_f32_16x16x32_bf16 v[72:75], v[174:177], v[214:217], v[72:75]
	v_mfma_f32_16x16x32_bf16 v[64:67], v[182:185], v[214:217], v[64:67]
	s_setprio 0
	s_barrier
; #define PG8_STAGE(bufoff, gbase, voff) do { _Pragma("unroll") for (int _i = 0; _i < 2; ++_i) \
;         __builtin_amdgcn_global_load_lds((const unsigned*)((const char*)(gbase) + (voff)[_i]), (PG8_LAS unsigned*)(lds + (bufoff) + ldsw + _i * 8192), 16, 0, 0); } while (0)
; #define PG8_LDA(dst, b, h) do { _Pragma("unroll") for (int m = 0; m < 4; ++m) _Pragma("unroll") for (int k = 0; k < 2; ++k) dst[m][k] = *(const PG8_LAS bf16x8*)(lds + PG8_SA(b, h) + aoff + m * 2048 + k * 1024); } while (0)
; #define PG8_MMA(ai, bj, At, Bt) do { __builtin_amdgcn_s_setprio(1); _Pragma("unroll") for (int m = 0; m < 4; ++m) _Pragma("unroll") for (int n = 0; n < 2; ++n) _Pragma("unroll") for (int k = 0; k < 2; ++k) \
;         acc[ai][bj][m][n] = __builtin_amdgcn_mfma_f32_16x16x32_bf16(Bt[n][k], At[m][k], acc[ai][bj][m][n], 0, 0, 0); __builtin_amdgcn_s_setprio(0); } while (0)
; #define PG8_WAIT_V(n) asm volatile("s_waitcnt vmcnt(" #n ")" ::: "memory")
; #define PG8_WAIT_L(n) asm volatile("s_waitcnt lgkmcnt(" #n ")" ::: "memory")
; #define PG8_BAR __builtin_amdgcn_s_barrier()
; #define PG8_SCHED __builtin_amdgcn_sched_barrier(0)
; template <class Epi, class Sched, bool ALIGN_EPI = false, bool SP2 = false>
; __device__ __forceinline__ void gemm_phase(PG8_LAS unsigned char* lds, const Gemm g, const Sched& S, const Epi& E) {
;     ...
;         for (int t = 0; t < nt; t += 2) {
;     ...
;             PG8_LDA(At, 1, 1); PG8_STAGE(PG8_SB(1, 0), b3, voffB); PG8_STAGE(PG8_SB(1, 1), b3 + hstep, voffB); PG8_STAGE(PG8_SA(1, 0), a3, voffA);
;             PG8_WAIT_V(8); PG8_WAIT_L(0); PG8_BAR; PG8_MMA(1, 0, At, B0); PG8_MMA(1, 1, At, B1); PG8_BAR; PG8_SCHED;
;     ...
;         if constexpr (ALIGN_EPI) { if (wr == 0) PG8_BAR; }
	s_add_i32 s52, s79, s3
	v_lshl_add_u64 v[144:145], v[144:145], 0, s[12:13]
	s_mov_b32 m0, s52
	ds_read_b128 v[186:189], v151 offset:49152
	ds_read_b128 v[190:193], v151 offset:50176
	ds_read_b128 v[194:197], v151 offset:51200
	ds_read_b128 v[198:201], v151 offset:52224
	ds_read_b128 v[202:205], v151 offset:53248
	ds_read_b128 v[206:209], v151 offset:54272
	ds_read_b128 v[210:213], v151 offset:55296
	ds_read_b128 v[214:217], v151 offset:56320
	global_load_lds_dwordx4 v[144:145], off
	s_add_i32 m0, s52, 0x2000
	s_add_u32 s40, s40, 0x40080
	v_lshl_add_u64 v[144:145], v[218:219], 0, s[12:13]
	s_addc_u32 s41, s41, 0
	s_add_i32 s52, s80, s3
	global_load_lds_dwordx4 v[144:145], off
	v_lshl_add_u64 v[144:145], s[40:41], 0, v[132:133]
	s_mov_b32 m0, s52
	s_nop 0
	global_load_lds_dwordx4 v[144:145], off
	v_lshl_add_u64 v[144:145], s[40:41], 0, v[128:129]
	s_add_i32 m0, s52, 0x2000
	s_nop 0
	global_load_lds_dwordx4 v[144:145], off
	v_lshl_add_u64 v[144:145], v[220:221], 0, s[12:13]
	s_mov_b32 m0, s62
	s_nop 0
	global_load_lds_dwordx4 v[144:145], off
	v_lshl_add_u64 v[144:145], v[222:223], 0, s[12:13]
	s_mov_b32 m0, s63
	s_nop 0
	global_load_lds_dwordx4 v[144:145], off
	s_waitcnt vmcnt(8)
	s_waitcnt lgkmcnt(0)
	s_barrier
	s_setprio 1
	s_waitcnt lgkmcnt(0)
	v_mfma_f32_16x16x32_bf16 v[60:63], v[152:155], v[186:189], v[60:63]
	v_mfma_f32_16x16x32_bf16 v[52:55], v[162:165], v[186:189], v[52:55]
	v_mfma_f32_16x16x32_bf16 v[44:47], v[152:155], v[194:197], v[44:47]
	v_mfma_f32_16x16x32_bf16 v[36:39], v[162:165], v[194:197], v[36:39]
	v_mfma_f32_16x16x32_bf16 v[28:31], v[152:155], v[202:205], v[28:31]
	v_mfma_f32_16x16x32_bf16 v[20:23], v[162:165], v[202:205], v[20:23]
	v_mfma_f32_16x16x32_bf16 v[12:15], v[152:155], v[210:213], v[12:15]
	v_mfma_f32_16x16x32_bf16 v[4:7], v[162:165], v[210:213], v[4:7]
	v_mfma_f32_16x16x32_bf16 v[60:63], v[156:159], v[190:193], v[60:63]
	v_mfma_f32_16x16x32_bf16 v[52:55], v[166:169], v[190:193], v[52:55]
	v_mfma_f32_16x16x32_bf16 v[44:47], v[156:159], v[198:201], v[44:47]
	v_mfma_f32_16x16x32_bf16 v[36:39], v[166:169], v[198:201], v[36:39]
	v_mfma_f32_16x16x32_bf16 v[28:31], v[156:159], v[206:209], v[28:31]
	v_mfma_f32_16x16x32_bf16 v[20:23], v[166:169], v[206:209], v[20:23]
	v_mfma_f32_16x16x32_bf16 v[12:15], v[156:159], v[214:217], v[12:15]
	v_mfma_f32_16x16x32_bf16 v[4:7], v[166:169], v[214:217], v[4:7]
	v_mfma_f32_16x16x32_bf16 v[56:59], v[170:173], v[186:189], v[56:59]
	v_mfma_f32_16x16x32_bf16 v[48:51], v[178:181], v[186:189], v[48:51]
	v_mfma_f32_16x16x32_bf16 v[40:43], v[170:173], v[194:197], v[40:43]
	v_mfma_f32_16x16x32_bf16 v[32:35], v[178:181], v[194:197], v[32:35]
	v_mfma_f32_16x16x32_bf16 v[24:27], v[170:173], v[202:205], v[24:27]
	v_mfma_f32_16x16x32_bf16 v[16:19], v[178:181], v[202:205], v[16:19]
	v_mfma_f32_16x16x32_bf16 v[8:11], v[170:173], v[210:213], v[8:11]
	v_mfma_f32_16x16x32_bf16 v[0:3], v[178:181], v[210:213], v[0:3]
	v_mfma_f32_16x16x32_bf16 v[56:59], v[174:177], v[190:193], v[56:59]
	v_mfma_f32_16x16x32_bf16 v[48:51], v[182:185], v[190:193], v[48:51]
	v_mfma_f32_16x16x32_bf16 v[40:43], v[174:177], v[198:201], v[40:43]
	v_mfma_f32_16x16x32_bf16 v[32:35], v[182:185], v[198:201], v[32:35]
	v_mfma_f32_16x16x32_bf16 v[24:27], v[174:177], v[206:209], v[24:27]
	v_mfma_f32_16x16x32_bf16 v[16:19], v[182:185], v[206:209], v[16:19]
	v_mfma_f32_16x16x32_bf16 v[8:11], v[174:177], v[214:217], v[8:11]
	v_mfma_f32_16x16x32_bf16 v[0:3], v[182:185], v[214:217], v[0:3]
	s_setprio 0
	s_barrier
	s_add_i32 s78, s78, 2
	s_add_u32 s38, s38, 0x100
	s_addc_u32 s39, s39, 0
	s_add_u32 s76, s76, 0x100
	s_addc_u32 s77, s77, 0
	s_cmp_gt_u32 s78, 13
	s_cbranch_scc0 .LBB0_194
	s_and_b64 vcc, exec, s[14:15]
	s_cbranch_vccz .LBB0_197
	s_barrier

; #define PG8_STAGE(bufoff, gbase, voff) do { _Pragma("unroll") for (int _i = 0; _i < 2; ++_i) \
;         __builtin_amdgcn_global_load_lds((const unsigned*)((const char*)(gbase) + (voff)[_i]), (PG8_LAS unsigned*)(lds + (bufoff) + ldsw + _i * 8192), 16, 0, 0); } while (0)
; #define PG8_LDA(dst, b, h) do { _Pragma("unroll") for (int m = 0; m < 4; ++m) _Pragma("unroll") for (int k = 0; k < 2; ++k) dst[m][k] = *(const PG8_LAS bf16x8*)(lds + PG8_SA(b, h) + aoff + m * 2048 + k * 1024); } while (0)
; #define PG8_LDB(dst, b, h) do { _Pragma("unroll") for (int n = 0; n < 2; ++n) _Pragma("unroll") for (int k = 0; k < 2; ++k) dst[n][k] = *(const PG8_LAS bf16x8*)(lds + PG8_SB(b, h) + boff + n * 2048 + k * 1024); } while (0)
; #define PG8_MMA(ai, bj, At, Bt) do { __builtin_amdgcn_s_setprio(1); _Pragma("unroll") for (int m = 0; m < 4; ++m) _Pragma("unroll") for (int n = 0; n < 2; ++n) _Pragma("unroll") for (int k = 0; k < 2; ++k) \
;         acc[ai][bj][m][n] = __builtin_amdgcn_mfma_f32_16x16x32_bf16(Bt[n][k], At[m][k], acc[ai][bj][m][n], 0, 0, 0); __builtin_amdgcn_s_setprio(0); } while (0)
; #define PG8_WAIT_V(n) asm volatile("s_waitcnt vmcnt(" #n ")" ::: "memory")
; #define PG8_WAIT_L(n) asm volatile("s_waitcnt lgkmcnt(" #n ")" ::: "memory")
; #define PG8_BAR __builtin_amdgcn_s_barrier()
; #define PG8_SCHED __builtin_amdgcn_sched_barrier(0)
; template <class Epi, class Sched, bool ALIGN_EPI = false, bool SP2 = false>
; __device__ __forceinline__ void gemm_phase(PG8_LAS unsigned char* lds, const Gemm g, const Sched& S, const Epi& E) {
;     ...
;             const bool last = (t == nt - 2);
;             const char* a1 = cA + (size_t)(t + 1) * kstep;
;             const char* a2 = last ? nA : cA + (size_t)(t + 2) * kstep; const char* b2 = last ? nB : cB + (size_t)(t + 2) * kstep;
;             const char* a3 = a2 + kstep; const char* b3 = b2 + kstep;
;             if (last && has_next) S.a_ready(nxt);
;             if constexpr (SP2) {
;             PG8_LDB(B0, 0, 0); PG8_LDB(B1, 0, 1); PG8_SCHED; PG8_LDA(At, 0, 0); PG8_STAGE(PG8_SA(1, 1), a1 + hstep, voffA);
;             PG8_WAIT_V(8); PG8_WAIT_L(0); PG8_BAR; PG8_MMA(0, 0, At, B0); PG8_MMA(0, 1, At, B1); PG8_BAR; PG8_SCHED;
;             PG8_LDA(At, 0, 1); PG8_STAGE(PG8_SB(0, 0), b2, voffB); PG8_STAGE(PG8_SB(0, 1), b2 + hstep, voffB); PG8_STAGE(PG8_SA(0, 0), a2, voffA);
.LBB0_289:
	ds_read_b128 v[144:147], v168
	ds_read_b128 v[148:151], v168 offset:1024
	ds_read_b128 v[152:155], v168 offset:2048
	ds_read_b128 v[156:159], v168 offset:3072
	ds_read_b128 v[162:165], v169
	ds_read_b128 v[172:175], v169 offset:1024
	ds_read_b128 v[176:179], v169 offset:2048
	ds_read_b128 v[180:183], v169 offset:3072
	s_add_u32 s34, s22, 0xfff50080
	s_addc_u32 s35, s23, -1
	s_cmp_eq_u32 s70, 40
	s_cselect_b32 s37, s1, s35
	s_cselect_b32 s36, s0, s34
	s_cselect_b32 s35, s21, s67
	s_cselect_b32 s34, s20, s66
	v_lshl_add_u64 v[216:217], s[22:23], 0, v[136:137]
	s_add_i32 m0, s38, 0xc000
	ds_read_b128 v[184:187], v170
	ds_read_b128 v[188:191], v170 offset:1024
	ds_read_b128 v[192:195], v170 offset:2048
	ds_read_b128 v[196:199], v170 offset:3072
	ds_read_b128 v[200:203], v170 offset:4096
	ds_read_b128 v[204:207], v170 offset:5120
	ds_read_b128 v[208:211], v170 offset:6144
	ds_read_b128 v[212:215], v170 offset:7168
	global_load_lds_dwordx4 v[216:217], off
	v_lshl_add_u64 v[216:217], s[22:23], 0, v[138:139]
	s_add_i32 m0, s38, 0xe000
	s_nop 0
	global_load_lds_dwordx4 v[216:217], off
	s_waitcnt vmcnt(8)
	s_waitcnt lgkmcnt(0)
	s_barrier
	s_setprio 1
	s_waitcnt lgkmcnt(0)
	v_mfma_f32_16x16x32_bf16 v[124:127], v[144:147], v[184:187], v[124:127]
	v_mfma_f32_16x16x32_bf16 v[120:123], v[152:155], v[184:187], v[120:123]
	v_mfma_f32_16x16x32_bf16 v[108:111], v[144:147], v[192:195], v[108:111]
	v_mfma_f32_16x16x32_bf16 v[104:107], v[152:155], v[192:195], v[104:107]
	v_mfma_f32_16x16x32_bf16 v[92:95], v[144:147], v[200:203], v[92:95]
	v_mfma_f32_16x16x32_bf16 v[88:91], v[152:155], v[200:203], v[88:91]
	v_mfma_f32_16x16x32_bf16 v[76:79], v[144:147], v[208:211], v[76:79]
	v_mfma_f32_16x16x32_bf16 v[72:75], v[152:155], v[208:211], v[72:75]
	v_mfma_f32_16x16x32_bf16 v[124:127], v[148:151], v[188:191], v[124:127]
	v_mfma_f32_16x16x32_bf16 v[120:123], v[156:159], v[188:191], v[120:123]
	v_mfma_f32_16x16x32_bf16 v[108:111], v[148:151], v[196:199], v[108:111]
	v_mfma_f32_16x16x32_bf16 v[104:107], v[156:159], v[196:199], v[104:107]
	v_mfma_f32_16x16x32_bf16 v[92:95], v[148:151], v[204:207], v[92:95]
	v_mfma_f32_16x16x32_bf16 v[88:91], v[156:159], v[204:207], v[88:91]
	v_mfma_f32_16x16x32_bf16 v[76:79], v[148:151], v[212:215], v[76:79]
	v_mfma_f32_16x16x32_bf16 v[72:75], v[156:159], v[212:215], v[72:75]
	v_mfma_f32_16x16x32_bf16 v[116:119], v[162:165], v[184:187], v[116:119]
	v_mfma_f32_16x16x32_bf16 v[112:115], v[176:179], v[184:187], v[112:115]
	v_mfma_f32_16x16x32_bf16 v[100:103], v[162:165], v[192:195], v[100:103]
	v_mfma_f32_16x16x32_bf16 v[96:99], v[176:179], v[192:195], v[96:99]
	v_mfma_f32_16x16x32_bf16 v[84:87], v[162:165], v[200:203], v[84:87]
	v_mfma_f32_16x16x32_bf16 v[80:83], v[176:179], v[200:203], v[80:83]
	v_mfma_f32_16x16x32_bf16 v[68:71], v[162:165], v[208:211], v[68:71]
	v_mfma_f32_16x16x32_bf16 v[64:67], v[176:179], v[208:211], v[64:67]
	v_mfma_f32_16x16x32_bf16 v[116:119], v[172:175], v[188:191], v[116:119]
	v_mfma_f32_16x16x32_bf16 v[112:115], v[180:183], v[188:191], v[112:115]
	v_mfma_f32_16x16x32_bf16 v[100:103], v[172:175], v[196:199], v[100:103]
	v_mfma_f32_16x16x32_bf16 v[96:99], v[180:183], v[196:199], v[96:99]
	v_mfma_f32_16x16x32_bf16 v[84:87], v[172:175], v[204:207], v[84:87]
	v_mfma_f32_16x16x32_bf16 v[80:83], v[180:183], v[204:207], v[80:83]
	v_mfma_f32_16x16x32_bf16 v[68:71], v[172:175], v[212:215], v[68:71]
	v_mfma_f32_16x16x32_bf16 v[64:67], v[180:183], v[212:215], v[64:67]
	s_setprio 0
	s_barrier
	s_add_i32 s71, s58, s3
	v_lshl_add_u64 v[216:217], s[34:35], 0, v[130:131]
	s_mov_b32 m0, s71
	ds_read_b128 v[184:187], v170 offset:16384
	ds_read_b128 v[188:191], v170 offset:17408
	ds_read_b128 v[192:195], v170 offset:18432
	ds_read_b128 v[196:199], v170 offset:19456
	ds_read_b128 v[200:203], v170 offset:20480
	ds_read_b128 v[204:207], v170 offset:21504
	ds_read_b128 v[208:211], v170 offset:22528
	ds_read_b128 v[212:215], v170 offset:23552
	global_load_lds_dwordx4 v[216:217], off
	s_add_i32 m0, s71, 0x2000
	s_add_u32 s72, s34, 0xb0000
	v_lshl_add_u64 v[218:219], s[34:35], 0, v[134:135]
	s_addc_u32 s73, s35, 0
	s_add_i32 s71, s59, s3
	global_load_lds_dwordx4 v[218:219], off
	v_lshl_add_u64 v[220:221], s[72:73], 0, v[130:131]
	s_mov_b32 m0, s71
	v_lshl_add_u64 v[222:223], s[36:37], 0, v[132:133]
	global_load_lds_dwordx4 v[220:221], off
	v_lshl_add_u64 v[220:221], s[72:73], 0, v[134:135]
	s_add_i32 m0, s71, 0x2000
	s_nop 0
	global_load_lds_dwordx4 v[220:221], off
	v_lshl_add_u64 v[220:221], s[36:37], 0, v[128:129]
	s_mov_b32 m0, s38
	s_nop 0
	global_load_lds_dwordx4 v[220:221], off
	s_mov_b32 m0, s39
	s_nop 0
	global_load_lds_dwordx4 v[222:223], off
	s_waitcnt vmcnt(8)
	s_waitcnt lgkmcnt(0)
	s_barrier
; #define PG8_STAGE(bufoff, gbase, voff) do { _Pragma("unroll") for (int _i = 0; _i < 2; ++_i) \
;         __builtin_amdgcn_global_load_lds((const unsigned*)((const char*)(gbase) + (voff)[_i]), (PG8_LAS unsigned*)(lds + (bufoff) + ldsw + _i * 8192), 16, 0, 0); } while (0)
; #define PG8_LDA(dst, b, h) do { _Pragma("unroll") for (int m = 0; m < 4; ++m) _Pragma("unroll") for (int k = 0; k < 2; ++k) dst[m][k] = *(const PG8_LAS bf16x8*)(lds + PG8_SA(b, h) + aoff + m * 2048 + k * 1024); } while (0)
; #define PG8_LDB(dst, b, h) do { _Pragma("unroll") for (int n = 0; n < 2; ++n) _Pragma("unroll") for (int k = 0; k < 2; ++k) dst[n][k] = *(const PG8_LAS bf16x8*)(lds + PG8_SB(b, h) + boff + n * 2048 + k * 1024); } while (0)
; #define PG8_MMA(ai, bj, At, Bt) do { __builtin_amdgcn_s_setprio(1); _Pragma("unroll") for (int m = 0; m < 4; ++m) _Pragma("unroll") for (int n = 0; n < 2; ++n) _Pragma("unroll") for (int k = 0; k < 2; ++k) \
;         acc[ai][bj][m][n] = __builtin_amdgcn_mfma_f32_16x16x32_bf16(Bt[n][k], At[m][k], acc[ai][bj][m][n], 0, 0, 0); __builtin_amdgcn_s_setprio(0); } while (0)
; #define PG8_WAIT_V(n) asm volatile("s_waitcnt vmcnt(" #n ")" ::: "memory")
; #define PG8_WAIT_L(n) asm volatile("s_waitcnt lgkmcnt(" #n ")" ::: "memory")
; #define PG8_BAR __builtin_amdgcn_s_barrier()
; #define PG8_SCHED __builtin_amdgcn_sched_barrier(0)
; template <class Epi, class Sched, bool ALIGN_EPI = false, bool SP2 = false>
; __device__ __forceinline__ void gemm_phase(PG8_LAS unsigned char* lds, const Gemm g, const Sched& S, const Epi& E) {
;     ...
;             PG8_LDA(At, 0, 1); PG8_STAGE(PG8_SB(0, 0), b2, voffB); PG8_STAGE(PG8_SB(0, 1), b2 + hstep, voffB); PG8_STAGE(PG8_SA(0, 0), a2, voffA);
;             PG8_WAIT_V(8); PG8_WAIT_L(0); PG8_BAR; PG8_MMA(1, 0, At, B0); PG8_MMA(1, 1, At, B1); PG8_BAR; PG8_SCHED;
;             PG8_LDB(B0, 1, 0); PG8_LDB(B1, 1, 1); PG8_SCHED; PG8_LDA(At, 1, 0); PG8_STAGE(PG8_SA(0, 1), a2 + hstep, voffA);
;             PG8_WAIT_V(8); PG8_WAIT_L(0); PG8_BAR; PG8_MMA(0, 0, At, B0); PG8_MMA(0, 1, At, B1); PG8_BAR; PG8_SCHED;
	s_setprio 1
	s_waitcnt lgkmcnt(0)
	v_mfma_f32_16x16x32_bf16 v[60:63], v[144:147], v[184:187], v[60:63]
	v_mfma_f32_16x16x32_bf16 v[56:59], v[152:155], v[184:187], v[56:59]
	v_mfma_f32_16x16x32_bf16 v[44:47], v[144:147], v[192:195], v[44:47]
	v_mfma_f32_16x16x32_bf16 v[40:43], v[152:155], v[192:195], v[40:43]
	v_mfma_f32_16x16x32_bf16 v[28:31], v[144:147], v[200:203], v[28:31]
	v_mfma_f32_16x16x32_bf16 v[24:27], v[152:155], v[200:203], v[24:27]
	v_mfma_f32_16x16x32_bf16 v[12:15], v[144:147], v[208:211], v[12:15]
	v_mfma_f32_16x16x32_bf16 v[8:11], v[152:155], v[208:211], v[8:11]
	v_mfma_f32_16x16x32_bf16 v[60:63], v[148:151], v[188:191], v[60:63]
	v_mfma_f32_16x16x32_bf16 v[56:59], v[156:159], v[188:191], v[56:59]
	v_mfma_f32_16x16x32_bf16 v[44:47], v[148:151], v[196:199], v[44:47]
	v_mfma_f32_16x16x32_bf16 v[40:43], v[156:159], v[196:199], v[40:43]
	v_mfma_f32_16x16x32_bf16 v[28:31], v[148:151], v[204:207], v[28:31]
	v_mfma_f32_16x16x32_bf16 v[24:27], v[156:159], v[204:207], v[24:27]
	v_mfma_f32_16x16x32_bf16 v[12:15], v[148:151], v[212:215], v[12:15]
	v_mfma_f32_16x16x32_bf16 v[8:11], v[156:159], v[212:215], v[8:11]
	v_mfma_f32_16x16x32_bf16 v[52:55], v[162:165], v[184:187], v[52:55]
	v_mfma_f32_16x16x32_bf16 v[48:51], v[176:179], v[184:187], v[48:51]
	v_mfma_f32_16x16x32_bf16 v[36:39], v[162:165], v[192:195], v[36:39]
	v_mfma_f32_16x16x32_bf16 v[32:35], v[176:179], v[192:195], v[32:35]
	v_mfma_f32_16x16x32_bf16 v[20:23], v[162:165], v[200:203], v[20:23]
	v_mfma_f32_16x16x32_bf16 v[16:19], v[176:179], v[200:203], v[16:19]
	v_mfma_f32_16x16x32_bf16 v[4:7], v[162:165], v[208:211], v[4:7]
	v_mfma_f32_16x16x32_bf16 v[0:3], v[176:179], v[208:211], v[0:3]
	v_mfma_f32_16x16x32_bf16 v[52:55], v[172:175], v[188:191], v[52:55]
	v_mfma_f32_16x16x32_bf16 v[48:51], v[180:183], v[188:191], v[48:51]
	v_mfma_f32_16x16x32_bf16 v[36:39], v[172:175], v[196:199], v[36:39]
	v_mfma_f32_16x16x32_bf16 v[32:35], v[180:183], v[196:199], v[32:35]
	v_mfma_f32_16x16x32_bf16 v[20:23], v[172:175], v[204:207], v[20:23]
	v_mfma_f32_16x16x32_bf16 v[16:19], v[180:183], v[204:207], v[16:19]
	v_mfma_f32_16x16x32_bf16 v[4:7], v[172:175], v[212:215], v[4:7]
	v_mfma_f32_16x16x32_bf16 v[0:3], v[180:183], v[212:215], v[0:3]
	s_setprio 0
	s_barrier
	s_add_i32 s71, 0, 0x18000
	s_add_i32 s72, 0, 0x1c000
	v_add_u32_e32 v156, s71, v166
	v_add_u32_e32 v180, s72, v166
	ds_read_b128 v[144:147], v156
	ds_read_b128 v[148:151], v156 offset:1024
	ds_read_b128 v[152:155], v156 offset:2048
	ds_read_b128 v[156:159], v156 offset:3072
	ds_read_b128 v[162:165], v180
	ds_read_b128 v[172:175], v180 offset:1024
	ds_read_b128 v[176:179], v180 offset:2048
	ds_read_b128 v[180:183], v180 offset:3072
	s_add_u32 s36, s36, 0xb0000
	s_addc_u32 s37, s37, 0
	s_mov_b32 m0, s40
	v_lshl_add_u64 v[224:225], s[36:37], 0, v[128:129]
	ds_read_b128 v[184:187], v170 offset:32768
	ds_read_b128 v[188:191], v170 offset:33792
	ds_read_b128 v[192:195], v170 offset:34816
	ds_read_b128 v[196:199], v170 offset:35840
	ds_read_b128 v[200:203], v170 offset:36864
	ds_read_b128 v[204:207], v170 offset:37888
	ds_read_b128 v[208:211], v170 offset:38912
	ds_read_b128 v[212:215], v170 offset:39936
	global_load_lds_dwordx4 v[224:225], off
	v_lshl_add_u64 v[224:225], s[36:37], 0, v[132:133]
	s_mov_b32 m0, s41
	s_nop 0
	global_load_lds_dwordx4 v[224:225], off
	s_waitcnt vmcnt(8)
	s_waitcnt lgkmcnt(0)
	s_barrier
	s_setprio 1
	s_waitcnt lgkmcnt(0)
	v_mfma_f32_16x16x32_bf16 v[124:127], v[144:147], v[184:187], v[124:127]
	v_mfma_f32_16x16x32_bf16 v[120:123], v[152:155], v[184:187], v[120:123]
	v_mfma_f32_16x16x32_bf16 v[108:111], v[144:147], v[192:195], v[108:111]
	v_mfma_f32_16x16x32_bf16 v[104:107], v[152:155], v[192:195], v[104:107]
	v_mfma_f32_16x16x32_bf16 v[92:95], v[144:147], v[200:203], v[92:95]
	v_mfma_f32_16x16x32_bf16 v[88:91], v[152:155], v[200:203], v[88:91]
	v_mfma_f32_16x16x32_bf16 v[76:79], v[144:147], v[208:211], v[76:79]
	v_mfma_f32_16x16x32_bf16 v[72:75], v[152:155], v[208:211], v[72:75]
	v_mfma_f32_16x16x32_bf16 v[124:127], v[148:151], v[188:191], v[124:127]
	v_mfma_f32_16x16x32_bf16 v[120:123], v[156:159], v[188:191], v[120:123]
	v_mfma_f32_16x16x32_bf16 v[108:111], v[148:151], v[196:199], v[108:111]
	v_mfma_f32_16x16x32_bf16 v[104:107], v[156:159], v[196:199], v[104:107]
	v_mfma_f32_16x16x32_bf16 v[92:95], v[148:151], v[204:207], v[92:95]
	v_mfma_f32_16x16x32_bf16 v[88:91], v[156:159], v[204:207], v[88:91]
	v_mfma_f32_16x16x32_bf16 v[76:79], v[148:151], v[212:215], v[76:79]
	v_mfma_f32_16x16x32_bf16 v[72:75], v[156:159], v[212:215], v[72:75]
	v_mfma_f32_16x16x32_bf16 v[116:119], v[162:165], v[184:187], v[116:119]
	v_mfma_f32_16x16x32_bf16 v[112:115], v[176:179], v[184:187], v[112:115]
	v_mfma_f32_16x16x32_bf16 v[100:103], v[162:165], v[192:195], v[100:103]
	v_mfma_f32_16x16x32_bf16 v[96:99], v[176:179], v[192:195], v[96:99]
	v_mfma_f32_16x16x32_bf16 v[84:87], v[162:165], v[200:203], v[84:87]
	v_mfma_f32_16x16x32_bf16 v[80:83], v[176:179], v[200:203], v[80:83]
	v_mfma_f32_16x16x32_bf16 v[68:71], v[162:165], v[208:211], v[68:71]
	v_mfma_f32_16x16x32_bf16 v[64:67], v[176:179], v[208:211], v[64:67]
	v_mfma_f32_16x16x32_bf16 v[116:119], v[172:175], v[188:191], v[116:119]
	v_mfma_f32_16x16x32_bf16 v[112:115], v[180:183], v[188:191], v[112:115]
	v_mfma_f32_16x16x32_bf16 v[100:103], v[172:175], v[196:199], v[100:103]
	v_mfma_f32_16x16x32_bf16 v[96:99], v[180:183], v[196:199], v[96:99]
	v_mfma_f32_16x16x32_bf16 v[84:87], v[172:175], v[204:207], v[84:87]
	v_mfma_f32_16x16x32_bf16 v[80:83], v[180:183], v[204:207], v[80:83]
	v_mfma_f32_16x16x32_bf16 v[68:71], v[172:175], v[212:215], v[68:71]
	v_mfma_f32_16x16x32_bf16 v[64:67], v[180:183], v[212:215], v[64:67]
	s_setprio 0
	s_barrier
; #define PG8_STAGE(bufoff, gbase, voff) do { _Pragma("unroll") for (int _i = 0; _i < 2; ++_i) \
;         __builtin_amdgcn_global_load_lds((const unsigned*)((const char*)(gbase) + (voff)[_i]), (PG8_LAS unsigned*)(lds + (bufoff) + ldsw + _i * 8192), 16, 0, 0); } while (0)
; #define PG8_LDA(dst, b, h) do { _Pragma("unroll") for (int m = 0; m < 4; ++m) _Pragma("unroll") for (int k = 0; k < 2; ++k) dst[m][k] = *(const PG8_LAS bf16x8*)(lds + PG8_SA(b, h) + aoff + m * 2048 + k * 1024); } while (0)
; #define PG8_MMA(ai, bj, At, Bt) do { __builtin_amdgcn_s_setprio(1); _Pragma("unroll") for (int m = 0; m < 4; ++m) _Pragma("unroll") for (int n = 0; n < 2; ++n) _Pragma("unroll") for (int k = 0; k < 2; ++k) \
;         acc[ai][bj][m][n] = __builtin_amdgcn_mfma_f32_16x16x32_bf16(Bt[n][k], At[m][k], acc[ai][bj][m][n], 0, 0, 0); __builtin_amdgcn_s_setprio(0); } while (0)
; #define PG8_WAIT_V(n) asm volatile("s_waitcnt vmcnt(" #n ")" ::: "memory")
; #define PG8_WAIT_L(n) asm volatile("s_waitcnt lgkmcnt(" #n ")" ::: "memory")
; #define PG8_BAR __builtin_amdgcn_s_barrier()
; #define PG8_SCHED __builtin_amdgcn_sched_barrier(0)
; template <class Epi, class Sched, bool ALIGN_EPI = false, bool SP2 = false>
; __device__ __forceinline__ void gemm_phase(PG8_LAS unsigned char* lds, const Gemm g, const Sched& S, const Epi& E) {
;     ...
;             PG8_LDA(At, 1, 1); PG8_STAGE(PG8_SB(1, 0), b3, voffB); PG8_STAGE(PG8_SB(1, 1), b3 + hstep, voffB); PG8_STAGE(PG8_SA(1, 0), a3, voffA);
;             PG8_WAIT_V(8); PG8_WAIT_L(0); PG8_BAR; PG8_MMA(1, 0, At, B0); PG8_MMA(1, 1, At, B1); PG8_BAR; PG8_SCHED;
; __global__ void __launch_bounds__(512, 2) hybrid_fwd(Args args) {
;     ...
;         for (int idx = blk * 512 + tid; idx < 2 * NBIAS; idx += G * 512) { const int bb = idx / NBIAS, col = idx - bb * NBIAS; float sacc = 0.f;
; #pragma unroll
;             for (int kb = 0; kb < 16; ++kb) sacc += BIASP[((size_t)bb * 16 + kb) * NBIAS + col];
;             BIAS[idx] = sacc; }
	s_add_i32 s36, s71, s3
	v_lshl_add_u64 v[216:217], v[216:217], 0, s[16:17]
	s_mov_b32 m0, s36
	ds_read_b128 v[184:187], v170 offset:49152
	ds_read_b128 v[188:191], v170 offset:50176
	ds_read_b128 v[192:195], v170 offset:51200
	ds_read_b128 v[196:199], v170 offset:52224
	ds_read_b128 v[200:203], v170 offset:53248
	ds_read_b128 v[204:207], v170 offset:54272
	ds_read_b128 v[208:211], v170 offset:55296
	ds_read_b128 v[212:215], v170 offset:56320
	global_load_lds_dwordx4 v[216:217], off
	s_add_i32 m0, s36, 0x2000
	s_add_u32 s34, s34, 0xb0080
	v_lshl_add_u64 v[216:217], v[218:219], 0, s[16:17]
	s_addc_u32 s35, s35, 0
	s_add_i32 s36, s72, s3
	global_load_lds_dwordx4 v[216:217], off
	v_lshl_add_u64 v[216:217], s[34:35], 0, v[130:131]
	s_mov_b32 m0, s36
	s_nop 0
	global_load_lds_dwordx4 v[216:217], off
	v_lshl_add_u64 v[216:217], s[34:35], 0, v[134:135]
	s_add_i32 m0, s36, 0x2000
	s_nop 0
	global_load_lds_dwordx4 v[216:217], off
	v_lshl_add_u64 v[216:217], v[220:221], 0, s[16:17]
	s_mov_b32 m0, s53
	s_nop 0
	global_load_lds_dwordx4 v[216:217], off
	v_lshl_add_u64 v[216:217], v[222:223], 0, s[16:17]
	s_mov_b32 m0, s54
	s_nop 0
	global_load_lds_dwordx4 v[216:217], off
	s_waitcnt vmcnt(8)
	s_waitcnt lgkmcnt(0)
	s_barrier
	s_setprio 1
	s_waitcnt lgkmcnt(0)
	v_mfma_f32_16x16x32_bf16 v[60:63], v[144:147], v[184:187], v[60:63]
	v_mfma_f32_16x16x32_bf16 v[56:59], v[152:155], v[184:187], v[56:59]
	v_mfma_f32_16x16x32_bf16 v[44:47], v[144:147], v[192:195], v[44:47]
	v_mfma_f32_16x16x32_bf16 v[40:43], v[152:155], v[192:195], v[40:43]
	v_mfma_f32_16x16x32_bf16 v[28:31], v[144:147], v[200:203], v[28:31]
	v_mfma_f32_16x16x32_bf16 v[24:27], v[152:155], v[200:203], v[24:27]
	v_mfma_f32_16x16x32_bf16 v[12:15], v[144:147], v[208:211], v[12:15]
	v_mfma_f32_16x16x32_bf16 v[8:11], v[152:155], v[208:211], v[8:11]
	v_mfma_f32_16x16x32_bf16 v[60:63], v[148:151], v[188:191], v[60:63]
	v_mfma_f32_16x16x32_bf16 v[56:59], v[156:159], v[188:191], v[56:59]
	v_mfma_f32_16x16x32_bf16 v[44:47], v[148:151], v[196:199], v[44:47]
	v_mfma_f32_16x16x32_bf16 v[40:43], v[156:159], v[196:199], v[40:43]
	v_mfma_f32_16x16x32_bf16 v[28:31], v[148:151], v[204:207], v[28:31]
	v_mfma_f32_16x16x32_bf16 v[24:27], v[156:159], v[204:207], v[24:27]
	v_mfma_f32_16x16x32_bf16 v[12:15], v[148:151], v[212:215], v[12:15]
	v_mfma_f32_16x16x32_bf16 v[8:11], v[156:159], v[212:215], v[8:11]
	v_mfma_f32_16x16x32_bf16 v[52:55], v[162:165], v[184:187], v[52:55]
	v_mfma_f32_16x16x32_bf16 v[48:51], v[176:179], v[184:187], v[48:51]
	v_mfma_f32_16x16x32_bf16 v[36:39], v[162:165], v[192:195], v[36:39]
	v_mfma_f32_16x16x32_bf16 v[32:35], v[176:179], v[192:195], v[32:35]
	v_mfma_f32_16x16x32_bf16 v[20:23], v[162:165], v[200:203], v[20:23]
	v_mfma_f32_16x16x32_bf16 v[16:19], v[176:179], v[200:203], v[16:19]
	v_mfma_f32_16x16x32_bf16 v[4:7], v[162:165], v[208:211], v[4:7]
	v_mfma_f32_16x16x32_bf16 v[0:3], v[176:179], v[208:211], v[0:3]
	v_mfma_f32_16x16x32_bf16 v[52:55], v[172:175], v[188:191], v[52:55]
	v_mfma_f32_16x16x32_bf16 v[48:51], v[180:183], v[188:191], v[48:51]
	v_mfma_f32_16x16x32_bf16 v[36:39], v[172:175], v[196:199], v[36:39]
	v_mfma_f32_16x16x32_bf16 v[32:35], v[180:183], v[196:199], v[32:35]
	v_mfma_f32_16x16x32_bf16 v[20:23], v[172:175], v[204:207], v[20:23]
	v_mfma_f32_16x16x32_bf16 v[16:19], v[180:183], v[204:207], v[16:19]
	v_mfma_f32_16x16x32_bf16 v[4:7], v[172:175], v[212:215], v[4:7]
	v_mfma_f32_16x16x32_bf16 v[0:3], v[180:183], v[212:215], v[0:3]
	s_setprio 0
	s_barrier
	s_add_i32 s70, s70, 2
	s_add_u32 s22, s22, 0x100
	s_addc_u32 s23, s23, 0
	s_add_u32 s66, s66, 0x100
	s_addc_u32 s67, s67, 0
	s_cmp_gt_u32 s70, 41
	s_cbranch_scc0 .LBB0_289
	s_cmp_lt_u32 s2, 38
	s_cbranch_scc0 .Lp3_bias_noload
	s_cmp_ge_u32 s2, 19
	s_cselect_b32 s99, 0x98000, 0
	s_cselect_b32 s100, 19, 0
	s_sub_i32 s100, s2, s100
	s_lshl_b32 s100, s100, 11
	s_add_u32 s100, s100, s99
	s_add_u32 s100, s100, 0xe800000
	s_add_u32 s100, s86, s100
	s_addc_u32 s101, s87, 0
	v_lshlrev_b32_e32 v227, 2, v226
	global_load_dword v228, v227, s[100:101]
	s_add_u32 s100, s100, 0x9800
	s_addc_u32 s101, s101, 0
	global_load_dword v229, v227, s[100:101]
	s_add_u32 s100, s100, 0x9800
	s_addc_u32 s101, s101, 0
	global_load_dword v230, v227, s[100:101]
	s_add_u32 s100, s100, 0x9800
	s_addc_u32 s101, s101, 0
	global_load_dword v231, v227, s[100:101]
	s_add_u32 s100, s100, 0x9800
	s_addc_u32 s101, s101, 0
	global_load_dword v232, v227, s[100:101]
	s_add_u32 s100, s100, 0x9800
	s_addc_u32 s101, s101, 0
	global_load_dword v233, v227, s[100:101]
	s_add_u32 s100, s100, 0x9800
	s_addc_u32 s101, s101, 0
	global_load_dword v234, v227, s[100:101]
	s_add_u32 s100, s100, 0x9800
	s_addc_u32 s101, s101, 0
	global_load_dword v235, v227, s[100:101]
	s_add_u32 s100, s100, 0x9800
	s_addc_u32 s101, s101, 0
	global_load_dword v236, v227, s[100:101]
	s_add_u32 s100, s100, 0x9800
	s_addc_u32 s101, s101, 0
	global_load_dword v237, v227, s[100:101]
	s_add_u32 s100, s100, 0x9800
	s_addc_u32 s101, s101, 0
	global_load_dword v238, v227, s[100:101]
	s_add_u32 s100, s100, 0x9800
	s_addc_u32 s101, s101, 0
	global_load_dword v239, v227, s[100:101]
	s_add_u32 s100, s100, 0x9800
	s_addc_u32 s101, s101, 0
	global_load_dword v240, v227, s[100:101]
	s_add_u32 s100, s100, 0x9800
	s_addc_u32 s101, s101, 0
	global_load_dword v241, v227, s[100:101]
	s_add_u32 s100, s100, 0x9800
	s_addc_u32 s101, s101, 0
	global_load_dword v242, v227, s[100:101]
	s_add_u32 s100, s100, 0x9800
	s_addc_u32 s101, s101, 0
	global_load_dword v243, v227, s[100:101]

; #define PG8_STAGE(bufoff, gbase, voff) do { _Pragma("unroll") for (int _i = 0; _i < 2; ++_i) \
;         __builtin_amdgcn_global_load_lds((const unsigned*)((const char*)(gbase) + (voff)[_i]), (PG8_LAS unsigned*)(lds + (bufoff) + ldsw + _i * 8192), 16, 0, 0); } while (0)
; #define PG8_LDA(dst, b, h) do { _Pragma("unroll") for (int m = 0; m < 4; ++m) _Pragma("unroll") for (int k = 0; k < 2; ++k) dst[m][k] = *(const PG8_LAS bf16x8*)(lds + PG8_SA(b, h) + aoff + m * 2048 + k * 1024); } while (0)
; #define PG8_LDB(dst, b, h) do { _Pragma("unroll") for (int n = 0; n < 2; ++n) _Pragma("unroll") for (int k = 0; k < 2; ++k) dst[n][k] = *(const PG8_LAS bf16x8*)(lds + PG8_SB(b, h) + boff + n * 2048 + k * 1024); } while (0)
; #define PG8_MMA(ai, bj, At, Bt) do { __builtin_amdgcn_s_setprio(1); _Pragma("unroll") for (int m = 0; m < 4; ++m) _Pragma("unroll") for (int n = 0; n < 2; ++n) _Pragma("unroll") for (int k = 0; k < 2; ++k) \
;         acc[ai][bj][m][n] = __builtin_amdgcn_mfma_f32_16x16x32_bf16(Bt[n][k], At[m][k], acc[ai][bj][m][n], 0, 0, 0); __builtin_amdgcn_s_setprio(0); } while (0)
; #define PG8_WAIT_V(n) asm volatile("s_waitcnt vmcnt(" #n ")" ::: "memory")
; #define PG8_WAIT_L(n) asm volatile("s_waitcnt lgkmcnt(" #n ")" ::: "memory")
; #define PG8_BAR __builtin_amdgcn_s_barrier()
; #define PG8_SCHED __builtin_amdgcn_sched_barrier(0)
; template <class Epi, class Sched, bool ALIGN_EPI = false, bool SP2 = false>
; __device__ __forceinline__ void gemm_phase(PG8_LAS unsigned char* lds, const Gemm g, const Sched& S, const Epi& E) {
;     ...
;             const bool last = (t == nt - 2);
;             const char* a1 = cA + (size_t)(t + 1) * kstep;
;             const char* a2 = last ? nA : cA + (size_t)(t + 2) * kstep; const char* b2 = last ? nB : cB + (size_t)(t + 2) * kstep;
;             const char* a3 = a2 + kstep; const char* b3 = b2 + kstep;
;             if (last && has_next) S.a_ready(nxt);
;             if constexpr (SP2) {
;             PG8_LDB(B0, 0, 0); PG8_LDB(B1, 0, 1); PG8_SCHED; PG8_LDA(At, 0, 0); PG8_STAGE(PG8_SA(1, 1), a1 + hstep, voffA);
;             PG8_WAIT_V(8); PG8_WAIT_L(0); PG8_BAR; PG8_MMA(0, 0, At, B0); PG8_MMA(0, 1, At, B1); PG8_BAR; PG8_SCHED;
;             PG8_LDA(At, 0, 1); PG8_STAGE(PG8_SB(0, 0), b2, voffB); PG8_STAGE(PG8_SB(0, 1), b2 + hstep, voffB); PG8_STAGE(PG8_SA(0, 0), a2, voffA);
.LBB0_407:
	ds_read_b128 v[24:27], v189
	ds_read_b128 v[28:31], v189 offset:1024
	ds_read_b128 v[36:39], v189 offset:2048
	ds_read_b128 v[44:47], v189 offset:3072
	ds_read_b128 v[48:51], v190
	ds_read_b128 v[52:55], v190 offset:1024
	ds_read_b128 v[56:59], v190 offset:2048
	ds_read_b128 v[60:63], v190 offset:3072
	s_add_u32 s48, s0, 0xfffc0080
	s_addc_u32 s49, s1, -1
	s_cmp_eq_u32 s55, 12
	s_cselect_b32 s53, s7, s49
	s_cselect_b32 s52, s9, s48
	s_cselect_b32 s49, s12, s54
	s_cselect_b32 s48, s23, s41
	v_lshl_add_u64 v[184:185], s[0:1], 0, v[176:177]
	s_add_i32 m0, s60, 0xc000
	ds_read_b128 v[196:199], v191
	ds_read_b128 v[200:203], v191 offset:1024
	ds_read_b128 v[204:207], v191 offset:2048
	ds_read_b128 v[208:211], v191 offset:3072
	ds_read_b128 v[212:215], v191 offset:4096
	ds_read_b128 v[216:219], v191 offset:5120
	ds_read_b128 v[220:223], v191 offset:6144
	ds_read_b128 v[228:231], v191 offset:7168
	global_load_lds_dwordx4 v[184:185], off
	v_lshl_add_u64 v[184:185], s[0:1], 0, v[178:179]
	s_add_i32 m0, s60, 0xe000
	s_nop 0
	global_load_lds_dwordx4 v[184:185], off
	s_waitcnt vmcnt(8)
	s_waitcnt lgkmcnt(0)
	s_barrier
	s_setprio 1
	s_waitcnt lgkmcnt(0)
	v_mfma_f32_16x16x32_bf16 v[156:159], v[24:27], v[196:199], v[156:159]
	v_mfma_f32_16x16x32_bf16 v[152:155], v[36:39], v[196:199], v[152:155]
	v_mfma_f32_16x16x32_bf16 v[140:143], v[24:27], v[204:207], v[140:143]
	v_mfma_f32_16x16x32_bf16 v[136:139], v[36:39], v[204:207], v[136:139]
	v_mfma_f32_16x16x32_bf16 v[124:127], v[24:27], v[212:215], v[124:127]
	v_mfma_f32_16x16x32_bf16 v[120:123], v[36:39], v[212:215], v[120:123]
	v_mfma_f32_16x16x32_bf16 v[108:111], v[24:27], v[220:223], v[108:111]
	v_mfma_f32_16x16x32_bf16 v[104:107], v[36:39], v[220:223], v[104:107]
	v_mfma_f32_16x16x32_bf16 v[156:159], v[28:31], v[200:203], v[156:159]
	v_mfma_f32_16x16x32_bf16 v[152:155], v[44:47], v[200:203], v[152:155]
	v_mfma_f32_16x16x32_bf16 v[140:143], v[28:31], v[208:211], v[140:143]
	v_mfma_f32_16x16x32_bf16 v[136:139], v[44:47], v[208:211], v[136:139]
	v_mfma_f32_16x16x32_bf16 v[124:127], v[28:31], v[216:219], v[124:127]
	v_mfma_f32_16x16x32_bf16 v[120:123], v[44:47], v[216:219], v[120:123]
	v_mfma_f32_16x16x32_bf16 v[108:111], v[28:31], v[228:231], v[108:111]
	v_mfma_f32_16x16x32_bf16 v[104:107], v[44:47], v[228:231], v[104:107]
	v_mfma_f32_16x16x32_bf16 v[148:151], v[48:51], v[196:199], v[148:151]
	v_mfma_f32_16x16x32_bf16 v[144:147], v[56:59], v[196:199], v[144:147]
	v_mfma_f32_16x16x32_bf16 v[132:135], v[48:51], v[204:207], v[132:135]
	v_mfma_f32_16x16x32_bf16 v[128:131], v[56:59], v[204:207], v[128:131]
	v_mfma_f32_16x16x32_bf16 v[116:119], v[48:51], v[212:215], v[116:119]
	v_mfma_f32_16x16x32_bf16 v[112:115], v[56:59], v[212:215], v[112:115]
	v_mfma_f32_16x16x32_bf16 v[100:103], v[48:51], v[220:223], v[100:103]
	v_mfma_f32_16x16x32_bf16 v[96:99], v[56:59], v[220:223], v[96:99]
	v_mfma_f32_16x16x32_bf16 v[148:151], v[52:55], v[200:203], v[148:151]
	v_mfma_f32_16x16x32_bf16 v[144:147], v[60:63], v[200:203], v[144:147]
	v_mfma_f32_16x16x32_bf16 v[132:135], v[52:55], v[208:211], v[132:135]
	v_mfma_f32_16x16x32_bf16 v[128:131], v[60:63], v[208:211], v[128:131]
	v_mfma_f32_16x16x32_bf16 v[116:119], v[52:55], v[216:219], v[116:119]
	v_mfma_f32_16x16x32_bf16 v[112:115], v[60:63], v[216:219], v[112:115]
	v_mfma_f32_16x16x32_bf16 v[100:103], v[52:55], v[228:231], v[100:103]
	v_mfma_f32_16x16x32_bf16 v[96:99], v[60:63], v[228:231], v[96:99]
	s_setprio 0
	s_barrier
	s_add_i32 s56, s74, s59
	v_lshl_add_u64 v[184:185], s[48:49], 0, v[164:165]
	s_mov_b32 m0, s56
	ds_read_b128 v[196:199], v191 offset:16384
	ds_read_b128 v[200:203], v191 offset:17408
	ds_read_b128 v[204:207], v191 offset:18432
	ds_read_b128 v[208:211], v191 offset:19456
	ds_read_b128 v[212:215], v191 offset:20480
	ds_read_b128 v[216:219], v191 offset:21504
	ds_read_b128 v[220:223], v191 offset:22528
	ds_read_b128 v[228:231], v191 offset:23552
	global_load_lds_dwordx4 v[184:185], off
	s_add_i32 m0, s56, 0x2000
	s_add_u32 s56, s48, 0x40000
	v_lshl_add_u64 v[224:225], s[48:49], 0, v[168:169]
	s_addc_u32 s57, s49, 0
	s_add_i32 s79, s75, s59
	global_load_lds_dwordx4 v[224:225], off
	v_lshl_add_u64 v[232:233], s[56:57], 0, v[164:165]
	s_mov_b32 m0, s79
	v_lshl_add_u64 v[240:241], s[52:53], 0, v[162:163]
	global_load_lds_dwordx4 v[232:233], off
	v_lshl_add_u64 v[232:233], s[56:57], 0, v[168:169]
	s_add_i32 m0, s79, 0x2000
	v_lshl_add_u64 v[242:243], s[52:53], 0, v[166:167]
	global_load_lds_dwordx4 v[232:233], off
	s_mov_b32 m0, s60
	s_nop 0
	global_load_lds_dwordx4 v[240:241], off
	s_mov_b32 m0, s61
	s_nop 0
	global_load_lds_dwordx4 v[242:243], off
	s_waitcnt vmcnt(8)
	s_waitcnt lgkmcnt(0)
	s_barrier
; #define PG8_STAGE(bufoff, gbase, voff) do { _Pragma("unroll") for (int _i = 0; _i < 2; ++_i) \
;         __builtin_amdgcn_global_load_lds((const unsigned*)((const char*)(gbase) + (voff)[_i]), (PG8_LAS unsigned*)(lds + (bufoff) + ldsw + _i * 8192), 16, 0, 0); } while (0)
; #define PG8_LDA(dst, b, h) do { _Pragma("unroll") for (int m = 0; m < 4; ++m) _Pragma("unroll") for (int k = 0; k < 2; ++k) dst[m][k] = *(const PG8_LAS bf16x8*)(lds + PG8_SA(b, h) + aoff + m * 2048 + k * 1024); } while (0)
; #define PG8_LDB(dst, b, h) do { _Pragma("unroll") for (int n = 0; n < 2; ++n) _Pragma("unroll") for (int k = 0; k < 2; ++k) dst[n][k] = *(const PG8_LAS bf16x8*)(lds + PG8_SB(b, h) + boff + n * 2048 + k * 1024); } while (0)
; #define PG8_MMA(ai, bj, At, Bt) do { __builtin_amdgcn_s_setprio(1); _Pragma("unroll") for (int m = 0; m < 4; ++m) _Pragma("unroll") for (int n = 0; n < 2; ++n) _Pragma("unroll") for (int k = 0; k < 2; ++k) \
;         acc[ai][bj][m][n] = __builtin_amdgcn_mfma_f32_16x16x32_bf16(Bt[n][k], At[m][k], acc[ai][bj][m][n], 0, 0, 0); __builtin_amdgcn_s_setprio(0); } while (0)
; #define PG8_WAIT_V(n) asm volatile("s_waitcnt vmcnt(" #n ")" ::: "memory")
; #define PG8_WAIT_L(n) asm volatile("s_waitcnt lgkmcnt(" #n ")" ::: "memory")
; #define PG8_BAR __builtin_amdgcn_s_barrier()
; #define PG8_SCHED __builtin_amdgcn_sched_barrier(0)
; template <class Epi, class Sched, bool ALIGN_EPI = false, bool SP2 = false>
; __device__ __forceinline__ void gemm_phase(PG8_LAS unsigned char* lds, const Gemm g, const Sched& S, const Epi& E) {
;     ...
;             PG8_LDA(At, 0, 1); PG8_STAGE(PG8_SB(0, 0), b2, voffB); PG8_STAGE(PG8_SB(0, 1), b2 + hstep, voffB); PG8_STAGE(PG8_SA(0, 0), a2, voffA);
;             PG8_WAIT_V(8); PG8_WAIT_L(0); PG8_BAR; PG8_MMA(1, 0, At, B0); PG8_MMA(1, 1, At, B1); PG8_BAR; PG8_SCHED;
;             PG8_LDB(B0, 1, 0); PG8_LDB(B1, 1, 1); PG8_SCHED; PG8_LDA(At, 1, 0); PG8_STAGE(PG8_SA(0, 1), a2 + hstep, voffA);
;             PG8_WAIT_V(8); PG8_WAIT_L(0); PG8_BAR; PG8_MMA(0, 0, At, B0); PG8_MMA(0, 1, At, B1); PG8_BAR; PG8_SCHED;
	s_setprio 1
	s_waitcnt lgkmcnt(0)
	v_mfma_f32_16x16x32_bf16 v[92:95], v[24:27], v[196:199], v[92:95]
	v_mfma_f32_16x16x32_bf16 v[88:91], v[36:39], v[196:199], v[88:91]
	v_mfma_f32_16x16x32_bf16 v[76:79], v[24:27], v[204:207], v[76:79]
	v_mfma_f32_16x16x32_bf16 v[72:75], v[36:39], v[204:207], v[72:75]
	v_mfma_f32_16x16x32_bf16 v[40:43], v[24:27], v[212:215], v[40:43]
	v_mfma_f32_16x16x32_bf16 v[32:35], v[36:39], v[212:215], v[32:35]
	v_mfma_f32_16x16x32_bf16 v[12:15], v[24:27], v[220:223], v[12:15]
	v_mfma_f32_16x16x32_bf16 v[8:11], v[36:39], v[220:223], v[8:11]
	v_mfma_f32_16x16x32_bf16 v[92:95], v[28:31], v[200:203], v[92:95]
	v_mfma_f32_16x16x32_bf16 v[88:91], v[44:47], v[200:203], v[88:91]
	v_mfma_f32_16x16x32_bf16 v[76:79], v[28:31], v[208:211], v[76:79]
	v_mfma_f32_16x16x32_bf16 v[72:75], v[44:47], v[208:211], v[72:75]
	v_mfma_f32_16x16x32_bf16 v[40:43], v[28:31], v[216:219], v[40:43]
	v_mfma_f32_16x16x32_bf16 v[32:35], v[44:47], v[216:219], v[32:35]
	v_mfma_f32_16x16x32_bf16 v[12:15], v[28:31], v[228:231], v[12:15]
	v_mfma_f32_16x16x32_bf16 v[8:11], v[44:47], v[228:231], v[8:11]
	v_mfma_f32_16x16x32_bf16 v[20:23], v[48:51], v[212:215], v[20:23]
	v_mfma_f32_16x16x32_bf16 v[16:19], v[56:59], v[212:215], v[16:19]
	v_mfma_f32_16x16x32_bf16 v[4:7], v[48:51], v[220:223], v[4:7]
	v_mfma_f32_16x16x32_bf16 v[0:3], v[56:59], v[220:223], v[0:3]
	v_mfma_f32_16x16x32_bf16 v[24:27], v[48:51], v[196:199], v[84:87]
	v_mfma_f32_16x16x32_bf16 v[28:31], v[56:59], v[196:199], v[80:83]
	v_mfma_f32_16x16x32_bf16 v[36:39], v[48:51], v[204:207], v[68:71]
	v_mfma_f32_16x16x32_bf16 v[44:47], v[56:59], v[204:207], v[64:67]
	v_mfma_f32_16x16x32_bf16 v[20:23], v[52:55], v[216:219], v[20:23]
	v_mfma_f32_16x16x32_bf16 v[16:19], v[60:63], v[216:219], v[16:19]
	v_mfma_f32_16x16x32_bf16 v[4:7], v[52:55], v[228:231], v[4:7]
	v_mfma_f32_16x16x32_bf16 v[0:3], v[60:63], v[228:231], v[0:3]
	v_mfma_f32_16x16x32_bf16 v[24:27], v[52:55], v[200:203], v[24:27]
	v_mfma_f32_16x16x32_bf16 v[28:31], v[60:63], v[200:203], v[28:31]
	v_mfma_f32_16x16x32_bf16 v[36:39], v[52:55], v[208:211], v[36:39]
	v_mfma_f32_16x16x32_bf16 v[44:47], v[60:63], v[208:211], v[44:47]
	s_setprio 0
	s_barrier
	s_add_i32 s56, 0, 0x18000
	s_add_i32 s57, 0, 0x1c000
	v_add_u32_e32 v60, s56, v186
	v_add_u32_e32 v64, s57, v186
	ds_read_b128 v[48:51], v60
	ds_read_b128 v[52:55], v60 offset:1024
	ds_read_b128 v[56:59], v60 offset:2048
	ds_read_b128 v[60:63], v60 offset:3072
	ds_read_b128 v[196:199], v64
	ds_read_b128 v[200:203], v64 offset:1024
	ds_read_b128 v[204:207], v64 offset:2048
	ds_read_b128 v[208:211], v64 offset:3072
	s_add_u32 s52, s52, 0x40000
	s_addc_u32 s53, s53, 0
	s_mov_b32 m0, s62
	v_lshl_add_u64 v[232:233], s[52:53], 0, v[162:163]
	ds_read_b128 v[64:67], v191 offset:32768
	ds_read_b128 v[68:71], v191 offset:33792
	ds_read_b128 v[80:83], v191 offset:34816
	ds_read_b128 v[84:87], v191 offset:35840
	ds_read_b128 v[212:215], v191 offset:36864
	ds_read_b128 v[216:219], v191 offset:37888
	ds_read_b128 v[220:223], v191 offset:38912
	ds_read_b128 v[228:231], v191 offset:39936
	global_load_lds_dwordx4 v[232:233], off
	v_lshl_add_u64 v[232:233], s[52:53], 0, v[166:167]
	s_mov_b32 m0, s63
	s_nop 0
	global_load_lds_dwordx4 v[232:233], off
	s_waitcnt vmcnt(8)
	s_waitcnt lgkmcnt(0)
	s_barrier
	s_setprio 1
	s_waitcnt lgkmcnt(0)
	v_mfma_f32_16x16x32_bf16 v[156:159], v[48:51], v[64:67], v[156:159]
	v_mfma_f32_16x16x32_bf16 v[152:155], v[56:59], v[64:67], v[152:155]
	v_mfma_f32_16x16x32_bf16 v[140:143], v[48:51], v[80:83], v[140:143]
	v_mfma_f32_16x16x32_bf16 v[136:139], v[56:59], v[80:83], v[136:139]
	v_mfma_f32_16x16x32_bf16 v[124:127], v[48:51], v[212:215], v[124:127]
	v_mfma_f32_16x16x32_bf16 v[120:123], v[56:59], v[212:215], v[120:123]
	v_mfma_f32_16x16x32_bf16 v[108:111], v[48:51], v[220:223], v[108:111]
	v_mfma_f32_16x16x32_bf16 v[104:107], v[56:59], v[220:223], v[104:107]
	v_mfma_f32_16x16x32_bf16 v[156:159], v[52:55], v[68:71], v[156:159]
	v_mfma_f32_16x16x32_bf16 v[152:155], v[60:63], v[68:71], v[152:155]
	v_mfma_f32_16x16x32_bf16 v[140:143], v[52:55], v[84:87], v[140:143]
	v_mfma_f32_16x16x32_bf16 v[136:139], v[60:63], v[84:87], v[136:139]
	v_mfma_f32_16x16x32_bf16 v[124:127], v[52:55], v[216:219], v[124:127]
	v_mfma_f32_16x16x32_bf16 v[120:123], v[60:63], v[216:219], v[120:123]
	v_mfma_f32_16x16x32_bf16 v[108:111], v[52:55], v[228:231], v[108:111]
	v_mfma_f32_16x16x32_bf16 v[104:107], v[60:63], v[228:231], v[104:107]
	v_mfma_f32_16x16x32_bf16 v[148:151], v[196:199], v[64:67], v[148:151]
	v_mfma_f32_16x16x32_bf16 v[64:67], v[204:207], v[64:67], v[144:147]
	v_mfma_f32_16x16x32_bf16 v[144:147], v[208:211], v[68:71], v[64:67]
	v_mfma_f32_16x16x32_bf16 v[64:67], v[196:199], v[80:83], v[132:135]
	v_mfma_f32_16x16x32_bf16 v[132:135], v[200:203], v[84:87], v[64:67]
	v_mfma_f32_16x16x32_bf16 v[64:67], v[204:207], v[80:83], v[128:131]
	v_mfma_f32_16x16x32_bf16 v[128:131], v[208:211], v[84:87], v[64:67]
	v_mfma_f32_16x16x32_bf16 v[64:67], v[196:199], v[212:215], v[116:119]
	v_mfma_f32_16x16x32_bf16 v[116:119], v[200:203], v[216:219], v[64:67]
	v_mfma_f32_16x16x32_bf16 v[64:67], v[204:207], v[212:215], v[112:115]
	v_mfma_f32_16x16x32_bf16 v[112:115], v[208:211], v[216:219], v[64:67]
	v_mfma_f32_16x16x32_bf16 v[64:67], v[196:199], v[220:223], v[100:103]
	v_mfma_f32_16x16x32_bf16 v[100:103], v[200:203], v[228:231], v[64:67]
	v_mfma_f32_16x16x32_bf16 v[64:67], v[204:207], v[220:223], v[96:99]
	v_mfma_f32_16x16x32_bf16 v[148:151], v[200:203], v[68:71], v[148:151]
	v_mfma_f32_16x16x32_bf16 v[96:99], v[208:211], v[228:231], v[64:67]
	s_setprio 0
	s_barrier
; #define PG8_STAGE(bufoff, gbase, voff) do { _Pragma("unroll") for (int _i = 0; _i < 2; ++_i) \
;         __builtin_amdgcn_global_load_lds((const unsigned*)((const char*)(gbase) + (voff)[_i]), (PG8_LAS unsigned*)(lds + (bufoff) + ldsw + _i * 8192), 16, 0, 0); } while (0)
; #define PG8_LDA(dst, b, h) do { _Pragma("unroll") for (int m = 0; m < 4; ++m) _Pragma("unroll") for (int k = 0; k < 2; ++k) dst[m][k] = *(const PG8_LAS bf16x8*)(lds + PG8_SA(b, h) + aoff + m * 2048 + k * 1024); } while (0)
; #define PG8_MMA(ai, bj, At, Bt) do { __builtin_amdgcn_s_setprio(1); _Pragma("unroll") for (int m = 0; m < 4; ++m) _Pragma("unroll") for (int n = 0; n < 2; ++n) _Pragma("unroll") for (int k = 0; k < 2; ++k) \
;         acc[ai][bj][m][n] = __builtin_amdgcn_mfma_f32_16x16x32_bf16(Bt[n][k], At[m][k], acc[ai][bj][m][n], 0, 0, 0); __builtin_amdgcn_s_setprio(0); } while (0)
; #define PG8_WAIT_V(n) asm volatile("s_waitcnt vmcnt(" #n ")" ::: "memory")
; #define PG8_WAIT_L(n) asm volatile("s_waitcnt lgkmcnt(" #n ")" ::: "memory")
; #define PG8_BAR __builtin_amdgcn_s_barrier()
; #define PG8_SCHED __builtin_amdgcn_sched_barrier(0)
; template <class Epi, class Sched, bool ALIGN_EPI = false, bool SP2 = false>
; __device__ __forceinline__ void gemm_phase(PG8_LAS unsigned char* lds, const Gemm g, const Sched& S, const Epi& E) {
;     ...
;         for (int t = 0; t < nt; t += 2) {
;     ...
;             PG8_LDA(At, 1, 1); PG8_STAGE(PG8_SB(1, 0), b3, voffB); PG8_STAGE(PG8_SB(1, 1), b3 + hstep, voffB); PG8_STAGE(PG8_SA(1, 0), a3, voffA);
;             PG8_WAIT_V(8); PG8_WAIT_L(0); PG8_BAR; PG8_MMA(1, 0, At, B0); PG8_MMA(1, 1, At, B1); PG8_BAR; PG8_SCHED;
;     ...
;         if constexpr (ALIGN_EPI) { if (wr == 0) PG8_BAR; }
	s_add_i32 s52, s56, s59
	v_lshl_add_u64 v[80:81], v[184:185], 0, s[16:17]
	s_mov_b32 m0, s52
	s_nop 0
	ds_read_b128 v[64:67], v191 offset:49152
	ds_read_b128 v[68:71], v191 offset:50176
	ds_read_b128 v[212:215], v191 offset:51200
	ds_read_b128 v[216:219], v191 offset:52224
	ds_read_b128 v[220:223], v191 offset:53248
	ds_read_b128 v[228:231], v191 offset:54272
	ds_read_b128 v[232:235], v191 offset:55296
	ds_read_b128 v[236:239], v191 offset:56320
	global_load_lds_dwordx4 v[80:81], off
	s_add_i32 m0, s52, 0x2000
	s_add_u32 s48, s48, 0x40080
	v_lshl_add_u64 v[80:81], v[224:225], 0, s[16:17]
	s_addc_u32 s49, s49, 0
	s_add_i32 s52, s57, s59
	global_load_lds_dwordx4 v[80:81], off
	v_lshl_add_u64 v[80:81], s[48:49], 0, v[164:165]
	s_mov_b32 m0, s52
	s_nop 0
	global_load_lds_dwordx4 v[80:81], off
	v_lshl_add_u64 v[80:81], s[48:49], 0, v[168:169]
	s_add_i32 m0, s52, 0x2000
	s_nop 0
	global_load_lds_dwordx4 v[80:81], off
	v_lshl_add_u64 v[80:81], v[240:241], 0, s[16:17]
	s_mov_b32 m0, s65
	s_nop 0
	global_load_lds_dwordx4 v[80:81], off
	v_lshl_add_u64 v[80:81], v[242:243], 0, s[16:17]
	s_mov_b32 m0, s68
	s_nop 0
	global_load_lds_dwordx4 v[80:81], off
	s_waitcnt vmcnt(8)
	s_waitcnt lgkmcnt(0)
	s_barrier
	s_setprio 1
	s_waitcnt lgkmcnt(0)
	v_mfma_f32_16x16x32_bf16 v[80:83], v[48:51], v[64:67], v[92:95]
	v_mfma_f32_16x16x32_bf16 v[92:95], v[52:55], v[68:71], v[80:83]
	v_mfma_f32_16x16x32_bf16 v[80:83], v[56:59], v[64:67], v[88:91]
	v_mfma_f32_16x16x32_bf16 v[76:79], v[48:51], v[212:215], v[76:79]
	v_mfma_f32_16x16x32_bf16 v[72:75], v[56:59], v[212:215], v[72:75]
	v_mfma_f32_16x16x32_bf16 v[40:43], v[48:51], v[220:223], v[40:43]
	v_mfma_f32_16x16x32_bf16 v[32:35], v[56:59], v[220:223], v[32:35]
	v_mfma_f32_16x16x32_bf16 v[12:15], v[48:51], v[232:235], v[12:15]
	v_mfma_f32_16x16x32_bf16 v[8:11], v[56:59], v[232:235], v[8:11]
	v_mfma_f32_16x16x32_bf16 v[88:91], v[60:63], v[68:71], v[80:83]
	v_mfma_f32_16x16x32_bf16 v[76:79], v[52:55], v[216:219], v[76:79]
	v_mfma_f32_16x16x32_bf16 v[72:75], v[60:63], v[216:219], v[72:75]
	v_mfma_f32_16x16x32_bf16 v[40:43], v[52:55], v[228:231], v[40:43]
	v_mfma_f32_16x16x32_bf16 v[32:35], v[60:63], v[228:231], v[32:35]
	v_mfma_f32_16x16x32_bf16 v[12:15], v[52:55], v[236:239], v[12:15]
	v_mfma_f32_16x16x32_bf16 v[8:11], v[60:63], v[236:239], v[8:11]
	v_mfma_f32_16x16x32_bf16 v[24:27], v[196:199], v[64:67], v[24:27]
	v_mfma_f32_16x16x32_bf16 v[84:87], v[200:203], v[68:71], v[24:27]
	v_mfma_f32_16x16x32_bf16 v[24:27], v[204:207], v[64:67], v[28:31]
	v_mfma_f32_16x16x32_bf16 v[80:83], v[208:211], v[68:71], v[24:27]
	v_mfma_f32_16x16x32_bf16 v[24:27], v[196:199], v[212:215], v[36:39]
	v_mfma_f32_16x16x32_bf16 v[68:71], v[200:203], v[216:219], v[24:27]
	v_mfma_f32_16x16x32_bf16 v[24:27], v[204:207], v[212:215], v[44:47]
	v_mfma_f32_16x16x32_bf16 v[20:23], v[196:199], v[220:223], v[20:23]
	v_mfma_f32_16x16x32_bf16 v[16:19], v[204:207], v[220:223], v[16:19]
	v_mfma_f32_16x16x32_bf16 v[4:7], v[196:199], v[232:235], v[4:7]
	v_mfma_f32_16x16x32_bf16 v[0:3], v[204:207], v[232:235], v[0:3]
	v_mfma_f32_16x16x32_bf16 v[64:67], v[208:211], v[216:219], v[24:27]
	v_mfma_f32_16x16x32_bf16 v[20:23], v[200:203], v[228:231], v[20:23]
	v_mfma_f32_16x16x32_bf16 v[16:19], v[208:211], v[228:231], v[16:19]
	v_mfma_f32_16x16x32_bf16 v[4:7], v[200:203], v[236:239], v[4:7]
	v_mfma_f32_16x16x32_bf16 v[0:3], v[208:211], v[236:239], v[0:3]
	s_setprio 0
	s_barrier
	s_add_i32 s55, s55, 2
	s_add_u32 s0, s0, 0x100
	s_addc_u32 s1, s1, 0
	s_add_u32 s41, s41, 0x100
	s_addc_u32 s54, s54, 0
	s_cmp_gt_u32 s55, 13
	s_cbranch_scc0 .LBB0_407
	s_and_b64 vcc, exec, s[18:19]
	s_cbranch_vccz .LBB0_410
	s_barrier

; #define PG8_STAGE(bufoff, gbase, voff) do { _Pragma("unroll") for (int _i = 0; _i < 2; ++_i) \
;         __builtin_amdgcn_global_load_lds((const unsigned*)((const char*)(gbase) + (voff)[_i]), (PG8_LAS unsigned*)(lds + (bufoff) + ldsw + _i * 8192), 16, 0, 0); } while (0)
; #define PG8_LDA(dst, b, h) do { _Pragma("unroll") for (int m = 0; m < 4; ++m) _Pragma("unroll") for (int k = 0; k < 2; ++k) dst[m][k] = *(const PG8_LAS bf16x8*)(lds + PG8_SA(b, h) + aoff + m * 2048 + k * 1024); } while (0)
; #define PG8_LDB(dst, b, h) do { _Pragma("unroll") for (int n = 0; n < 2; ++n) _Pragma("unroll") for (int k = 0; k < 2; ++k) dst[n][k] = *(const PG8_LAS bf16x8*)(lds + PG8_SB(b, h) + boff + n * 2048 + k * 1024); } while (0)
; #define PG8_MMA(ai, bj, At, Bt) do { __builtin_amdgcn_s_setprio(1); _Pragma("unroll") for (int m = 0; m < 4; ++m) _Pragma("unroll") for (int n = 0; n < 2; ++n) _Pragma("unroll") for (int k = 0; k < 2; ++k) \
;         acc[ai][bj][m][n] = __builtin_amdgcn_mfma_f32_16x16x32_bf16(Bt[n][k], At[m][k], acc[ai][bj][m][n], 0, 0, 0); __builtin_amdgcn_s_setprio(0); } while (0)
; #define PG8_WAIT_V(n) asm volatile("s_waitcnt vmcnt(" #n ")" ::: "memory")
; #define PG8_WAIT_L(n) asm volatile("s_waitcnt lgkmcnt(" #n ")" ::: "memory")
; #define PG8_BAR __builtin_amdgcn_s_barrier()
; #define PG8_SCHED __builtin_amdgcn_sched_barrier(0)
; template <class Epi, class Sched, bool ALIGN_EPI = false, bool SP2 = false>
; __device__ __forceinline__ void gemm_phase(PG8_LAS unsigned char* lds, const Gemm g, const Sched& S, const Epi& E) {
;     ...
;             const bool last = (t == nt - 2);
;             const char* a1 = cA + (size_t)(t + 1) * kstep;
;             const char* a2 = last ? nA : cA + (size_t)(t + 2) * kstep; const char* b2 = last ? nB : cB + (size_t)(t + 2) * kstep;
;             const char* a3 = a2 + kstep; const char* b3 = b2 + kstep;
;             if (last && has_next) S.a_ready(nxt);
;             if constexpr (SP2) {
;             PG8_LDB(B0, 0, 0); PG8_LDB(B1, 0, 1); PG8_SCHED; PG8_LDA(At, 0, 0); PG8_STAGE(PG8_SA(1, 1), a1 + hstep, voffA);
;             PG8_WAIT_V(8); PG8_WAIT_L(0); PG8_BAR; PG8_MMA(0, 0, At, B0); PG8_MMA(0, 1, At, B1); PG8_BAR; PG8_SCHED;
;             PG8_LDA(At, 0, 1); PG8_STAGE(PG8_SB(0, 0), b2, voffB); PG8_STAGE(PG8_SB(0, 1), b2 + hstep, voffB); PG8_STAGE(PG8_SA(0, 0), a2, voffA);
.LBB0_647:
	v_add_u32_e32 v52, s54, v178
	v_add_u32_e32 v116, s55, v178
	ds_read_b128 v[16:19], v52
	ds_read_b128 v[20:23], v52 offset:1024
	ds_read_b128 v[48:51], v52 offset:2048
	ds_read_b128 v[52:55], v52 offset:3072
	ds_read_b128 v[80:83], v116
	ds_read_b128 v[84:87], v116 offset:1024
	ds_read_b128 v[112:115], v116 offset:2048
	ds_read_b128 v[116:119], v116 offset:3072
	s_add_u32 s44, s40, 0xfffe0080
	s_addc_u32 s45, s41, -1
	s_cmp_eq_u32 s59, 4
	s_cselect_b32 s47, s7, s45
	s_cselect_b32 s46, s15, s44
	s_cselect_b32 s45, s17, s58
	s_cselect_b32 s44, s39, s57
	v_lshl_add_u64 v[210:211], s[40:41], 0, v[170:171]
	s_add_i32 m0, s48, 0xc000
	ds_read_b128 v[174:177], v180
	ds_read_b128 v[182:185], v180 offset:1024
	ds_read_b128 v[186:189], v180 offset:2048
	ds_read_b128 v[190:193], v180 offset:3072
	ds_read_b128 v[194:197], v180 offset:4096
	ds_read_b128 v[198:201], v180 offset:5120
	ds_read_b128 v[202:205], v180 offset:6144
	ds_read_b128 v[206:209], v180 offset:7168
	global_load_lds_dwordx4 v[210:211], off
	v_lshl_add_u64 v[210:211], s[40:41], 0, v[172:173]
	s_add_i32 m0, s48, 0xe000
	s_nop 0
	global_load_lds_dwordx4 v[210:211], off
	s_waitcnt vmcnt(8)
	s_waitcnt lgkmcnt(0)
	s_barrier
	s_setprio 1
	s_waitcnt lgkmcnt(0)
	v_mfma_f32_16x16x32_bf16 v[36:39], v[16:19], v[174:177], v[36:39]
	v_mfma_f32_16x16x32_bf16 v[32:35], v[48:51], v[174:177], v[32:35]
	v_mfma_f32_16x16x32_bf16 v[68:71], v[16:19], v[186:189], v[68:71]
	v_mfma_f32_16x16x32_bf16 v[64:67], v[48:51], v[186:189], v[64:67]
	v_mfma_f32_16x16x32_bf16 v[100:103], v[16:19], v[194:197], v[100:103]
	v_mfma_f32_16x16x32_bf16 v[96:99], v[48:51], v[194:197], v[96:99]
	v_mfma_f32_16x16x32_bf16 v[132:135], v[16:19], v[202:205], v[132:135]
	v_mfma_f32_16x16x32_bf16 v[128:131], v[48:51], v[202:205], v[128:131]
	v_mfma_f32_16x16x32_bf16 v[36:39], v[20:23], v[182:185], v[36:39]
	v_mfma_f32_16x16x32_bf16 v[32:35], v[52:55], v[182:185], v[32:35]
	v_mfma_f32_16x16x32_bf16 v[68:71], v[20:23], v[190:193], v[68:71]
	v_mfma_f32_16x16x32_bf16 v[64:67], v[52:55], v[190:193], v[64:67]
	v_mfma_f32_16x16x32_bf16 v[100:103], v[20:23], v[198:201], v[100:103]
	v_mfma_f32_16x16x32_bf16 v[96:99], v[52:55], v[198:201], v[96:99]
	v_mfma_f32_16x16x32_bf16 v[132:135], v[20:23], v[206:209], v[132:135]
	v_mfma_f32_16x16x32_bf16 v[128:131], v[52:55], v[206:209], v[128:131]
	v_mfma_f32_16x16x32_bf16 v[156:159], v[80:83], v[174:177], v[156:159]
	v_mfma_f32_16x16x32_bf16 v[152:155], v[112:115], v[174:177], v[152:155]
	v_mfma_f32_16x16x32_bf16 v[148:151], v[80:83], v[186:189], v[148:151]
	v_mfma_f32_16x16x32_bf16 v[144:147], v[112:115], v[186:189], v[144:147]
	v_mfma_f32_16x16x32_bf16 v[140:143], v[80:83], v[194:197], v[140:143]
	v_mfma_f32_16x16x32_bf16 v[136:139], v[112:115], v[194:197], v[136:139]
	v_mfma_f32_16x16x32_bf16 v[124:127], v[80:83], v[202:205], v[124:127]
	v_mfma_f32_16x16x32_bf16 v[120:123], v[112:115], v[202:205], v[120:123]
	v_mfma_f32_16x16x32_bf16 v[156:159], v[84:87], v[182:185], v[156:159]
	v_mfma_f32_16x16x32_bf16 v[152:155], v[116:119], v[182:185], v[152:155]
	v_mfma_f32_16x16x32_bf16 v[148:151], v[84:87], v[190:193], v[148:151]
	v_mfma_f32_16x16x32_bf16 v[144:147], v[116:119], v[190:193], v[144:147]
	v_mfma_f32_16x16x32_bf16 v[140:143], v[84:87], v[198:201], v[140:143]
	v_mfma_f32_16x16x32_bf16 v[136:139], v[116:119], v[198:201], v[136:139]
	v_mfma_f32_16x16x32_bf16 v[124:127], v[84:87], v[206:209], v[124:127]
	v_mfma_f32_16x16x32_bf16 v[120:123], v[116:119], v[206:209], v[120:123]
	s_setprio 0
	s_barrier
	s_add_i32 s60, s54, s19
	v_lshl_add_u64 v[214:215], s[44:45], 0, v[164:165]
	s_mov_b32 m0, s60
	ds_read_b128 v[174:177], v180 offset:16384
	ds_read_b128 v[182:185], v180 offset:17408
	ds_read_b128 v[186:189], v180 offset:18432
	ds_read_b128 v[190:193], v180 offset:19456
	ds_read_b128 v[194:197], v180 offset:20480
	ds_read_b128 v[198:201], v180 offset:21504
	ds_read_b128 v[202:205], v180 offset:22528
	ds_read_b128 v[206:209], v180 offset:23552
	global_load_lds_dwordx4 v[214:215], off
	s_add_i32 m0, s60, 0x2000
	s_add_u32 s60, s44, 0x20000
	v_lshl_add_u64 v[216:217], s[44:45], 0, v[168:169]
	s_addc_u32 s61, s45, 0
	s_add_i32 s63, s55, s19
	global_load_lds_dwordx4 v[216:217], off
	v_lshl_add_u64 v[210:211], s[60:61], 0, v[164:165]
	s_mov_b32 m0, s63
	v_lshl_add_u64 v[218:219], s[46:47], 0, v[160:161]
	global_load_lds_dwordx4 v[210:211], off
	v_lshl_add_u64 v[210:211], s[60:61], 0, v[168:169]
	s_add_i32 m0, s63, 0x2000
	v_lshl_add_u64 v[220:221], s[46:47], 0, v[166:167]
	global_load_lds_dwordx4 v[210:211], off
	s_mov_b32 m0, s48
	s_nop 0
	global_load_lds_dwordx4 v[218:219], off
	s_mov_b32 m0, s49
	s_nop 0
	global_load_lds_dwordx4 v[220:221], off
	s_waitcnt vmcnt(8)
	s_waitcnt lgkmcnt(0)
	s_barrier
; #define PG8_STAGE(bufoff, gbase, voff) do { _Pragma("unroll") for (int _i = 0; _i < 2; ++_i) \
;         __builtin_amdgcn_global_load_lds((const unsigned*)((const char*)(gbase) + (voff)[_i]), (PG8_LAS unsigned*)(lds + (bufoff) + ldsw + _i * 8192), 16, 0, 0); } while (0)
; #define PG8_LDA(dst, b, h) do { _Pragma("unroll") for (int m = 0; m < 4; ++m) _Pragma("unroll") for (int k = 0; k < 2; ++k) dst[m][k] = *(const PG8_LAS bf16x8*)(lds + PG8_SA(b, h) + aoff + m * 2048 + k * 1024); } while (0)
; #define PG8_LDB(dst, b, h) do { _Pragma("unroll") for (int n = 0; n < 2; ++n) _Pragma("unroll") for (int k = 0; k < 2; ++k) dst[n][k] = *(const PG8_LAS bf16x8*)(lds + PG8_SB(b, h) + boff + n * 2048 + k * 1024); } while (0)
; #define PG8_MMA(ai, bj, At, Bt) do { __builtin_amdgcn_s_setprio(1); _Pragma("unroll") for (int m = 0; m < 4; ++m) _Pragma("unroll") for (int n = 0; n < 2; ++n) _Pragma("unroll") for (int k = 0; k < 2; ++k) \
;         acc[ai][bj][m][n] = __builtin_amdgcn_mfma_f32_16x16x32_bf16(Bt[n][k], At[m][k], acc[ai][bj][m][n], 0, 0, 0); __builtin_amdgcn_s_setprio(0); } while (0)
; #define PG8_WAIT_V(n) asm volatile("s_waitcnt vmcnt(" #n ")" ::: "memory")
; #define PG8_WAIT_L(n) asm volatile("s_waitcnt lgkmcnt(" #n ")" ::: "memory")
; #define PG8_BAR __builtin_amdgcn_s_barrier()
; #define PG8_SCHED __builtin_amdgcn_sched_barrier(0)
; template <class Epi, class Sched, bool ALIGN_EPI = false, bool SP2 = false>
; __device__ __forceinline__ void gemm_phase(PG8_LAS unsigned char* lds, const Gemm g, const Sched& S, const Epi& E) {
;     ...
;             PG8_LDA(At, 0, 1); PG8_STAGE(PG8_SB(0, 0), b2, voffB); PG8_STAGE(PG8_SB(0, 1), b2 + hstep, voffB); PG8_STAGE(PG8_SA(0, 0), a2, voffA);
;             PG8_WAIT_V(8); PG8_WAIT_L(0); PG8_BAR; PG8_MMA(1, 0, At, B0); PG8_MMA(1, 1, At, B1); PG8_BAR; PG8_SCHED;
;             PG8_LDB(B0, 1, 0); PG8_LDB(B1, 1, 1); PG8_SCHED; PG8_LDA(At, 1, 0); PG8_STAGE(PG8_SA(0, 1), a2 + hstep, voffA);
;             PG8_WAIT_V(8); PG8_WAIT_L(0); PG8_BAR; PG8_MMA(0, 0, At, B0); PG8_MMA(0, 1, At, B1); PG8_BAR; PG8_SCHED;
	s_setprio 1
	s_waitcnt lgkmcnt(0)
	v_mfma_f32_16x16x32_bf16 v[108:111], v[16:19], v[174:177], v[108:111]
	v_mfma_f32_16x16x32_bf16 v[104:107], v[48:51], v[174:177], v[104:107]
	v_mfma_f32_16x16x32_bf16 v[76:79], v[16:19], v[186:189], v[76:79]
	v_mfma_f32_16x16x32_bf16 v[72:75], v[48:51], v[186:189], v[72:75]
	v_mfma_f32_16x16x32_bf16 v[44:47], v[16:19], v[194:197], v[44:47]
	v_mfma_f32_16x16x32_bf16 v[40:43], v[48:51], v[194:197], v[40:43]
	v_mfma_f32_16x16x32_bf16 v[12:15], v[16:19], v[202:205], v[12:15]
	v_mfma_f32_16x16x32_bf16 v[8:11], v[48:51], v[202:205], v[8:11]
	v_mfma_f32_16x16x32_bf16 v[108:111], v[20:23], v[182:185], v[108:111]
	v_mfma_f32_16x16x32_bf16 v[104:107], v[52:55], v[182:185], v[104:107]
	v_mfma_f32_16x16x32_bf16 v[76:79], v[20:23], v[190:193], v[76:79]
	v_mfma_f32_16x16x32_bf16 v[72:75], v[52:55], v[190:193], v[72:75]
	v_mfma_f32_16x16x32_bf16 v[44:47], v[20:23], v[198:201], v[44:47]
	v_mfma_f32_16x16x32_bf16 v[40:43], v[52:55], v[198:201], v[40:43]
	v_mfma_f32_16x16x32_bf16 v[12:15], v[20:23], v[206:209], v[12:15]
	v_mfma_f32_16x16x32_bf16 v[8:11], v[52:55], v[206:209], v[8:11]
	v_mfma_f32_16x16x32_bf16 v[28:31], v[80:83], v[194:197], v[28:31]
	v_mfma_f32_16x16x32_bf16 v[24:27], v[112:115], v[194:197], v[24:27]
	v_mfma_f32_16x16x32_bf16 v[4:7], v[80:83], v[202:205], v[4:7]
	v_mfma_f32_16x16x32_bf16 v[0:3], v[112:115], v[202:205], v[0:3]
	v_mfma_f32_16x16x32_bf16 v[16:19], v[80:83], v[174:177], v[92:95]
	v_mfma_f32_16x16x32_bf16 v[20:23], v[112:115], v[174:177], v[88:91]
	v_mfma_f32_16x16x32_bf16 v[48:51], v[80:83], v[186:189], v[60:63]
	v_mfma_f32_16x16x32_bf16 v[52:55], v[112:115], v[186:189], v[56:59]
	v_mfma_f32_16x16x32_bf16 v[28:31], v[84:87], v[198:201], v[28:31]
	v_mfma_f32_16x16x32_bf16 v[24:27], v[116:119], v[198:201], v[24:27]
	v_mfma_f32_16x16x32_bf16 v[4:7], v[84:87], v[206:209], v[4:7]
	v_mfma_f32_16x16x32_bf16 v[0:3], v[116:119], v[206:209], v[0:3]
	v_mfma_f32_16x16x32_bf16 v[16:19], v[84:87], v[182:185], v[16:19]
	v_mfma_f32_16x16x32_bf16 v[20:23], v[116:119], v[182:185], v[20:23]
	v_mfma_f32_16x16x32_bf16 v[48:51], v[84:87], v[190:193], v[48:51]
	v_mfma_f32_16x16x32_bf16 v[52:55], v[116:119], v[190:193], v[52:55]
	s_setprio 0
	s_barrier
	s_add_i32 s60, 0, 0x18000
	s_add_i32 s61, 0, 0x1c000
	v_add_u32_e32 v84, s60, v178
	v_add_u32_e32 v88, s61, v178
	ds_read_b128 v[56:59], v84
	ds_read_b128 v[60:63], v84 offset:1024
	ds_read_b128 v[80:83], v84 offset:2048
	ds_read_b128 v[84:87], v84 offset:3072
	ds_read_b128 v[112:115], v88
	ds_read_b128 v[116:119], v88 offset:1024
	ds_read_b128 v[174:177], v88 offset:2048
	ds_read_b128 v[182:185], v88 offset:3072
	s_add_u32 s46, s46, 0x20000
	s_addc_u32 s47, s47, 0
	s_mov_b32 m0, s50
	v_lshl_add_u64 v[210:211], s[46:47], 0, v[160:161]
	ds_read_b128 v[88:91], v180 offset:32768
	ds_read_b128 v[92:95], v180 offset:33792
	ds_read_b128 v[186:189], v180 offset:34816
	ds_read_b128 v[190:193], v180 offset:35840
	ds_read_b128 v[194:197], v180 offset:36864
	ds_read_b128 v[198:201], v180 offset:37888
	ds_read_b128 v[202:205], v180 offset:38912
	ds_read_b128 v[206:209], v180 offset:39936
	global_load_lds_dwordx4 v[210:211], off
	v_lshl_add_u64 v[210:211], s[46:47], 0, v[166:167]
	s_mov_b32 m0, s51
	s_nop 0
	global_load_lds_dwordx4 v[210:211], off
	s_waitcnt vmcnt(8)
	s_waitcnt lgkmcnt(0)
	s_barrier
	s_setprio 1
	s_waitcnt lgkmcnt(0)
	v_mfma_f32_16x16x32_bf16 v[36:39], v[56:59], v[88:91], v[36:39]
	v_mfma_f32_16x16x32_bf16 v[32:35], v[80:83], v[88:91], v[32:35]
	v_mfma_f32_16x16x32_bf16 v[68:71], v[56:59], v[186:189], v[68:71]
	v_mfma_f32_16x16x32_bf16 v[64:67], v[80:83], v[186:189], v[64:67]
	v_mfma_f32_16x16x32_bf16 v[100:103], v[56:59], v[194:197], v[100:103]
	v_mfma_f32_16x16x32_bf16 v[96:99], v[80:83], v[194:197], v[96:99]
	v_mfma_f32_16x16x32_bf16 v[132:135], v[56:59], v[202:205], v[132:135]
	v_mfma_f32_16x16x32_bf16 v[128:131], v[80:83], v[202:205], v[128:131]
	v_mfma_f32_16x16x32_bf16 v[36:39], v[60:63], v[92:95], v[36:39]
	v_mfma_f32_16x16x32_bf16 v[32:35], v[84:87], v[92:95], v[32:35]
	v_mfma_f32_16x16x32_bf16 v[68:71], v[60:63], v[190:193], v[68:71]
	v_mfma_f32_16x16x32_bf16 v[64:67], v[84:87], v[190:193], v[64:67]
	v_mfma_f32_16x16x32_bf16 v[100:103], v[60:63], v[198:201], v[100:103]
	v_mfma_f32_16x16x32_bf16 v[96:99], v[84:87], v[198:201], v[96:99]
	v_mfma_f32_16x16x32_bf16 v[132:135], v[60:63], v[206:209], v[132:135]
	v_mfma_f32_16x16x32_bf16 v[128:131], v[84:87], v[206:209], v[128:131]
	v_mfma_f32_16x16x32_bf16 v[156:159], v[112:115], v[88:91], v[156:159]
	v_mfma_f32_16x16x32_bf16 v[88:91], v[174:177], v[88:91], v[152:155]
	v_mfma_f32_16x16x32_bf16 v[152:155], v[182:185], v[92:95], v[88:91]
	v_mfma_f32_16x16x32_bf16 v[88:91], v[112:115], v[186:189], v[148:151]
	v_mfma_f32_16x16x32_bf16 v[148:151], v[116:119], v[190:193], v[88:91]
	v_mfma_f32_16x16x32_bf16 v[88:91], v[174:177], v[186:189], v[144:147]
	v_mfma_f32_16x16x32_bf16 v[144:147], v[182:185], v[190:193], v[88:91]
	v_mfma_f32_16x16x32_bf16 v[88:91], v[112:115], v[194:197], v[140:143]
	v_mfma_f32_16x16x32_bf16 v[140:143], v[116:119], v[198:201], v[88:91]
	v_mfma_f32_16x16x32_bf16 v[88:91], v[174:177], v[194:197], v[136:139]
	v_mfma_f32_16x16x32_bf16 v[136:139], v[182:185], v[198:201], v[88:91]
	v_mfma_f32_16x16x32_bf16 v[88:91], v[112:115], v[202:205], v[124:127]
	v_mfma_f32_16x16x32_bf16 v[124:127], v[116:119], v[206:209], v[88:91]
	v_mfma_f32_16x16x32_bf16 v[88:91], v[174:177], v[202:205], v[120:123]
	v_mfma_f32_16x16x32_bf16 v[156:159], v[116:119], v[92:95], v[156:159]
	v_mfma_f32_16x16x32_bf16 v[120:123], v[182:185], v[206:209], v[88:91]
	s_setprio 0
	s_barrier
; #define PG8_STAGE(bufoff, gbase, voff) do { _Pragma("unroll") for (int _i = 0; _i < 2; ++_i) \
;         __builtin_amdgcn_global_load_lds((const unsigned*)((const char*)(gbase) + (voff)[_i]), (PG8_LAS unsigned*)(lds + (bufoff) + ldsw + _i * 8192), 16, 0, 0); } while (0)
; #define PG8_LDA(dst, b, h) do { _Pragma("unroll") for (int m = 0; m < 4; ++m) _Pragma("unroll") for (int k = 0; k < 2; ++k) dst[m][k] = *(const PG8_LAS bf16x8*)(lds + PG8_SA(b, h) + aoff + m * 2048 + k * 1024); } while (0)
; #define PG8_MMA(ai, bj, At, Bt) do { __builtin_amdgcn_s_setprio(1); _Pragma("unroll") for (int m = 0; m < 4; ++m) _Pragma("unroll") for (int n = 0; n < 2; ++n) _Pragma("unroll") for (int k = 0; k < 2; ++k) \
;         acc[ai][bj][m][n] = __builtin_amdgcn_mfma_f32_16x16x32_bf16(Bt[n][k], At[m][k], acc[ai][bj][m][n], 0, 0, 0); __builtin_amdgcn_s_setprio(0); } while (0)
; #define PG8_WAIT_V(n) asm volatile("s_waitcnt vmcnt(" #n ")" ::: "memory")
; #define PG8_WAIT_L(n) asm volatile("s_waitcnt lgkmcnt(" #n ")" ::: "memory")
; #define PG8_BAR __builtin_amdgcn_s_barrier()
; #define PG8_SCHED __builtin_amdgcn_sched_barrier(0)
; template <class Epi, class Sched, bool ALIGN_EPI = false, bool SP2 = false>
; __device__ __forceinline__ void gemm_phase(PG8_LAS unsigned char* lds, const Gemm g, const Sched& S, const Epi& E) {
;     ...
;         for (int t = 0; t < nt; t += 2) {
;     ...
;             PG8_LDA(At, 1, 1); PG8_STAGE(PG8_SB(1, 0), b3, voffB); PG8_STAGE(PG8_SB(1, 1), b3 + hstep, voffB); PG8_STAGE(PG8_SA(1, 0), a3, voffA);
;             PG8_WAIT_V(8); PG8_WAIT_L(0); PG8_BAR; PG8_MMA(1, 0, At, B0); PG8_MMA(1, 1, At, B1); PG8_BAR; PG8_SCHED;
;     ...
;         if constexpr (ALIGN_EPI) { if (wr == 0) PG8_BAR; }
	s_add_i32 s46, s60, s19
	v_lshl_add_u64 v[92:93], v[214:215], 0, s[10:11]
	s_mov_b32 m0, s46
	s_nop 0
	ds_read_b128 v[88:91], v180 offset:49152
	ds_read_b128 v[186:189], v180 offset:50176
	ds_read_b128 v[190:193], v180 offset:51200
	ds_read_b128 v[194:197], v180 offset:52224
	ds_read_b128 v[198:201], v180 offset:53248
	ds_read_b128 v[202:205], v180 offset:54272
	ds_read_b128 v[206:209], v180 offset:55296
	ds_read_b128 v[210:213], v180 offset:56320
	global_load_lds_dwordx4 v[92:93], off
	s_add_i32 m0, s46, 0x2000
	s_add_u32 s44, s44, 0x20080
	v_lshl_add_u64 v[92:93], v[216:217], 0, s[10:11]
	s_addc_u32 s45, s45, 0
	s_add_i32 s46, s61, s19
	global_load_lds_dwordx4 v[92:93], off
	v_lshl_add_u64 v[92:93], s[44:45], 0, v[164:165]
	s_mov_b32 m0, s46
	s_nop 0
	global_load_lds_dwordx4 v[92:93], off
	v_lshl_add_u64 v[92:93], s[44:45], 0, v[168:169]
	s_add_i32 m0, s46, 0x2000
	s_nop 0
	global_load_lds_dwordx4 v[92:93], off
	v_lshl_add_u64 v[92:93], v[218:219], 0, s[10:11]
	s_mov_b32 m0, s52
	s_nop 0
	global_load_lds_dwordx4 v[92:93], off
	v_lshl_add_u64 v[92:93], v[220:221], 0, s[10:11]
	s_mov_b32 m0, s53
	s_nop 0
	global_load_lds_dwordx4 v[92:93], off
	s_waitcnt vmcnt(8)
	s_waitcnt lgkmcnt(0)
	s_barrier
	s_setprio 1
	s_waitcnt lgkmcnt(0)
	v_mfma_f32_16x16x32_bf16 v[92:95], v[56:59], v[88:91], v[108:111]
	v_mfma_f32_16x16x32_bf16 v[108:111], v[60:63], v[186:189], v[92:95]
	v_mfma_f32_16x16x32_bf16 v[92:95], v[80:83], v[88:91], v[104:107]
	v_mfma_f32_16x16x32_bf16 v[76:79], v[56:59], v[190:193], v[76:79]
	v_mfma_f32_16x16x32_bf16 v[72:75], v[80:83], v[190:193], v[72:75]
	v_mfma_f32_16x16x32_bf16 v[44:47], v[56:59], v[198:201], v[44:47]
	v_mfma_f32_16x16x32_bf16 v[40:43], v[80:83], v[198:201], v[40:43]
	v_mfma_f32_16x16x32_bf16 v[12:15], v[56:59], v[206:209], v[12:15]
	v_mfma_f32_16x16x32_bf16 v[8:11], v[80:83], v[206:209], v[8:11]
	v_mfma_f32_16x16x32_bf16 v[104:107], v[84:87], v[186:189], v[92:95]
	v_mfma_f32_16x16x32_bf16 v[76:79], v[60:63], v[194:197], v[76:79]
	v_mfma_f32_16x16x32_bf16 v[72:75], v[84:87], v[194:197], v[72:75]
	v_mfma_f32_16x16x32_bf16 v[44:47], v[60:63], v[202:205], v[44:47]
	v_mfma_f32_16x16x32_bf16 v[40:43], v[84:87], v[202:205], v[40:43]
	v_mfma_f32_16x16x32_bf16 v[12:15], v[60:63], v[210:213], v[12:15]
	v_mfma_f32_16x16x32_bf16 v[8:11], v[84:87], v[210:213], v[8:11]
	v_mfma_f32_16x16x32_bf16 v[16:19], v[112:115], v[88:91], v[16:19]
	v_mfma_f32_16x16x32_bf16 v[92:95], v[116:119], v[186:189], v[16:19]
	v_mfma_f32_16x16x32_bf16 v[16:19], v[174:177], v[88:91], v[20:23]
	v_mfma_f32_16x16x32_bf16 v[88:91], v[182:185], v[186:189], v[16:19]
	v_mfma_f32_16x16x32_bf16 v[16:19], v[112:115], v[190:193], v[48:51]
	v_mfma_f32_16x16x32_bf16 v[60:63], v[116:119], v[194:197], v[16:19]
	v_mfma_f32_16x16x32_bf16 v[16:19], v[174:177], v[190:193], v[52:55]
	v_mfma_f32_16x16x32_bf16 v[56:59], v[182:185], v[194:197], v[16:19]
	v_mfma_f32_16x16x32_bf16 v[16:19], v[112:115], v[198:201], v[28:31]
	v_mfma_f32_16x16x32_bf16 v[28:31], v[116:119], v[202:205], v[16:19]
	v_mfma_f32_16x16x32_bf16 v[16:19], v[174:177], v[198:201], v[24:27]
	v_mfma_f32_16x16x32_bf16 v[4:7], v[112:115], v[206:209], v[4:7]
	v_mfma_f32_16x16x32_bf16 v[0:3], v[174:177], v[206:209], v[0:3]
	v_mfma_f32_16x16x32_bf16 v[24:27], v[182:185], v[202:205], v[16:19]
	v_mfma_f32_16x16x32_bf16 v[4:7], v[116:119], v[210:213], v[4:7]
	v_mfma_f32_16x16x32_bf16 v[0:3], v[182:185], v[210:213], v[0:3]
	s_setprio 0
	s_barrier
	s_add_i32 s59, s59, 2
	s_add_u32 s40, s40, 0x100
	s_addc_u32 s41, s41, 0
	s_add_u32 s57, s57, 0x100
	s_addc_u32 s58, s58, 0
	s_cmp_gt_u32 s59, 5
	s_cbranch_scc0 .LBB0_647
	s_and_b64 vcc, exec, s[12:13]
	s_cbranch_vccz .LBB0_650
	s_barrier

; #define PG8_STAGE(bufoff, gbase, voff) do { _Pragma("unroll") for (int _i = 0; _i < 2; ++_i) \
;         __builtin_amdgcn_global_load_lds((const unsigned*)((const char*)(gbase) + (voff)[_i]), (PG8_LAS unsigned*)(lds + (bufoff) + ldsw + _i * 8192), 16, 0, 0); } while (0)
; #define PG8_LDA(dst, b, h) do { _Pragma("unroll") for (int m = 0; m < 4; ++m) _Pragma("unroll") for (int k = 0; k < 2; ++k) dst[m][k] = *(const PG8_LAS bf16x8*)(lds + PG8_SA(b, h) + aoff + m * 2048 + k * 1024); } while (0)
; #define PG8_LDB(dst, b, h) do { _Pragma("unroll") for (int n = 0; n < 2; ++n) _Pragma("unroll") for (int k = 0; k < 2; ++k) dst[n][k] = *(const PG8_LAS bf16x8*)(lds + PG8_SB(b, h) + boff + n * 2048 + k * 1024); } while (0)
; #define PG8_MMA(ai, bj, At, Bt) do { __builtin_amdgcn_s_setprio(1); _Pragma("unroll") for (int m = 0; m < 4; ++m) _Pragma("unroll") for (int n = 0; n < 2; ++n) _Pragma("unroll") for (int k = 0; k < 2; ++k) \
;         acc[ai][bj][m][n] = __builtin_amdgcn_mfma_f32_16x16x32_bf16(Bt[n][k], At[m][k], acc[ai][bj][m][n], 0, 0, 0); __builtin_amdgcn_s_setprio(0); } while (0)
; #define PG8_WAIT_V(n) asm volatile("s_waitcnt vmcnt(" #n ")" ::: "memory")
; #define PG8_WAIT_L(n) asm volatile("s_waitcnt lgkmcnt(" #n ")" ::: "memory")
; template <class Epi, class Sched, bool ALIGN_EPI = false, bool SP2 = false>
; __device__ __forceinline__ void gemm_phase(PG8_LAS unsigned char* lds, const Gemm g, const Sched& S, const Epi& E) {
;     ...
;             const bool last = (t == nt - 2);
;             const char* a1 = cA + (size_t)(t + 1) * kstep;
;             const char* a2 = last ? nA : cA + (size_t)(t + 2) * kstep; const char* b2 = last ? nB : cB + (size_t)(t + 2) * kstep;
;             const char* a3 = a2 + kstep; const char* b3 = b2 + kstep;
;             if (last && has_next) S.a_ready(nxt);
;             if constexpr (SP2) {
;             PG8_LDB(B0, 0, 0); PG8_LDB(B1, 0, 1); PG8_SCHED; PG8_LDA(At, 0, 0); PG8_STAGE(PG8_SA(1, 1), a1 + hstep, voffA);
;             PG8_WAIT_V(8); PG8_WAIT_L(0); PG8_BAR; PG8_MMA(0, 0, At, B0); PG8_MMA(0, 1, At, B1); PG8_BAR; PG8_SCHED;
;             PG8_LDA(At, 0, 1); PG8_STAGE(PG8_SB(0, 0), b2, voffB); PG8_STAGE(PG8_SB(0, 1), b2 + hstep, voffB); PG8_STAGE(PG8_SA(0, 0), a2, voffA);
;             PG8_WAIT_V(8); PG8_WAIT_L(0); PG8_BAR; PG8_MMA(1, 0, At, B0); PG8_MMA(1, 1, At, B1); PG8_BAR; PG8_SCHED;
.LBB0_808:
	ds_read_b128 v[80:83], v168
	ds_read_b128 v[84:87], v168 offset:1024
	ds_read_b128 v[96:99], v168 offset:2048
	ds_read_b128 v[100:103], v168 offset:3072
	ds_read_b128 v[172:175], v169
	ds_read_b128 v[176:179], v169 offset:1024
	ds_read_b128 v[180:183], v169 offset:2048
	ds_read_b128 v[184:187], v169 offset:3072
	s_add_u32 s46, s44, 0xfffc0080
	s_addc_u32 s47, s45, -1
	s_cmp_eq_u32 s71, 12
	s_cselect_b32 s49, s23, s47
	s_cselect_b32 s48, s41, s46
	s_cselect_b32 s47, s21, s70
	s_cselect_b32 s46, s68, s69
	v_lshl_add_u64 v[160:161], s[44:45], 0, v[152:153]
	s_add_i32 m0, s50, 0xc000
	ds_read_b128 v[188:191], v170
	ds_read_b128 v[192:195], v170 offset:1024
	ds_read_b128 v[196:199], v170 offset:2048
	ds_read_b128 v[200:203], v170 offset:3072
	ds_read_b128 v[204:207], v170 offset:4096
	ds_read_b128 v[208:211], v170 offset:5120
	ds_read_b128 v[212:215], v170 offset:6144
	ds_read_b128 v[216:219], v170 offset:7168
	global_load_lds_dwordx4 v[160:161], off
	v_lshl_add_u64 v[160:161], s[44:45], 0, v[154:155]
	s_add_i32 m0, s50, 0xe000
	s_nop 0
	global_load_lds_dwordx4 v[160:161], off
	s_waitcnt vmcnt(8)
	s_waitcnt lgkmcnt(0)
	s_barrier
	s_setprio 1
	s_waitcnt lgkmcnt(0)
	v_mfma_f32_16x16x32_bf16 v[140:143], v[80:83], v[188:191], v[140:143]
	v_mfma_f32_16x16x32_bf16 v[136:139], v[96:99], v[188:191], v[136:139]
	v_mfma_f32_16x16x32_bf16 v[124:127], v[80:83], v[196:199], v[124:127]
	v_mfma_f32_16x16x32_bf16 v[120:123], v[96:99], v[196:199], v[120:123]
	v_mfma_f32_16x16x32_bf16 v[108:111], v[80:83], v[204:207], v[108:111]
	v_mfma_f32_16x16x32_bf16 v[104:107], v[96:99], v[204:207], v[104:107]
	v_mfma_f32_16x16x32_bf16 v[76:79], v[80:83], v[212:215], v[76:79]
	v_mfma_f32_16x16x32_bf16 v[72:75], v[96:99], v[212:215], v[72:75]
	v_mfma_f32_16x16x32_bf16 v[140:143], v[84:87], v[192:195], v[140:143]
	v_mfma_f32_16x16x32_bf16 v[136:139], v[100:103], v[192:195], v[136:139]
	v_mfma_f32_16x16x32_bf16 v[124:127], v[84:87], v[200:203], v[124:127]
	v_mfma_f32_16x16x32_bf16 v[120:123], v[100:103], v[200:203], v[120:123]
	v_mfma_f32_16x16x32_bf16 v[108:111], v[84:87], v[208:211], v[108:111]
	v_mfma_f32_16x16x32_bf16 v[104:107], v[100:103], v[208:211], v[104:107]
	v_mfma_f32_16x16x32_bf16 v[76:79], v[84:87], v[216:219], v[76:79]
	v_mfma_f32_16x16x32_bf16 v[72:75], v[100:103], v[216:219], v[72:75]
	v_mfma_f32_16x16x32_bf16 v[132:135], v[172:175], v[188:191], v[132:135]
	v_mfma_f32_16x16x32_bf16 v[128:131], v[180:183], v[188:191], v[128:131]
	v_mfma_f32_16x16x32_bf16 v[116:119], v[172:175], v[196:199], v[116:119]
	v_mfma_f32_16x16x32_bf16 v[112:115], v[180:183], v[196:199], v[112:115]
	v_mfma_f32_16x16x32_bf16 v[92:95], v[172:175], v[204:207], v[92:95]
	v_mfma_f32_16x16x32_bf16 v[88:91], v[180:183], v[204:207], v[88:91]
	v_mfma_f32_16x16x32_bf16 v[68:71], v[172:175], v[212:215], v[68:71]
	v_mfma_f32_16x16x32_bf16 v[64:67], v[180:183], v[212:215], v[64:67]
	v_mfma_f32_16x16x32_bf16 v[132:135], v[176:179], v[192:195], v[132:135]
	v_mfma_f32_16x16x32_bf16 v[128:131], v[184:187], v[192:195], v[128:131]
	v_mfma_f32_16x16x32_bf16 v[116:119], v[176:179], v[200:203], v[116:119]
	v_mfma_f32_16x16x32_bf16 v[112:115], v[184:187], v[200:203], v[112:115]
	v_mfma_f32_16x16x32_bf16 v[92:95], v[176:179], v[208:211], v[92:95]
	v_mfma_f32_16x16x32_bf16 v[88:91], v[184:187], v[208:211], v[88:91]
	v_mfma_f32_16x16x32_bf16 v[68:71], v[176:179], v[216:219], v[68:71]
	v_mfma_f32_16x16x32_bf16 v[64:67], v[184:187], v[216:219], v[64:67]
	s_setprio 0
	s_barrier
	s_add_i32 s72, s63, s3
	v_lshl_add_u64 v[160:161], s[46:47], 0, v[146:147]
	s_mov_b32 m0, s72
	ds_read_b128 v[188:191], v170 offset:16384
	ds_read_b128 v[192:195], v170 offset:17408
	ds_read_b128 v[196:199], v170 offset:18432
	ds_read_b128 v[200:203], v170 offset:19456
	ds_read_b128 v[204:207], v170 offset:20480
	ds_read_b128 v[208:211], v170 offset:21504
	ds_read_b128 v[212:215], v170 offset:22528
	ds_read_b128 v[216:219], v170 offset:23552
	global_load_lds_dwordx4 v[160:161], off
	s_add_i32 m0, s72, 0x2000
	s_add_u32 s72, s46, 0x40000
	v_lshl_add_u64 v[164:165], s[46:47], 0, v[150:151]
	s_addc_u32 s73, s47, 0
	s_add_i32 s74, s64, s3
	global_load_lds_dwordx4 v[164:165], off
	v_lshl_add_u64 v[220:221], s[72:73], 0, v[146:147]
	s_mov_b32 m0, s74
	v_lshl_add_u64 v[222:223], s[48:49], 0, v[148:149]
	global_load_lds_dwordx4 v[220:221], off
	v_lshl_add_u64 v[220:221], s[72:73], 0, v[150:151]
	s_add_i32 m0, s74, 0x2000
	s_nop 0
	global_load_lds_dwordx4 v[220:221], off
	v_lshl_add_u64 v[220:221], s[48:49], 0, v[144:145]
	s_mov_b32 m0, s50
	s_nop 0
	global_load_lds_dwordx4 v[220:221], off
	s_mov_b32 m0, s51
	s_nop 0
	global_load_lds_dwordx4 v[222:223], off
	s_waitcnt vmcnt(8)
	s_waitcnt lgkmcnt(0)
	s_barrier
; #define PG8_STAGE(bufoff, gbase, voff) do { _Pragma("unroll") for (int _i = 0; _i < 2; ++_i) \
;         __builtin_amdgcn_global_load_lds((const unsigned*)((const char*)(gbase) + (voff)[_i]), (PG8_LAS unsigned*)(lds + (bufoff) + ldsw + _i * 8192), 16, 0, 0); } while (0)
; #define PG8_LDA(dst, b, h) do { _Pragma("unroll") for (int m = 0; m < 4; ++m) _Pragma("unroll") for (int k = 0; k < 2; ++k) dst[m][k] = *(const PG8_LAS bf16x8*)(lds + PG8_SA(b, h) + aoff + m * 2048 + k * 1024); } while (0)
; #define PG8_LDB(dst, b, h) do { _Pragma("unroll") for (int n = 0; n < 2; ++n) _Pragma("unroll") for (int k = 0; k < 2; ++k) dst[n][k] = *(const PG8_LAS bf16x8*)(lds + PG8_SB(b, h) + boff + n * 2048 + k * 1024); } while (0)
; #define PG8_MMA(ai, bj, At, Bt) do { __builtin_amdgcn_s_setprio(1); _Pragma("unroll") for (int m = 0; m < 4; ++m) _Pragma("unroll") for (int n = 0; n < 2; ++n) _Pragma("unroll") for (int k = 0; k < 2; ++k) \
;         acc[ai][bj][m][n] = __builtin_amdgcn_mfma_f32_16x16x32_bf16(Bt[n][k], At[m][k], acc[ai][bj][m][n], 0, 0, 0); __builtin_amdgcn_s_setprio(0); } while (0)
; #define PG8_WAIT_V(n) asm volatile("s_waitcnt vmcnt(" #n ")" ::: "memory")
; #define PG8_WAIT_L(n) asm volatile("s_waitcnt lgkmcnt(" #n ")" ::: "memory")
; #define PG8_BAR __builtin_amdgcn_s_barrier()
; #define PG8_SCHED __builtin_amdgcn_sched_barrier(0)
; template <class Epi, class Sched, bool ALIGN_EPI = false, bool SP2 = false>
; __device__ __forceinline__ void gemm_phase(PG8_LAS unsigned char* lds, const Gemm g, const Sched& S, const Epi& E) {
;     ...
;             PG8_WAIT_V(8); PG8_WAIT_L(0); PG8_BAR; PG8_MMA(1, 0, At, B0); PG8_MMA(1, 1, At, B1); PG8_BAR; PG8_SCHED;
;             PG8_LDB(B0, 1, 0); PG8_LDB(B1, 1, 1); PG8_SCHED; PG8_LDA(At, 1, 0); PG8_STAGE(PG8_SA(0, 1), a2 + hstep, voffA);
;             PG8_WAIT_V(8); PG8_WAIT_L(0); PG8_BAR; PG8_MMA(0, 0, At, B0); PG8_MMA(0, 1, At, B1); PG8_BAR; PG8_SCHED;
	s_setprio 1
	s_waitcnt lgkmcnt(0)
	v_mfma_f32_16x16x32_bf16 v[60:63], v[80:83], v[188:191], v[60:63]
	v_mfma_f32_16x16x32_bf16 v[56:59], v[96:99], v[188:191], v[56:59]
	v_mfma_f32_16x16x32_bf16 v[44:47], v[80:83], v[196:199], v[44:47]
	v_mfma_f32_16x16x32_bf16 v[40:43], v[96:99], v[196:199], v[40:43]
	v_mfma_f32_16x16x32_bf16 v[28:31], v[80:83], v[204:207], v[28:31]
	v_mfma_f32_16x16x32_bf16 v[24:27], v[96:99], v[204:207], v[24:27]
	v_mfma_f32_16x16x32_bf16 v[12:15], v[80:83], v[212:215], v[12:15]
	v_mfma_f32_16x16x32_bf16 v[8:11], v[96:99], v[212:215], v[8:11]
	v_mfma_f32_16x16x32_bf16 v[60:63], v[84:87], v[192:195], v[60:63]
	v_mfma_f32_16x16x32_bf16 v[56:59], v[100:103], v[192:195], v[56:59]
	v_mfma_f32_16x16x32_bf16 v[44:47], v[84:87], v[200:203], v[44:47]
	v_mfma_f32_16x16x32_bf16 v[40:43], v[100:103], v[200:203], v[40:43]
	v_mfma_f32_16x16x32_bf16 v[28:31], v[84:87], v[208:211], v[28:31]
	v_mfma_f32_16x16x32_bf16 v[24:27], v[100:103], v[208:211], v[24:27]
	v_mfma_f32_16x16x32_bf16 v[12:15], v[84:87], v[216:219], v[12:15]
	v_mfma_f32_16x16x32_bf16 v[8:11], v[100:103], v[216:219], v[8:11]
	v_mfma_f32_16x16x32_bf16 v[52:55], v[172:175], v[188:191], v[52:55]
	v_mfma_f32_16x16x32_bf16 v[48:51], v[180:183], v[188:191], v[48:51]
	v_mfma_f32_16x16x32_bf16 v[36:39], v[172:175], v[196:199], v[36:39]
	v_mfma_f32_16x16x32_bf16 v[32:35], v[180:183], v[196:199], v[32:35]
	v_mfma_f32_16x16x32_bf16 v[20:23], v[172:175], v[204:207], v[20:23]
	v_mfma_f32_16x16x32_bf16 v[16:19], v[180:183], v[204:207], v[16:19]
	v_mfma_f32_16x16x32_bf16 v[4:7], v[172:175], v[212:215], v[4:7]
	v_mfma_f32_16x16x32_bf16 v[0:3], v[180:183], v[212:215], v[0:3]
	v_mfma_f32_16x16x32_bf16 v[52:55], v[176:179], v[192:195], v[52:55]
	v_mfma_f32_16x16x32_bf16 v[48:51], v[184:187], v[192:195], v[48:51]
	v_mfma_f32_16x16x32_bf16 v[36:39], v[176:179], v[200:203], v[36:39]
	v_mfma_f32_16x16x32_bf16 v[32:35], v[184:187], v[200:203], v[32:35]
	v_mfma_f32_16x16x32_bf16 v[20:23], v[176:179], v[208:211], v[20:23]
	v_mfma_f32_16x16x32_bf16 v[16:19], v[184:187], v[208:211], v[16:19]
	v_mfma_f32_16x16x32_bf16 v[4:7], v[176:179], v[216:219], v[4:7]
	v_mfma_f32_16x16x32_bf16 v[0:3], v[184:187], v[216:219], v[0:3]
	s_setprio 0
	s_barrier
	s_add_i32 s72, 0, 0x18000
	s_add_i32 s73, 0, 0x1c000
	v_add_u32_e32 v100, s72, v166
	v_add_u32_e32 v184, s73, v166
	ds_read_b128 v[80:83], v100
	ds_read_b128 v[84:87], v100 offset:1024
	ds_read_b128 v[96:99], v100 offset:2048
	ds_read_b128 v[100:103], v100 offset:3072
	ds_read_b128 v[172:175], v184
	ds_read_b128 v[176:179], v184 offset:1024
	ds_read_b128 v[180:183], v184 offset:2048
	ds_read_b128 v[184:187], v184 offset:3072
	s_add_u32 s48, s48, 0x40000
	s_addc_u32 s49, s49, 0
	s_mov_b32 m0, s52
	v_lshl_add_u64 v[224:225], s[48:49], 0, v[144:145]
	ds_read_b128 v[188:191], v170 offset:32768
	ds_read_b128 v[192:195], v170 offset:33792
	ds_read_b128 v[196:199], v170 offset:34816
	ds_read_b128 v[200:203], v170 offset:35840
	ds_read_b128 v[204:207], v170 offset:36864
	ds_read_b128 v[208:211], v170 offset:37888
	ds_read_b128 v[212:215], v170 offset:38912
	ds_read_b128 v[216:219], v170 offset:39936
	global_load_lds_dwordx4 v[224:225], off
	v_lshl_add_u64 v[224:225], s[48:49], 0, v[148:149]
	s_mov_b32 m0, s53
	s_nop 0
	global_load_lds_dwordx4 v[224:225], off
	s_waitcnt vmcnt(8)
	s_waitcnt lgkmcnt(0)
	s_barrier
	s_setprio 1
	s_waitcnt lgkmcnt(0)
	v_mfma_f32_16x16x32_bf16 v[140:143], v[80:83], v[188:191], v[140:143]
	v_mfma_f32_16x16x32_bf16 v[136:139], v[96:99], v[188:191], v[136:139]
	v_mfma_f32_16x16x32_bf16 v[124:127], v[80:83], v[196:199], v[124:127]
	v_mfma_f32_16x16x32_bf16 v[120:123], v[96:99], v[196:199], v[120:123]
	v_mfma_f32_16x16x32_bf16 v[108:111], v[80:83], v[204:207], v[108:111]
	v_mfma_f32_16x16x32_bf16 v[104:107], v[96:99], v[204:207], v[104:107]
	v_mfma_f32_16x16x32_bf16 v[76:79], v[80:83], v[212:215], v[76:79]
	v_mfma_f32_16x16x32_bf16 v[72:75], v[96:99], v[212:215], v[72:75]
	v_mfma_f32_16x16x32_bf16 v[140:143], v[84:87], v[192:195], v[140:143]
	v_mfma_f32_16x16x32_bf16 v[136:139], v[100:103], v[192:195], v[136:139]
	v_mfma_f32_16x16x32_bf16 v[124:127], v[84:87], v[200:203], v[124:127]
	v_mfma_f32_16x16x32_bf16 v[120:123], v[100:103], v[200:203], v[120:123]
	v_mfma_f32_16x16x32_bf16 v[108:111], v[84:87], v[208:211], v[108:111]
	v_mfma_f32_16x16x32_bf16 v[104:107], v[100:103], v[208:211], v[104:107]
	v_mfma_f32_16x16x32_bf16 v[76:79], v[84:87], v[216:219], v[76:79]
	v_mfma_f32_16x16x32_bf16 v[72:75], v[100:103], v[216:219], v[72:75]
	v_mfma_f32_16x16x32_bf16 v[132:135], v[172:175], v[188:191], v[132:135]
	v_mfma_f32_16x16x32_bf16 v[128:131], v[180:183], v[188:191], v[128:131]
	v_mfma_f32_16x16x32_bf16 v[116:119], v[172:175], v[196:199], v[116:119]
	v_mfma_f32_16x16x32_bf16 v[112:115], v[180:183], v[196:199], v[112:115]
	v_mfma_f32_16x16x32_bf16 v[92:95], v[172:175], v[204:207], v[92:95]
	v_mfma_f32_16x16x32_bf16 v[88:91], v[180:183], v[204:207], v[88:91]
	v_mfma_f32_16x16x32_bf16 v[68:71], v[172:175], v[212:215], v[68:71]
	v_mfma_f32_16x16x32_bf16 v[64:67], v[180:183], v[212:215], v[64:67]
	v_mfma_f32_16x16x32_bf16 v[132:135], v[176:179], v[192:195], v[132:135]
	v_mfma_f32_16x16x32_bf16 v[128:131], v[184:187], v[192:195], v[128:131]
	v_mfma_f32_16x16x32_bf16 v[116:119], v[176:179], v[200:203], v[116:119]
	v_mfma_f32_16x16x32_bf16 v[112:115], v[184:187], v[200:203], v[112:115]
	v_mfma_f32_16x16x32_bf16 v[92:95], v[176:179], v[208:211], v[92:95]
	v_mfma_f32_16x16x32_bf16 v[88:91], v[184:187], v[208:211], v[88:91]
	v_mfma_f32_16x16x32_bf16 v[68:71], v[176:179], v[216:219], v[68:71]
	v_mfma_f32_16x16x32_bf16 v[64:67], v[184:187], v[216:219], v[64:67]
	s_setprio 0
	s_barrier
; #define PG8_STAGE(bufoff, gbase, voff) do { _Pragma("unroll") for (int _i = 0; _i < 2; ++_i) \
;         __builtin_amdgcn_global_load_lds((const unsigned*)((const char*)(gbase) + (voff)[_i]), (PG8_LAS unsigned*)(lds + (bufoff) + ldsw + _i * 8192), 16, 0, 0); } while (0)
; #define PG8_LDA(dst, b, h) do { _Pragma("unroll") for (int m = 0; m < 4; ++m) _Pragma("unroll") for (int k = 0; k < 2; ++k) dst[m][k] = *(const PG8_LAS bf16x8*)(lds + PG8_SA(b, h) + aoff + m * 2048 + k * 1024); } while (0)
; #define PG8_MMA(ai, bj, At, Bt) do { __builtin_amdgcn_s_setprio(1); _Pragma("unroll") for (int m = 0; m < 4; ++m) _Pragma("unroll") for (int n = 0; n < 2; ++n) _Pragma("unroll") for (int k = 0; k < 2; ++k) \
;         acc[ai][bj][m][n] = __builtin_amdgcn_mfma_f32_16x16x32_bf16(Bt[n][k], At[m][k], acc[ai][bj][m][n], 0, 0, 0); __builtin_amdgcn_s_setprio(0); } while (0)
; #define PG8_WAIT_V(n) asm volatile("s_waitcnt vmcnt(" #n ")" ::: "memory")
; #define PG8_WAIT_L(n) asm volatile("s_waitcnt lgkmcnt(" #n ")" ::: "memory")
; #define PG8_BAR __builtin_amdgcn_s_barrier()
; #define PG8_SCHED __builtin_amdgcn_sched_barrier(0)
; template <class Epi, class Sched, bool ALIGN_EPI = false, bool SP2 = false>
; __device__ __forceinline__ void gemm_phase(PG8_LAS unsigned char* lds, const Gemm g, const Sched& S, const Epi& E) {
;     ...
;             PG8_LDA(At, 1, 1); PG8_STAGE(PG8_SB(1, 0), b3, voffB); PG8_STAGE(PG8_SB(1, 1), b3 + hstep, voffB); PG8_STAGE(PG8_SA(1, 0), a3, voffA);
;             PG8_WAIT_V(8); PG8_WAIT_L(0); PG8_BAR; PG8_MMA(1, 0, At, B0); PG8_MMA(1, 1, At, B1); PG8_BAR; PG8_SCHED;
;     ...
;         if constexpr (ALIGN_EPI) { if (wr == 0) PG8_BAR; }
	s_add_i32 s48, s72, s3
	v_lshl_add_u64 v[160:161], v[160:161], 0, s[16:17]
	s_mov_b32 m0, s48
	ds_read_b128 v[188:191], v170 offset:49152
	ds_read_b128 v[192:195], v170 offset:50176
	ds_read_b128 v[196:199], v170 offset:51200
	ds_read_b128 v[200:203], v170 offset:52224
	ds_read_b128 v[204:207], v170 offset:53248
	ds_read_b128 v[208:211], v170 offset:54272
	ds_read_b128 v[212:215], v170 offset:55296
	ds_read_b128 v[216:219], v170 offset:56320
	global_load_lds_dwordx4 v[160:161], off
	s_add_i32 m0, s48, 0x2000
	s_add_u32 s46, s46, 0x40080
	v_lshl_add_u64 v[160:161], v[164:165], 0, s[16:17]
	s_addc_u32 s47, s47, 0
	s_add_i32 s48, s73, s3
	global_load_lds_dwordx4 v[160:161], off
	v_lshl_add_u64 v[160:161], s[46:47], 0, v[146:147]
	s_mov_b32 m0, s48
	s_nop 0
	global_load_lds_dwordx4 v[160:161], off
	v_lshl_add_u64 v[160:161], s[46:47], 0, v[150:151]
	s_add_i32 m0, s48, 0x2000
	s_nop 0
	global_load_lds_dwordx4 v[160:161], off
	v_lshl_add_u64 v[160:161], v[220:221], 0, s[16:17]
	s_mov_b32 m0, s57
	s_nop 0
	global_load_lds_dwordx4 v[160:161], off
	v_lshl_add_u64 v[160:161], v[222:223], 0, s[16:17]
	s_mov_b32 m0, s58
	s_nop 0
	global_load_lds_dwordx4 v[160:161], off
	s_waitcnt vmcnt(8)
	s_waitcnt lgkmcnt(0)
	s_barrier
	s_setprio 1
	s_waitcnt lgkmcnt(0)
	v_mfma_f32_16x16x32_bf16 v[60:63], v[80:83], v[188:191], v[60:63]
	v_mfma_f32_16x16x32_bf16 v[56:59], v[96:99], v[188:191], v[56:59]
	v_mfma_f32_16x16x32_bf16 v[44:47], v[80:83], v[196:199], v[44:47]
	v_mfma_f32_16x16x32_bf16 v[40:43], v[96:99], v[196:199], v[40:43]
	v_mfma_f32_16x16x32_bf16 v[28:31], v[80:83], v[204:207], v[28:31]
	v_mfma_f32_16x16x32_bf16 v[24:27], v[96:99], v[204:207], v[24:27]
	v_mfma_f32_16x16x32_bf16 v[12:15], v[80:83], v[212:215], v[12:15]
	v_mfma_f32_16x16x32_bf16 v[8:11], v[96:99], v[212:215], v[8:11]
	v_mfma_f32_16x16x32_bf16 v[60:63], v[84:87], v[192:195], v[60:63]
	v_mfma_f32_16x16x32_bf16 v[56:59], v[100:103], v[192:195], v[56:59]
	v_mfma_f32_16x16x32_bf16 v[44:47], v[84:87], v[200:203], v[44:47]
	v_mfma_f32_16x16x32_bf16 v[40:43], v[100:103], v[200:203], v[40:43]
	v_mfma_f32_16x16x32_bf16 v[28:31], v[84:87], v[208:211], v[28:31]
	v_mfma_f32_16x16x32_bf16 v[24:27], v[100:103], v[208:211], v[24:27]
	v_mfma_f32_16x16x32_bf16 v[12:15], v[84:87], v[216:219], v[12:15]
	v_mfma_f32_16x16x32_bf16 v[8:11], v[100:103], v[216:219], v[8:11]
	v_mfma_f32_16x16x32_bf16 v[52:55], v[172:175], v[188:191], v[52:55]
	v_mfma_f32_16x16x32_bf16 v[48:51], v[180:183], v[188:191], v[48:51]
	v_mfma_f32_16x16x32_bf16 v[36:39], v[172:175], v[196:199], v[36:39]
	v_mfma_f32_16x16x32_bf16 v[32:35], v[180:183], v[196:199], v[32:35]
	v_mfma_f32_16x16x32_bf16 v[20:23], v[172:175], v[204:207], v[20:23]
	v_mfma_f32_16x16x32_bf16 v[16:19], v[180:183], v[204:207], v[16:19]
	v_mfma_f32_16x16x32_bf16 v[4:7], v[172:175], v[212:215], v[4:7]
	v_mfma_f32_16x16x32_bf16 v[0:3], v[180:183], v[212:215], v[0:3]
	v_mfma_f32_16x16x32_bf16 v[52:55], v[176:179], v[192:195], v[52:55]
	v_mfma_f32_16x16x32_bf16 v[48:51], v[184:187], v[192:195], v[48:51]
	v_mfma_f32_16x16x32_bf16 v[36:39], v[176:179], v[200:203], v[36:39]
	v_mfma_f32_16x16x32_bf16 v[32:35], v[184:187], v[200:203], v[32:35]
	v_mfma_f32_16x16x32_bf16 v[20:23], v[176:179], v[208:211], v[20:23]
	v_mfma_f32_16x16x32_bf16 v[16:19], v[184:187], v[208:211], v[16:19]
	v_mfma_f32_16x16x32_bf16 v[4:7], v[176:179], v[216:219], v[4:7]
	v_mfma_f32_16x16x32_bf16 v[0:3], v[184:187], v[216:219], v[0:3]
	s_setprio 0
	s_barrier
	s_add_i32 s71, s71, 2
	s_add_u32 s44, s44, 0x100
	s_addc_u32 s45, s45, 0
	s_add_u32 s69, s69, 0x100
	s_addc_u32 s70, s70, 0
	s_cmp_gt_u32 s71, 13
	s_cbranch_scc0 .LBB0_808
	s_and_b64 vcc, exec, s[18:19]
	s_cbranch_vccz .LBB0_811
	s_barrier

; #define PG8_STAGE(bufoff, gbase, voff) do { _Pragma("unroll") for (int _i = 0; _i < 2; ++_i) \
;         __builtin_amdgcn_global_load_lds((const unsigned*)((const char*)(gbase) + (voff)[_i]), (PG8_LAS unsigned*)(lds + (bufoff) + ldsw + _i * 8192), 16, 0, 0); } while (0)
; #define PG8_LDA(dst, b, h) do { _Pragma("unroll") for (int m = 0; m < 4; ++m) _Pragma("unroll") for (int k = 0; k < 2; ++k) dst[m][k] = *(const PG8_LAS bf16x8*)(lds + PG8_SA(b, h) + aoff + m * 2048 + k * 1024); } while (0)
; #define PG8_LDB(dst, b, h) do { _Pragma("unroll") for (int n = 0; n < 2; ++n) _Pragma("unroll") for (int k = 0; k < 2; ++k) dst[n][k] = *(const PG8_LAS bf16x8*)(lds + PG8_SB(b, h) + boff + n * 2048 + k * 1024); } while (0)
; #define PG8_MMA(ai, bj, At, Bt) do { __builtin_amdgcn_s_setprio(1); _Pragma("unroll") for (int m = 0; m < 4; ++m) _Pragma("unroll") for (int n = 0; n < 2; ++n) _Pragma("unroll") for (int k = 0; k < 2; ++k) \
;         acc[ai][bj][m][n] = __builtin_amdgcn_mfma_f32_16x16x32_bf16(Bt[n][k], At[m][k], acc[ai][bj][m][n], 0, 0, 0); __builtin_amdgcn_s_setprio(0); } while (0)
; #define PG8_WAIT_V(n) asm volatile("s_waitcnt vmcnt(" #n ")" ::: "memory")
; #define PG8_WAIT_L(n) asm volatile("s_waitcnt lgkmcnt(" #n ")" ::: "memory")
; template <class Epi, class Sched, bool ALIGN_EPI = false, bool SP2 = false>
; __device__ __forceinline__ void gemm_phase(PG8_LAS unsigned char* lds, const Gemm g, const Sched& S, const Epi& E) {
;     ...
;             const bool last = (t == nt - 2);
;             const char* a1 = cA + (size_t)(t + 1) * kstep;
;             const char* a2 = last ? nA : cA + (size_t)(t + 2) * kstep; const char* b2 = last ? nB : cB + (size_t)(t + 2) * kstep;
;             const char* a3 = a2 + kstep; const char* b3 = b2 + kstep;
;             if (last && has_next) S.a_ready(nxt);
;             if constexpr (SP2) {
;             PG8_LDB(B0, 0, 0); PG8_LDB(B1, 0, 1); PG8_SCHED; PG8_LDA(At, 0, 0); PG8_STAGE(PG8_SA(1, 1), a1 + hstep, voffA);
;             PG8_WAIT_V(8); PG8_WAIT_L(0); PG8_BAR; PG8_MMA(0, 0, At, B0); PG8_MMA(0, 1, At, B1); PG8_BAR; PG8_SCHED;
;             PG8_LDA(At, 0, 1); PG8_STAGE(PG8_SB(0, 0), b2, voffB); PG8_STAGE(PG8_SB(0, 1), b2 + hstep, voffB); PG8_STAGE(PG8_SA(0, 0), a2, voffA);
;             PG8_WAIT_V(8); PG8_WAIT_L(0); PG8_BAR; PG8_MMA(1, 0, At, B0); PG8_MMA(1, 1, At, B1); PG8_BAR; PG8_SCHED;
.LBB0_907:
	ds_read_b128 v[132:135], v171
	ds_read_b128 v[136:139], v171 offset:1024
	ds_read_b128 v[140:143], v171 offset:2048
	ds_read_b128 v[174:177], v171 offset:3072
	ds_read_b128 v[178:181], v172
	ds_read_b128 v[182:185], v172 offset:1024
	ds_read_b128 v[186:189], v172 offset:2048
	ds_read_b128 v[190:193], v172 offset:3072
	s_add_u32 s59, s36, 0xfffc0080
	s_addc_u32 s60, s37, -1
	s_cmp_eq_u32 s21, 12
	s_cselect_b64 vcc, -1, 0
	s_and_b64 s[38:39], vcc, exec
	v_cndmask_b32_e32 v165, v131, v129, vcc
	s_cselect_b32 s39, s23, s60
	s_cselect_b32 s38, s58, s59
	v_cndmask_b32_e32 v164, v130, v128, vcc
	s_mov_b32 m0, s55
	v_lshl_add_u64 v[228:229], s[36:37], 0, v[154:155]
	ds_read_b128 v[194:197], v173
	ds_read_b128 v[198:201], v173 offset:1024
	ds_read_b128 v[202:205], v173 offset:2048
	ds_read_b128 v[206:209], v173 offset:3072
	ds_read_b128 v[210:213], v173 offset:4096
	ds_read_b128 v[214:217], v173 offset:5120
	ds_read_b128 v[218:221], v173 offset:6144
	ds_read_b128 v[222:225], v173 offset:7168
	global_load_lds_dwordx4 v[228:229], off
	v_lshl_add_u64 v[228:229], s[36:37], 0, v[156:157]
	s_mov_b32 m0, s56
	s_nop 0
	global_load_lds_dwordx4 v[228:229], off
	s_waitcnt vmcnt(8)
	s_waitcnt lgkmcnt(0)
	s_barrier
	s_setprio 1
	s_waitcnt lgkmcnt(0)
	v_mfma_f32_16x16x32_bf16 v[124:127], v[132:135], v[194:197], v[124:127]
	v_mfma_f32_16x16x32_bf16 v[120:123], v[140:143], v[194:197], v[120:123]
	v_mfma_f32_16x16x32_bf16 v[108:111], v[132:135], v[202:205], v[108:111]
	v_mfma_f32_16x16x32_bf16 v[104:107], v[140:143], v[202:205], v[104:107]
	v_mfma_f32_16x16x32_bf16 v[92:95], v[132:135], v[210:213], v[92:95]
	v_mfma_f32_16x16x32_bf16 v[88:91], v[140:143], v[210:213], v[88:91]
	v_mfma_f32_16x16x32_bf16 v[76:79], v[132:135], v[218:221], v[76:79]
	v_mfma_f32_16x16x32_bf16 v[72:75], v[140:143], v[218:221], v[72:75]
	v_mfma_f32_16x16x32_bf16 v[124:127], v[136:139], v[198:201], v[124:127]
	v_mfma_f32_16x16x32_bf16 v[120:123], v[174:177], v[198:201], v[120:123]
	v_mfma_f32_16x16x32_bf16 v[108:111], v[136:139], v[206:209], v[108:111]
	v_mfma_f32_16x16x32_bf16 v[104:107], v[174:177], v[206:209], v[104:107]
	v_mfma_f32_16x16x32_bf16 v[92:95], v[136:139], v[214:217], v[92:95]
	v_mfma_f32_16x16x32_bf16 v[88:91], v[174:177], v[214:217], v[88:91]
	v_mfma_f32_16x16x32_bf16 v[76:79], v[136:139], v[222:225], v[76:79]
	v_mfma_f32_16x16x32_bf16 v[72:75], v[174:177], v[222:225], v[72:75]
	v_mfma_f32_16x16x32_bf16 v[116:119], v[178:181], v[194:197], v[116:119]
	v_mfma_f32_16x16x32_bf16 v[112:115], v[186:189], v[194:197], v[112:115]
	v_mfma_f32_16x16x32_bf16 v[100:103], v[178:181], v[202:205], v[100:103]
	v_mfma_f32_16x16x32_bf16 v[96:99], v[186:189], v[202:205], v[96:99]
	v_mfma_f32_16x16x32_bf16 v[84:87], v[178:181], v[210:213], v[84:87]
	v_mfma_f32_16x16x32_bf16 v[80:83], v[186:189], v[210:213], v[80:83]
	v_mfma_f32_16x16x32_bf16 v[68:71], v[178:181], v[218:221], v[68:71]
	v_mfma_f32_16x16x32_bf16 v[64:67], v[186:189], v[218:221], v[64:67]
	v_mfma_f32_16x16x32_bf16 v[116:119], v[182:185], v[198:201], v[116:119]
	v_mfma_f32_16x16x32_bf16 v[112:115], v[190:193], v[198:201], v[112:115]
	v_mfma_f32_16x16x32_bf16 v[100:103], v[182:185], v[206:209], v[100:103]
	v_mfma_f32_16x16x32_bf16 v[96:99], v[190:193], v[206:209], v[96:99]
	v_mfma_f32_16x16x32_bf16 v[84:87], v[182:185], v[214:217], v[84:87]
	v_mfma_f32_16x16x32_bf16 v[80:83], v[190:193], v[214:217], v[80:83]
	v_mfma_f32_16x16x32_bf16 v[68:71], v[182:185], v[222:225], v[68:71]
	v_mfma_f32_16x16x32_bf16 v[64:67], v[190:193], v[222:225], v[64:67]
	s_setprio 0
	s_barrier
	s_add_i32 s59, s52, s40
	v_lshl_add_u64 v[228:229], v[164:165], 0, v[150:151]
	s_mov_b32 m0, s59
	ds_read_b128 v[194:197], v173 offset:16384
	ds_read_b128 v[198:201], v173 offset:17408
	ds_read_b128 v[202:205], v173 offset:18432
	ds_read_b128 v[206:209], v173 offset:19456
	ds_read_b128 v[210:213], v173 offset:20480
	ds_read_b128 v[214:217], v173 offset:21504
	ds_read_b128 v[218:221], v173 offset:22528
	ds_read_b128 v[222:225], v173 offset:23552
	global_load_lds_dwordx4 v[228:229], off
	v_lshl_add_u64 v[230:231], v[164:165], 0, v[146:147]
	s_add_i32 m0, s59, 0x2000
	v_lshl_add_u64 v[232:233], v[164:165], 0, s[0:1]
	s_add_i32 s59, s53, s40
	global_load_lds_dwordx4 v[230:231], off
	v_lshl_add_u64 v[234:235], v[232:233], 0, v[150:151]
	s_mov_b32 m0, s59
	v_lshl_add_u64 v[232:233], v[232:233], 0, v[146:147]
	global_load_lds_dwordx4 v[234:235], off
	s_add_i32 m0, s59, 0x2000
	v_lshl_add_u64 v[234:235], s[38:39], 0, v[148:149]
	global_load_lds_dwordx4 v[232:233], off
	v_lshl_add_u64 v[232:233], s[38:39], 0, v[152:153]
	s_mov_b32 m0, s31
	s_nop 0
	global_load_lds_dwordx4 v[232:233], off
	s_mov_b32 m0, s44
	s_nop 0
	global_load_lds_dwordx4 v[234:235], off
	s_waitcnt vmcnt(8)
	s_waitcnt lgkmcnt(0)
	s_barrier
; #define PG8_STAGE(bufoff, gbase, voff) do { _Pragma("unroll") for (int _i = 0; _i < 2; ++_i) \
;         __builtin_amdgcn_global_load_lds((const unsigned*)((const char*)(gbase) + (voff)[_i]), (PG8_LAS unsigned*)(lds + (bufoff) + ldsw + _i * 8192), 16, 0, 0); } while (0)
; #define PG8_LDA(dst, b, h) do { _Pragma("unroll") for (int m = 0; m < 4; ++m) _Pragma("unroll") for (int k = 0; k < 2; ++k) dst[m][k] = *(const PG8_LAS bf16x8*)(lds + PG8_SA(b, h) + aoff + m * 2048 + k * 1024); } while (0)
; #define PG8_LDB(dst, b, h) do { _Pragma("unroll") for (int n = 0; n < 2; ++n) _Pragma("unroll") for (int k = 0; k < 2; ++k) dst[n][k] = *(const PG8_LAS bf16x8*)(lds + PG8_SB(b, h) + boff + n * 2048 + k * 1024); } while (0)
; #define PG8_MMA(ai, bj, At, Bt) do { __builtin_amdgcn_s_setprio(1); _Pragma("unroll") for (int m = 0; m < 4; ++m) _Pragma("unroll") for (int n = 0; n < 2; ++n) _Pragma("unroll") for (int k = 0; k < 2; ++k) \
;         acc[ai][bj][m][n] = __builtin_amdgcn_mfma_f32_16x16x32_bf16(Bt[n][k], At[m][k], acc[ai][bj][m][n], 0, 0, 0); __builtin_amdgcn_s_setprio(0); } while (0)
; #define PG8_WAIT_V(n) asm volatile("s_waitcnt vmcnt(" #n ")" ::: "memory")
; #define PG8_WAIT_L(n) asm volatile("s_waitcnt lgkmcnt(" #n ")" ::: "memory")
; #define PG8_BAR __builtin_amdgcn_s_barrier()
; #define PG8_SCHED __builtin_amdgcn_sched_barrier(0)
; template <class Epi, class Sched, bool ALIGN_EPI = false, bool SP2 = false>
; __device__ __forceinline__ void gemm_phase(PG8_LAS unsigned char* lds, const Gemm g, const Sched& S, const Epi& E) {
;     ...
;             PG8_WAIT_V(8); PG8_WAIT_L(0); PG8_BAR; PG8_MMA(1, 0, At, B0); PG8_MMA(1, 1, At, B1); PG8_BAR; PG8_SCHED;
;             PG8_LDB(B0, 1, 0); PG8_LDB(B1, 1, 1); PG8_SCHED; PG8_LDA(At, 1, 0); PG8_STAGE(PG8_SA(0, 1), a2 + hstep, voffA);
;             PG8_WAIT_V(8); PG8_WAIT_L(0); PG8_BAR; PG8_MMA(0, 0, At, B0); PG8_MMA(0, 1, At, B1); PG8_BAR; PG8_SCHED;
	s_setprio 1
	s_waitcnt lgkmcnt(0)
	v_mfma_f32_16x16x32_bf16 v[60:63], v[132:135], v[194:197], v[60:63]
	v_mfma_f32_16x16x32_bf16 v[56:59], v[140:143], v[194:197], v[56:59]
	v_mfma_f32_16x16x32_bf16 v[44:47], v[132:135], v[202:205], v[44:47]
	v_mfma_f32_16x16x32_bf16 v[40:43], v[140:143], v[202:205], v[40:43]
	v_mfma_f32_16x16x32_bf16 v[28:31], v[132:135], v[210:213], v[28:31]
	v_mfma_f32_16x16x32_bf16 v[24:27], v[140:143], v[210:213], v[24:27]
	v_mfma_f32_16x16x32_bf16 v[12:15], v[132:135], v[218:221], v[12:15]
	v_mfma_f32_16x16x32_bf16 v[8:11], v[140:143], v[218:221], v[8:11]
	v_mfma_f32_16x16x32_bf16 v[60:63], v[136:139], v[198:201], v[60:63]
	v_mfma_f32_16x16x32_bf16 v[56:59], v[174:177], v[198:201], v[56:59]
	v_mfma_f32_16x16x32_bf16 v[44:47], v[136:139], v[206:209], v[44:47]
	v_mfma_f32_16x16x32_bf16 v[40:43], v[174:177], v[206:209], v[40:43]
	v_mfma_f32_16x16x32_bf16 v[28:31], v[136:139], v[214:217], v[28:31]
	v_mfma_f32_16x16x32_bf16 v[24:27], v[174:177], v[214:217], v[24:27]
	v_mfma_f32_16x16x32_bf16 v[12:15], v[136:139], v[222:225], v[12:15]
	v_mfma_f32_16x16x32_bf16 v[8:11], v[174:177], v[222:225], v[8:11]
	v_mfma_f32_16x16x32_bf16 v[52:55], v[178:181], v[194:197], v[52:55]
	v_mfma_f32_16x16x32_bf16 v[48:51], v[186:189], v[194:197], v[48:51]
	v_mfma_f32_16x16x32_bf16 v[36:39], v[178:181], v[202:205], v[36:39]
	v_mfma_f32_16x16x32_bf16 v[32:35], v[186:189], v[202:205], v[32:35]
	v_mfma_f32_16x16x32_bf16 v[20:23], v[178:181], v[210:213], v[20:23]
	v_mfma_f32_16x16x32_bf16 v[16:19], v[186:189], v[210:213], v[16:19]
	v_mfma_f32_16x16x32_bf16 v[4:7], v[178:181], v[218:221], v[4:7]
	v_mfma_f32_16x16x32_bf16 v[0:3], v[186:189], v[218:221], v[0:3]
	v_mfma_f32_16x16x32_bf16 v[52:55], v[182:185], v[198:201], v[52:55]
	v_mfma_f32_16x16x32_bf16 v[48:51], v[190:193], v[198:201], v[48:51]
	v_mfma_f32_16x16x32_bf16 v[36:39], v[182:185], v[206:209], v[36:39]
	v_mfma_f32_16x16x32_bf16 v[32:35], v[190:193], v[206:209], v[32:35]
	v_mfma_f32_16x16x32_bf16 v[20:23], v[182:185], v[214:217], v[20:23]
	v_mfma_f32_16x16x32_bf16 v[16:19], v[190:193], v[214:217], v[16:19]
	v_mfma_f32_16x16x32_bf16 v[4:7], v[182:185], v[222:225], v[4:7]
	v_mfma_f32_16x16x32_bf16 v[0:3], v[190:193], v[222:225], v[0:3]
	s_setprio 0
	s_barrier
	s_add_i32 s59, 0, 0x18000
	s_add_i32 s60, 0, 0x1c000
	v_add_u32_e32 v174, s59, v167
	v_add_u32_e32 v190, s60, v167
	ds_read_b128 v[132:135], v174
	ds_read_b128 v[136:139], v174 offset:1024
	ds_read_b128 v[140:143], v174 offset:2048
	ds_read_b128 v[174:177], v174 offset:3072
	ds_read_b128 v[178:181], v190
	ds_read_b128 v[182:185], v190 offset:1024
	ds_read_b128 v[186:189], v190 offset:2048
	ds_read_b128 v[190:193], v190 offset:3072
	s_add_u32 s38, s38, 0x40000
	s_addc_u32 s39, s39, 0
	s_mov_b32 m0, s45
	v_lshl_add_u64 v[236:237], s[38:39], 0, v[152:153]
	ds_read_b128 v[194:197], v173 offset:32768
	ds_read_b128 v[198:201], v173 offset:33792
	ds_read_b128 v[202:205], v173 offset:34816
	ds_read_b128 v[206:209], v173 offset:35840
	ds_read_b128 v[210:213], v173 offset:36864
	ds_read_b128 v[214:217], v173 offset:37888
	ds_read_b128 v[218:221], v173 offset:38912
	ds_read_b128 v[222:225], v173 offset:39936
	global_load_lds_dwordx4 v[236:237], off
	v_lshl_add_u64 v[236:237], s[38:39], 0, v[148:149]
	s_mov_b32 m0, s46
	s_nop 0
	global_load_lds_dwordx4 v[236:237], off
	s_waitcnt vmcnt(8)
	s_waitcnt lgkmcnt(0)
	s_barrier
	s_setprio 1
	s_waitcnt lgkmcnt(0)
	v_mfma_f32_16x16x32_bf16 v[124:127], v[132:135], v[194:197], v[124:127]
	v_mfma_f32_16x16x32_bf16 v[120:123], v[140:143], v[194:197], v[120:123]
	v_mfma_f32_16x16x32_bf16 v[108:111], v[132:135], v[202:205], v[108:111]
	v_mfma_f32_16x16x32_bf16 v[104:107], v[140:143], v[202:205], v[104:107]
	v_mfma_f32_16x16x32_bf16 v[92:95], v[132:135], v[210:213], v[92:95]
	v_mfma_f32_16x16x32_bf16 v[88:91], v[140:143], v[210:213], v[88:91]
	v_mfma_f32_16x16x32_bf16 v[76:79], v[132:135], v[218:221], v[76:79]
	v_mfma_f32_16x16x32_bf16 v[72:75], v[140:143], v[218:221], v[72:75]
	v_mfma_f32_16x16x32_bf16 v[124:127], v[136:139], v[198:201], v[124:127]
	v_mfma_f32_16x16x32_bf16 v[120:123], v[174:177], v[198:201], v[120:123]
	v_mfma_f32_16x16x32_bf16 v[108:111], v[136:139], v[206:209], v[108:111]
	v_mfma_f32_16x16x32_bf16 v[104:107], v[174:177], v[206:209], v[104:107]
	v_mfma_f32_16x16x32_bf16 v[92:95], v[136:139], v[214:217], v[92:95]
	v_mfma_f32_16x16x32_bf16 v[88:91], v[174:177], v[214:217], v[88:91]
	v_mfma_f32_16x16x32_bf16 v[76:79], v[136:139], v[222:225], v[76:79]
	v_mfma_f32_16x16x32_bf16 v[72:75], v[174:177], v[222:225], v[72:75]
	v_mfma_f32_16x16x32_bf16 v[116:119], v[178:181], v[194:197], v[116:119]
	v_mfma_f32_16x16x32_bf16 v[112:115], v[186:189], v[194:197], v[112:115]
	v_mfma_f32_16x16x32_bf16 v[100:103], v[178:181], v[202:205], v[100:103]
	v_mfma_f32_16x16x32_bf16 v[96:99], v[186:189], v[202:205], v[96:99]
	v_mfma_f32_16x16x32_bf16 v[84:87], v[178:181], v[210:213], v[84:87]
	v_mfma_f32_16x16x32_bf16 v[80:83], v[186:189], v[210:213], v[80:83]
	v_mfma_f32_16x16x32_bf16 v[68:71], v[178:181], v[218:221], v[68:71]
	v_mfma_f32_16x16x32_bf16 v[64:67], v[186:189], v[218:221], v[64:67]
	v_mfma_f32_16x16x32_bf16 v[116:119], v[182:185], v[198:201], v[116:119]
	v_mfma_f32_16x16x32_bf16 v[112:115], v[190:193], v[198:201], v[112:115]
	v_mfma_f32_16x16x32_bf16 v[100:103], v[182:185], v[206:209], v[100:103]
	v_mfma_f32_16x16x32_bf16 v[96:99], v[190:193], v[206:209], v[96:99]
	v_mfma_f32_16x16x32_bf16 v[84:87], v[182:185], v[214:217], v[84:87]
	v_mfma_f32_16x16x32_bf16 v[80:83], v[190:193], v[214:217], v[80:83]
	v_mfma_f32_16x16x32_bf16 v[68:71], v[182:185], v[222:225], v[68:71]
	v_mfma_f32_16x16x32_bf16 v[64:67], v[190:193], v[222:225], v[64:67]
	s_setprio 0
	s_barrier
; #define PG8_STAGE(bufoff, gbase, voff) do { _Pragma("unroll") for (int _i = 0; _i < 2; ++_i) \
;         __builtin_amdgcn_global_load_lds((const unsigned*)((const char*)(gbase) + (voff)[_i]), (PG8_LAS unsigned*)(lds + (bufoff) + ldsw + _i * 8192), 16, 0, 0); } while (0)
; #define PG8_LDA(dst, b, h) do { _Pragma("unroll") for (int m = 0; m < 4; ++m) _Pragma("unroll") for (int k = 0; k < 2; ++k) dst[m][k] = *(const PG8_LAS bf16x8*)(lds + PG8_SA(b, h) + aoff + m * 2048 + k * 1024); } while (0)
; #define PG8_MMA(ai, bj, At, Bt) do { __builtin_amdgcn_s_setprio(1); _Pragma("unroll") for (int m = 0; m < 4; ++m) _Pragma("unroll") for (int n = 0; n < 2; ++n) _Pragma("unroll") for (int k = 0; k < 2; ++k) \
;         acc[ai][bj][m][n] = __builtin_amdgcn_mfma_f32_16x16x32_bf16(Bt[n][k], At[m][k], acc[ai][bj][m][n], 0, 0, 0); __builtin_amdgcn_s_setprio(0); } while (0)
; #define PG8_WAIT_V(n) asm volatile("s_waitcnt vmcnt(" #n ")" ::: "memory")
; #define PG8_WAIT_L(n) asm volatile("s_waitcnt lgkmcnt(" #n ")" ::: "memory")
; #define PG8_BAR __builtin_amdgcn_s_barrier()
; #define PG8_SCHED __builtin_amdgcn_sched_barrier(0)
; template <class Epi, class Sched, bool ALIGN_EPI = false, bool SP2 = false>
; __device__ __forceinline__ void gemm_phase(PG8_LAS unsigned char* lds, const Gemm g, const Sched& S, const Epi& E) {
;     ...
;             PG8_LDA(At, 1, 1); PG8_STAGE(PG8_SB(1, 0), b3, voffB); PG8_STAGE(PG8_SB(1, 1), b3 + hstep, voffB); PG8_STAGE(PG8_SA(1, 0), a3, voffA);
;             PG8_WAIT_V(8); PG8_WAIT_L(0); PG8_BAR; PG8_MMA(1, 0, At, B0); PG8_MMA(1, 1, At, B1); PG8_BAR; PG8_SCHED;
;     ...
;         if constexpr (ALIGN_EPI) { if (wr == 0) PG8_BAR; }
	s_add_i32 s38, s59, s40
	v_lshl_add_u64 v[228:229], v[228:229], 0, s[12:13]
	s_mov_b32 m0, s38
	ds_read_b128 v[194:197], v173 offset:49152
	ds_read_b128 v[198:201], v173 offset:50176
	ds_read_b128 v[202:205], v173 offset:51200
	ds_read_b128 v[206:209], v173 offset:52224
	ds_read_b128 v[210:213], v173 offset:53248
	ds_read_b128 v[214:217], v173 offset:54272
	ds_read_b128 v[218:221], v173 offset:55296
	ds_read_b128 v[222:225], v173 offset:56320
	global_load_lds_dwordx4 v[228:229], off
	v_lshl_add_u64 v[228:229], v[230:231], 0, s[12:13]
	s_add_i32 m0, s38, 0x2000
	v_lshl_add_u64 v[164:165], v[164:165], 0, s[14:15]
	s_add_i32 s38, s60, s40
	global_load_lds_dwordx4 v[228:229], off
	v_lshl_add_u64 v[228:229], v[164:165], 0, v[150:151]
	s_mov_b32 m0, s38
	v_lshl_add_u64 v[164:165], v[164:165], 0, v[146:147]
	global_load_lds_dwordx4 v[228:229], off
	s_add_i32 m0, s38, 0x2000
	s_nop 0
	global_load_lds_dwordx4 v[164:165], off
	v_lshl_add_u64 v[164:165], v[232:233], 0, s[12:13]
	s_mov_b32 m0, s48
	s_nop 0
	global_load_lds_dwordx4 v[164:165], off
	v_lshl_add_u64 v[164:165], v[234:235], 0, s[12:13]
	s_mov_b32 m0, s49
	s_nop 0
	global_load_lds_dwordx4 v[164:165], off
	s_waitcnt vmcnt(8)
	s_waitcnt lgkmcnt(0)
	s_barrier
	s_setprio 1
	s_waitcnt lgkmcnt(0)
	v_mfma_f32_16x16x32_bf16 v[60:63], v[132:135], v[194:197], v[60:63]
	v_mfma_f32_16x16x32_bf16 v[56:59], v[140:143], v[194:197], v[56:59]
	v_mfma_f32_16x16x32_bf16 v[44:47], v[132:135], v[202:205], v[44:47]
	v_mfma_f32_16x16x32_bf16 v[40:43], v[140:143], v[202:205], v[40:43]
	v_mfma_f32_16x16x32_bf16 v[28:31], v[132:135], v[210:213], v[28:31]
	v_mfma_f32_16x16x32_bf16 v[24:27], v[140:143], v[210:213], v[24:27]
	v_mfma_f32_16x16x32_bf16 v[12:15], v[132:135], v[218:221], v[12:15]
	v_mfma_f32_16x16x32_bf16 v[8:11], v[140:143], v[218:221], v[8:11]
	v_mfma_f32_16x16x32_bf16 v[60:63], v[136:139], v[198:201], v[60:63]
	v_mfma_f32_16x16x32_bf16 v[56:59], v[174:177], v[198:201], v[56:59]
	v_mfma_f32_16x16x32_bf16 v[44:47], v[136:139], v[206:209], v[44:47]
	v_mfma_f32_16x16x32_bf16 v[40:43], v[174:177], v[206:209], v[40:43]
	v_mfma_f32_16x16x32_bf16 v[28:31], v[136:139], v[214:217], v[28:31]
	v_mfma_f32_16x16x32_bf16 v[24:27], v[174:177], v[214:217], v[24:27]
	v_mfma_f32_16x16x32_bf16 v[12:15], v[136:139], v[222:225], v[12:15]
	v_mfma_f32_16x16x32_bf16 v[8:11], v[174:177], v[222:225], v[8:11]
	v_mfma_f32_16x16x32_bf16 v[52:55], v[178:181], v[194:197], v[52:55]
	v_mfma_f32_16x16x32_bf16 v[48:51], v[186:189], v[194:197], v[48:51]
	v_mfma_f32_16x16x32_bf16 v[36:39], v[178:181], v[202:205], v[36:39]
	v_mfma_f32_16x16x32_bf16 v[32:35], v[186:189], v[202:205], v[32:35]
	v_mfma_f32_16x16x32_bf16 v[20:23], v[178:181], v[210:213], v[20:23]
	v_mfma_f32_16x16x32_bf16 v[16:19], v[186:189], v[210:213], v[16:19]
	v_mfma_f32_16x16x32_bf16 v[4:7], v[178:181], v[218:221], v[4:7]
	v_mfma_f32_16x16x32_bf16 v[0:3], v[186:189], v[218:221], v[0:3]
	v_mfma_f32_16x16x32_bf16 v[52:55], v[182:185], v[198:201], v[52:55]
	v_mfma_f32_16x16x32_bf16 v[48:51], v[190:193], v[198:201], v[48:51]
	v_mfma_f32_16x16x32_bf16 v[36:39], v[182:185], v[206:209], v[36:39]
	v_mfma_f32_16x16x32_bf16 v[32:35], v[190:193], v[206:209], v[32:35]
	v_mfma_f32_16x16x32_bf16 v[20:23], v[182:185], v[214:217], v[20:23]
	v_mfma_f32_16x16x32_bf16 v[16:19], v[190:193], v[214:217], v[16:19]
	v_mfma_f32_16x16x32_bf16 v[4:7], v[182:185], v[222:225], v[4:7]
	v_mfma_f32_16x16x32_bf16 v[0:3], v[190:193], v[222:225], v[0:3]
	s_setprio 0
	s_barrier
	s_add_i32 s21, s21, 2
	s_add_u32 s36, s36, 0x100
	s_addc_u32 s37, s37, 0
	s_cmp_gt_u32 s21, 13
	v_lshl_add_u64 v[130:131], v[130:131], 0, s[18:19]
	s_cbranch_scc0 .LBB0_907
	s_and_b64 vcc, exec, s[16:17]
	s_cbranch_vccz .LBB0_910
	s_barrier

; #define PG8_STAGE(bufoff, gbase, voff) do { _Pragma("unroll") for (int _i = 0; _i < 2; ++_i) \
;         __builtin_amdgcn_global_load_lds((const unsigned*)((const char*)(gbase) + (voff)[_i]), (PG8_LAS unsigned*)(lds + (bufoff) + ldsw + _i * 8192), 16, 0, 0); } while (0)
; #define PG8_LDA(dst, b, h) do { _Pragma("unroll") for (int m = 0; m < 4; ++m) _Pragma("unroll") for (int k = 0; k < 2; ++k) dst[m][k] = *(const PG8_LAS bf16x8*)(lds + PG8_SA(b, h) + aoff + m * 2048 + k * 1024); } while (0)
; #define PG8_LDB(dst, b, h) do { _Pragma("unroll") for (int n = 0; n < 2; ++n) _Pragma("unroll") for (int k = 0; k < 2; ++k) dst[n][k] = *(const PG8_LAS bf16x8*)(lds + PG8_SB(b, h) + boff + n * 2048 + k * 1024); } while (0)
; #define PG8_MMA(ai, bj, At, Bt) do { __builtin_amdgcn_s_setprio(1); _Pragma("unroll") for (int m = 0; m < 4; ++m) _Pragma("unroll") for (int n = 0; n < 2; ++n) _Pragma("unroll") for (int k = 0; k < 2; ++k) \
;         acc[ai][bj][m][n] = __builtin_amdgcn_mfma_f32_16x16x32_bf16(Bt[n][k], At[m][k], acc[ai][bj][m][n], 0, 0, 0); __builtin_amdgcn_s_setprio(0); } while (0)
; #define PG8_WAIT_V(n) asm volatile("s_waitcnt vmcnt(" #n ")" ::: "memory")
; #define PG8_WAIT_L(n) asm volatile("s_waitcnt lgkmcnt(" #n ")" ::: "memory")
; template <class Epi, class Sched, bool ALIGN_EPI = false, bool SP2 = false>
; __device__ __forceinline__ void gemm_phase(PG8_LAS unsigned char* lds, const Gemm g, const Sched& S, const Epi& E) {
;     ...
;             const bool last = (t == nt - 2);
;             const char* a1 = cA + (size_t)(t + 1) * kstep;
;             const char* a2 = last ? nA : cA + (size_t)(t + 2) * kstep; const char* b2 = last ? nB : cB + (size_t)(t + 2) * kstep;
;             const char* a3 = a2 + kstep; const char* b3 = b2 + kstep;
;             if (last && has_next) S.a_ready(nxt);
;             if constexpr (SP2) {
;             PG8_LDB(B0, 0, 0); PG8_LDB(B1, 0, 1); PG8_SCHED; PG8_LDA(At, 0, 0); PG8_STAGE(PG8_SA(1, 1), a1 + hstep, voffA);
;             PG8_WAIT_V(8); PG8_WAIT_L(0); PG8_BAR; PG8_MMA(0, 0, At, B0); PG8_MMA(0, 1, At, B1); PG8_BAR; PG8_SCHED;
;             PG8_LDA(At, 0, 1); PG8_STAGE(PG8_SB(0, 0), b2, voffB); PG8_STAGE(PG8_SB(0, 1), b2 + hstep, voffB); PG8_STAGE(PG8_SA(0, 0), a2, voffA);
;             PG8_WAIT_V(8); PG8_WAIT_L(0); PG8_BAR; PG8_MMA(1, 0, At, B0); PG8_MMA(1, 1, At, B1); PG8_BAR; PG8_SCHED;
.LBB0_1007:
	ds_read_b128 v[144:147], v169
	ds_read_b128 v[148:151], v169 offset:1024
	ds_read_b128 v[152:155], v169 offset:2048
	ds_read_b128 v[156:159], v169 offset:3072
	ds_read_b128 v[160:163], v170
	ds_read_b128 v[172:175], v170 offset:1024
	ds_read_b128 v[176:179], v170 offset:2048
	ds_read_b128 v[180:183], v170 offset:3072
	s_add_u32 s26, s22, 0xfff50080
	s_addc_u32 s27, s23, -1
	s_cmp_eq_u32 s53, 40
	s_cselect_b32 s29, s5, s27
	s_cselect_b32 s28, s4, s26
	s_cselect_b32 s27, s21, s52
	s_cselect_b32 s26, s20, s51
	v_lshl_add_u64 v[164:165], s[22:23], 0, v[136:137]
	s_add_i32 m0, s31, 0xc000
	ds_read_b128 v[184:187], v171
	ds_read_b128 v[188:191], v171 offset:1024
	ds_read_b128 v[192:195], v171 offset:2048
	ds_read_b128 v[196:199], v171 offset:3072
	ds_read_b128 v[200:203], v171 offset:4096
	ds_read_b128 v[204:207], v171 offset:5120
	ds_read_b128 v[208:211], v171 offset:6144
	ds_read_b128 v[212:215], v171 offset:7168
	global_load_lds_dwordx4 v[164:165], off
	v_lshl_add_u64 v[164:165], s[22:23], 0, v[138:139]
	s_add_i32 m0, s31, 0xe000
	s_nop 0
	global_load_lds_dwordx4 v[164:165], off
	s_waitcnt vmcnt(8)
	s_waitcnt lgkmcnt(0)
	s_barrier
	s_setprio 1
	s_waitcnt lgkmcnt(0)
	v_mfma_f32_16x16x32_bf16 v[124:127], v[144:147], v[184:187], v[124:127]
	v_mfma_f32_16x16x32_bf16 v[120:123], v[152:155], v[184:187], v[120:123]
	v_mfma_f32_16x16x32_bf16 v[108:111], v[144:147], v[192:195], v[108:111]
	v_mfma_f32_16x16x32_bf16 v[104:107], v[152:155], v[192:195], v[104:107]
	v_mfma_f32_16x16x32_bf16 v[92:95], v[144:147], v[200:203], v[92:95]
	v_mfma_f32_16x16x32_bf16 v[88:91], v[152:155], v[200:203], v[88:91]
	v_mfma_f32_16x16x32_bf16 v[76:79], v[144:147], v[208:211], v[76:79]
	v_mfma_f32_16x16x32_bf16 v[72:75], v[152:155], v[208:211], v[72:75]
	v_mfma_f32_16x16x32_bf16 v[124:127], v[148:151], v[188:191], v[124:127]
	v_mfma_f32_16x16x32_bf16 v[120:123], v[156:159], v[188:191], v[120:123]
	v_mfma_f32_16x16x32_bf16 v[108:111], v[148:151], v[196:199], v[108:111]
	v_mfma_f32_16x16x32_bf16 v[104:107], v[156:159], v[196:199], v[104:107]
	v_mfma_f32_16x16x32_bf16 v[92:95], v[148:151], v[204:207], v[92:95]
	v_mfma_f32_16x16x32_bf16 v[88:91], v[156:159], v[204:207], v[88:91]
	v_mfma_f32_16x16x32_bf16 v[76:79], v[148:151], v[212:215], v[76:79]
	v_mfma_f32_16x16x32_bf16 v[72:75], v[156:159], v[212:215], v[72:75]
	v_mfma_f32_16x16x32_bf16 v[116:119], v[160:163], v[184:187], v[116:119]
	v_mfma_f32_16x16x32_bf16 v[112:115], v[176:179], v[184:187], v[112:115]
	v_mfma_f32_16x16x32_bf16 v[100:103], v[160:163], v[192:195], v[100:103]
	v_mfma_f32_16x16x32_bf16 v[96:99], v[176:179], v[192:195], v[96:99]
	v_mfma_f32_16x16x32_bf16 v[84:87], v[160:163], v[200:203], v[84:87]
	v_mfma_f32_16x16x32_bf16 v[80:83], v[176:179], v[200:203], v[80:83]
	v_mfma_f32_16x16x32_bf16 v[68:71], v[160:163], v[208:211], v[68:71]
	v_mfma_f32_16x16x32_bf16 v[64:67], v[176:179], v[208:211], v[64:67]
	v_mfma_f32_16x16x32_bf16 v[116:119], v[172:175], v[188:191], v[116:119]
	v_mfma_f32_16x16x32_bf16 v[112:115], v[180:183], v[188:191], v[112:115]
	v_mfma_f32_16x16x32_bf16 v[100:103], v[172:175], v[196:199], v[100:103]
	v_mfma_f32_16x16x32_bf16 v[96:99], v[180:183], v[196:199], v[96:99]
	v_mfma_f32_16x16x32_bf16 v[84:87], v[172:175], v[204:207], v[84:87]
	v_mfma_f32_16x16x32_bf16 v[80:83], v[180:183], v[204:207], v[80:83]
	v_mfma_f32_16x16x32_bf16 v[68:71], v[172:175], v[212:215], v[68:71]
	v_mfma_f32_16x16x32_bf16 v[64:67], v[180:183], v[212:215], v[64:67]
	s_setprio 0
	s_barrier
	s_add_i32 s54, s45, s30
	v_lshl_add_u64 v[164:165], s[26:27], 0, v[130:131]
	s_mov_b32 m0, s54
	ds_read_b128 v[184:187], v171 offset:16384
	ds_read_b128 v[188:191], v171 offset:17408
	ds_read_b128 v[192:195], v171 offset:18432
	ds_read_b128 v[196:199], v171 offset:19456
	ds_read_b128 v[200:203], v171 offset:20480
	ds_read_b128 v[204:207], v171 offset:21504
	ds_read_b128 v[208:211], v171 offset:22528
	ds_read_b128 v[212:215], v171 offset:23552
	global_load_lds_dwordx4 v[164:165], off
	s_add_i32 m0, s54, 0x2000
	s_add_u32 s54, s26, 0xb0000
	v_lshl_add_u64 v[216:217], s[26:27], 0, v[134:135]
	s_addc_u32 s55, s27, 0
	s_add_i32 s56, s46, s30
	global_load_lds_dwordx4 v[216:217], off
	v_lshl_add_u64 v[218:219], s[54:55], 0, v[130:131]
	s_mov_b32 m0, s56
	v_lshl_add_u64 v[220:221], s[28:29], 0, v[132:133]
	global_load_lds_dwordx4 v[218:219], off
	v_lshl_add_u64 v[218:219], s[54:55], 0, v[134:135]
	s_add_i32 m0, s56, 0x2000
	s_nop 0
	global_load_lds_dwordx4 v[218:219], off
	v_lshl_add_u64 v[218:219], s[28:29], 0, v[128:129]
	s_mov_b32 m0, s31
	s_nop 0
	global_load_lds_dwordx4 v[218:219], off
	s_mov_b32 m0, s33
	s_nop 0
	global_load_lds_dwordx4 v[220:221], off
	s_waitcnt vmcnt(8)
	s_waitcnt lgkmcnt(0)
	s_barrier
; #define PG8_STAGE(bufoff, gbase, voff) do { _Pragma("unroll") for (int _i = 0; _i < 2; ++_i) \
;         __builtin_amdgcn_global_load_lds((const unsigned*)((const char*)(gbase) + (voff)[_i]), (PG8_LAS unsigned*)(lds + (bufoff) + ldsw + _i * 8192), 16, 0, 0); } while (0)
; #define PG8_LDA(dst, b, h) do { _Pragma("unroll") for (int m = 0; m < 4; ++m) _Pragma("unroll") for (int k = 0; k < 2; ++k) dst[m][k] = *(const PG8_LAS bf16x8*)(lds + PG8_SA(b, h) + aoff + m * 2048 + k * 1024); } while (0)
; #define PG8_LDB(dst, b, h) do { _Pragma("unroll") for (int n = 0; n < 2; ++n) _Pragma("unroll") for (int k = 0; k < 2; ++k) dst[n][k] = *(const PG8_LAS bf16x8*)(lds + PG8_SB(b, h) + boff + n * 2048 + k * 1024); } while (0)
; #define PG8_MMA(ai, bj, At, Bt) do { __builtin_amdgcn_s_setprio(1); _Pragma("unroll") for (int m = 0; m < 4; ++m) _Pragma("unroll") for (int n = 0; n < 2; ++n) _Pragma("unroll") for (int k = 0; k < 2; ++k) \
;         acc[ai][bj][m][n] = __builtin_amdgcn_mfma_f32_16x16x32_bf16(Bt[n][k], At[m][k], acc[ai][bj][m][n], 0, 0, 0); __builtin_amdgcn_s_setprio(0); } while (0)
; #define PG8_WAIT_V(n) asm volatile("s_waitcnt vmcnt(" #n ")" ::: "memory")
; #define PG8_WAIT_L(n) asm volatile("s_waitcnt lgkmcnt(" #n ")" ::: "memory")
; #define PG8_BAR __builtin_amdgcn_s_barrier()
; #define PG8_SCHED __builtin_amdgcn_sched_barrier(0)
; template <class Epi, class Sched, bool ALIGN_EPI = false, bool SP2 = false>
; __device__ __forceinline__ void gemm_phase(PG8_LAS unsigned char* lds, const Gemm g, const Sched& S, const Epi& E) {
;     ...
;             PG8_WAIT_V(8); PG8_WAIT_L(0); PG8_BAR; PG8_MMA(1, 0, At, B0); PG8_MMA(1, 1, At, B1); PG8_BAR; PG8_SCHED;
;             PG8_LDB(B0, 1, 0); PG8_LDB(B1, 1, 1); PG8_SCHED; PG8_LDA(At, 1, 0); PG8_STAGE(PG8_SA(0, 1), a2 + hstep, voffA);
;             PG8_WAIT_V(8); PG8_WAIT_L(0); PG8_BAR; PG8_MMA(0, 0, At, B0); PG8_MMA(0, 1, At, B1); PG8_BAR; PG8_SCHED;
	s_setprio 1
	s_waitcnt lgkmcnt(0)
	v_mfma_f32_16x16x32_bf16 v[60:63], v[144:147], v[184:187], v[60:63]
	v_mfma_f32_16x16x32_bf16 v[56:59], v[152:155], v[184:187], v[56:59]
	v_mfma_f32_16x16x32_bf16 v[44:47], v[144:147], v[192:195], v[44:47]
	v_mfma_f32_16x16x32_bf16 v[40:43], v[152:155], v[192:195], v[40:43]
	v_mfma_f32_16x16x32_bf16 v[28:31], v[144:147], v[200:203], v[28:31]
	v_mfma_f32_16x16x32_bf16 v[24:27], v[152:155], v[200:203], v[24:27]
	v_mfma_f32_16x16x32_bf16 v[12:15], v[144:147], v[208:211], v[12:15]
	v_mfma_f32_16x16x32_bf16 v[8:11], v[152:155], v[208:211], v[8:11]
	v_mfma_f32_16x16x32_bf16 v[60:63], v[148:151], v[188:191], v[60:63]
	v_mfma_f32_16x16x32_bf16 v[56:59], v[156:159], v[188:191], v[56:59]
	v_mfma_f32_16x16x32_bf16 v[44:47], v[148:151], v[196:199], v[44:47]
	v_mfma_f32_16x16x32_bf16 v[40:43], v[156:159], v[196:199], v[40:43]
	v_mfma_f32_16x16x32_bf16 v[28:31], v[148:151], v[204:207], v[28:31]
	v_mfma_f32_16x16x32_bf16 v[24:27], v[156:159], v[204:207], v[24:27]
	v_mfma_f32_16x16x32_bf16 v[12:15], v[148:151], v[212:215], v[12:15]
	v_mfma_f32_16x16x32_bf16 v[8:11], v[156:159], v[212:215], v[8:11]
	v_mfma_f32_16x16x32_bf16 v[52:55], v[160:163], v[184:187], v[52:55]
	v_mfma_f32_16x16x32_bf16 v[48:51], v[176:179], v[184:187], v[48:51]
	v_mfma_f32_16x16x32_bf16 v[36:39], v[160:163], v[192:195], v[36:39]
	v_mfma_f32_16x16x32_bf16 v[32:35], v[176:179], v[192:195], v[32:35]
	v_mfma_f32_16x16x32_bf16 v[20:23], v[160:163], v[200:203], v[20:23]
	v_mfma_f32_16x16x32_bf16 v[16:19], v[176:179], v[200:203], v[16:19]
	v_mfma_f32_16x16x32_bf16 v[4:7], v[160:163], v[208:211], v[4:7]
	v_mfma_f32_16x16x32_bf16 v[0:3], v[176:179], v[208:211], v[0:3]
	v_mfma_f32_16x16x32_bf16 v[52:55], v[172:175], v[188:191], v[52:55]
	v_mfma_f32_16x16x32_bf16 v[48:51], v[180:183], v[188:191], v[48:51]
	v_mfma_f32_16x16x32_bf16 v[36:39], v[172:175], v[196:199], v[36:39]
	v_mfma_f32_16x16x32_bf16 v[32:35], v[180:183], v[196:199], v[32:35]
	v_mfma_f32_16x16x32_bf16 v[20:23], v[172:175], v[204:207], v[20:23]
	v_mfma_f32_16x16x32_bf16 v[16:19], v[180:183], v[204:207], v[16:19]
	v_mfma_f32_16x16x32_bf16 v[4:7], v[172:175], v[212:215], v[4:7]
	v_mfma_f32_16x16x32_bf16 v[0:3], v[180:183], v[212:215], v[0:3]
	s_setprio 0
	s_barrier
	s_add_i32 s54, 0, 0x18000
	s_add_i32 s55, 0, 0x1c000
	v_add_u32_e32 v156, s54, v167
	v_add_u32_e32 v180, s55, v167
	ds_read_b128 v[144:147], v156
	ds_read_b128 v[148:151], v156 offset:1024
	ds_read_b128 v[152:155], v156 offset:2048
	ds_read_b128 v[156:159], v156 offset:3072
	ds_read_b128 v[160:163], v180
	ds_read_b128 v[172:175], v180 offset:1024
	ds_read_b128 v[176:179], v180 offset:2048
	ds_read_b128 v[180:183], v180 offset:3072
	s_add_u32 s28, s28, 0xb0000
	s_addc_u32 s29, s29, 0
	s_mov_b32 m0, s36
	v_lshl_add_u64 v[222:223], s[28:29], 0, v[128:129]
	ds_read_b128 v[184:187], v171 offset:32768
	ds_read_b128 v[188:191], v171 offset:33792
	ds_read_b128 v[192:195], v171 offset:34816
	ds_read_b128 v[196:199], v171 offset:35840
	ds_read_b128 v[200:203], v171 offset:36864
	ds_read_b128 v[204:207], v171 offset:37888
	ds_read_b128 v[208:211], v171 offset:38912
	ds_read_b128 v[212:215], v171 offset:39936
	global_load_lds_dwordx4 v[222:223], off
	v_lshl_add_u64 v[222:223], s[28:29], 0, v[132:133]
	s_mov_b32 m0, s37
	s_nop 0
	global_load_lds_dwordx4 v[222:223], off
	s_waitcnt vmcnt(8)
	s_waitcnt lgkmcnt(0)
	s_barrier
	s_setprio 1
	s_waitcnt lgkmcnt(0)
	v_mfma_f32_16x16x32_bf16 v[124:127], v[144:147], v[184:187], v[124:127]
	v_mfma_f32_16x16x32_bf16 v[120:123], v[152:155], v[184:187], v[120:123]
	v_mfma_f32_16x16x32_bf16 v[108:111], v[144:147], v[192:195], v[108:111]
	v_mfma_f32_16x16x32_bf16 v[104:107], v[152:155], v[192:195], v[104:107]
	v_mfma_f32_16x16x32_bf16 v[92:95], v[144:147], v[200:203], v[92:95]
	v_mfma_f32_16x16x32_bf16 v[88:91], v[152:155], v[200:203], v[88:91]
	v_mfma_f32_16x16x32_bf16 v[76:79], v[144:147], v[208:211], v[76:79]
	v_mfma_f32_16x16x32_bf16 v[72:75], v[152:155], v[208:211], v[72:75]
	v_mfma_f32_16x16x32_bf16 v[124:127], v[148:151], v[188:191], v[124:127]
	v_mfma_f32_16x16x32_bf16 v[120:123], v[156:159], v[188:191], v[120:123]
	v_mfma_f32_16x16x32_bf16 v[108:111], v[148:151], v[196:199], v[108:111]
	v_mfma_f32_16x16x32_bf16 v[104:107], v[156:159], v[196:199], v[104:107]
	v_mfma_f32_16x16x32_bf16 v[92:95], v[148:151], v[204:207], v[92:95]
	v_mfma_f32_16x16x32_bf16 v[88:91], v[156:159], v[204:207], v[88:91]
	v_mfma_f32_16x16x32_bf16 v[76:79], v[148:151], v[212:215], v[76:79]
	v_mfma_f32_16x16x32_bf16 v[72:75], v[156:159], v[212:215], v[72:75]
	v_mfma_f32_16x16x32_bf16 v[116:119], v[160:163], v[184:187], v[116:119]
	v_mfma_f32_16x16x32_bf16 v[112:115], v[176:179], v[184:187], v[112:115]
	v_mfma_f32_16x16x32_bf16 v[100:103], v[160:163], v[192:195], v[100:103]
	v_mfma_f32_16x16x32_bf16 v[96:99], v[176:179], v[192:195], v[96:99]
	v_mfma_f32_16x16x32_bf16 v[84:87], v[160:163], v[200:203], v[84:87]
	v_mfma_f32_16x16x32_bf16 v[80:83], v[176:179], v[200:203], v[80:83]
	v_mfma_f32_16x16x32_bf16 v[68:71], v[160:163], v[208:211], v[68:71]
	v_mfma_f32_16x16x32_bf16 v[64:67], v[176:179], v[208:211], v[64:67]
	v_mfma_f32_16x16x32_bf16 v[116:119], v[172:175], v[188:191], v[116:119]
	v_mfma_f32_16x16x32_bf16 v[112:115], v[180:183], v[188:191], v[112:115]
	v_mfma_f32_16x16x32_bf16 v[100:103], v[172:175], v[196:199], v[100:103]
	v_mfma_f32_16x16x32_bf16 v[96:99], v[180:183], v[196:199], v[96:99]
	v_mfma_f32_16x16x32_bf16 v[84:87], v[172:175], v[204:207], v[84:87]
	v_mfma_f32_16x16x32_bf16 v[80:83], v[180:183], v[204:207], v[80:83]
	v_mfma_f32_16x16x32_bf16 v[68:71], v[172:175], v[212:215], v[68:71]
	v_mfma_f32_16x16x32_bf16 v[64:67], v[180:183], v[212:215], v[64:67]
	s_setprio 0
	s_barrier
; #define PG8_STAGE(bufoff, gbase, voff) do { _Pragma("unroll") for (int _i = 0; _i < 2; ++_i) \
;         __builtin_amdgcn_global_load_lds((const unsigned*)((const char*)(gbase) + (voff)[_i]), (PG8_LAS unsigned*)(lds + (bufoff) + ldsw + _i * 8192), 16, 0, 0); } while (0)
; #define PG8_LDA(dst, b, h) do { _Pragma("unroll") for (int m = 0; m < 4; ++m) _Pragma("unroll") for (int k = 0; k < 2; ++k) dst[m][k] = *(const PG8_LAS bf16x8*)(lds + PG8_SA(b, h) + aoff + m * 2048 + k * 1024); } while (0)
; #define PG8_MMA(ai, bj, At, Bt) do { __builtin_amdgcn_s_setprio(1); _Pragma("unroll") for (int m = 0; m < 4; ++m) _Pragma("unroll") for (int n = 0; n < 2; ++n) _Pragma("unroll") for (int k = 0; k < 2; ++k) \
;         acc[ai][bj][m][n] = __builtin_amdgcn_mfma_f32_16x16x32_bf16(Bt[n][k], At[m][k], acc[ai][bj][m][n], 0, 0, 0); __builtin_amdgcn_s_setprio(0); } while (0)
; #define PG8_WAIT_V(n) asm volatile("s_waitcnt vmcnt(" #n ")" ::: "memory")
; #define PG8_WAIT_L(n) asm volatile("s_waitcnt lgkmcnt(" #n ")" ::: "memory")
; #define PG8_BAR __builtin_amdgcn_s_barrier()
; #define PG8_SCHED __builtin_amdgcn_sched_barrier(0)
; template <class Epi, class Sched, bool ALIGN_EPI = false, bool SP2 = false>
; __device__ __forceinline__ void gemm_phase(PG8_LAS unsigned char* lds, const Gemm g, const Sched& S, const Epi& E) {
;     ...
;             PG8_LDA(At, 1, 1); PG8_STAGE(PG8_SB(1, 0), b3, voffB); PG8_STAGE(PG8_SB(1, 1), b3 + hstep, voffB); PG8_STAGE(PG8_SA(1, 0), a3, voffA);
;             PG8_WAIT_V(8); PG8_WAIT_L(0); PG8_BAR; PG8_MMA(1, 0, At, B0); PG8_MMA(1, 1, At, B1); PG8_BAR; PG8_SCHED;
;     ...
;         if constexpr (ALIGN_EPI) { if (wr == 0) PG8_BAR; }
	s_add_i32 s28, s54, s30
	v_lshl_add_u64 v[164:165], v[164:165], 0, s[8:9]
	s_mov_b32 m0, s28
	ds_read_b128 v[184:187], v171 offset:49152
	ds_read_b128 v[188:191], v171 offset:50176
	ds_read_b128 v[192:195], v171 offset:51200
	ds_read_b128 v[196:199], v171 offset:52224
	ds_read_b128 v[200:203], v171 offset:53248
	ds_read_b128 v[204:207], v171 offset:54272
	ds_read_b128 v[208:211], v171 offset:55296
	ds_read_b128 v[212:215], v171 offset:56320
	global_load_lds_dwordx4 v[164:165], off
	s_add_i32 m0, s28, 0x2000
	s_add_u32 s26, s26, 0xb0080
	v_lshl_add_u64 v[164:165], v[216:217], 0, s[8:9]
	s_addc_u32 s27, s27, 0
	s_add_i32 s28, s55, s30
	global_load_lds_dwordx4 v[164:165], off
	v_lshl_add_u64 v[164:165], s[26:27], 0, v[130:131]
	s_mov_b32 m0, s28
	s_nop 0
	global_load_lds_dwordx4 v[164:165], off
	v_lshl_add_u64 v[164:165], s[26:27], 0, v[134:135]
	s_add_i32 m0, s28, 0x2000
	s_nop 0
	global_load_lds_dwordx4 v[164:165], off
	v_lshl_add_u64 v[164:165], v[218:219], 0, s[8:9]
	s_mov_b32 m0, s41
	s_nop 0
	global_load_lds_dwordx4 v[164:165], off
	v_lshl_add_u64 v[164:165], v[220:221], 0, s[8:9]
	s_mov_b32 m0, s43
	s_nop 0
	global_load_lds_dwordx4 v[164:165], off
	s_waitcnt vmcnt(8)
	s_waitcnt lgkmcnt(0)
	s_barrier
	s_setprio 1
	s_waitcnt lgkmcnt(0)
	v_mfma_f32_16x16x32_bf16 v[60:63], v[144:147], v[184:187], v[60:63]
	v_mfma_f32_16x16x32_bf16 v[56:59], v[152:155], v[184:187], v[56:59]
	v_mfma_f32_16x16x32_bf16 v[44:47], v[144:147], v[192:195], v[44:47]
	v_mfma_f32_16x16x32_bf16 v[40:43], v[152:155], v[192:195], v[40:43]
	v_mfma_f32_16x16x32_bf16 v[28:31], v[144:147], v[200:203], v[28:31]
	v_mfma_f32_16x16x32_bf16 v[24:27], v[152:155], v[200:203], v[24:27]
	v_mfma_f32_16x16x32_bf16 v[12:15], v[144:147], v[208:211], v[12:15]
	v_mfma_f32_16x16x32_bf16 v[8:11], v[152:155], v[208:211], v[8:11]
	v_mfma_f32_16x16x32_bf16 v[60:63], v[148:151], v[188:191], v[60:63]
	v_mfma_f32_16x16x32_bf16 v[56:59], v[156:159], v[188:191], v[56:59]
	v_mfma_f32_16x16x32_bf16 v[44:47], v[148:151], v[196:199], v[44:47]
	v_mfma_f32_16x16x32_bf16 v[40:43], v[156:159], v[196:199], v[40:43]
	v_mfma_f32_16x16x32_bf16 v[28:31], v[148:151], v[204:207], v[28:31]
	v_mfma_f32_16x16x32_bf16 v[24:27], v[156:159], v[204:207], v[24:27]
	v_mfma_f32_16x16x32_bf16 v[12:15], v[148:151], v[212:215], v[12:15]
	v_mfma_f32_16x16x32_bf16 v[8:11], v[156:159], v[212:215], v[8:11]
	v_mfma_f32_16x16x32_bf16 v[52:55], v[160:163], v[184:187], v[52:55]
	v_mfma_f32_16x16x32_bf16 v[48:51], v[176:179], v[184:187], v[48:51]
	v_mfma_f32_16x16x32_bf16 v[36:39], v[160:163], v[192:195], v[36:39]
	v_mfma_f32_16x16x32_bf16 v[32:35], v[176:179], v[192:195], v[32:35]
	v_mfma_f32_16x16x32_bf16 v[20:23], v[160:163], v[200:203], v[20:23]
	v_mfma_f32_16x16x32_bf16 v[16:19], v[176:179], v[200:203], v[16:19]
	v_mfma_f32_16x16x32_bf16 v[4:7], v[160:163], v[208:211], v[4:7]
	v_mfma_f32_16x16x32_bf16 v[0:3], v[176:179], v[208:211], v[0:3]
	v_mfma_f32_16x16x32_bf16 v[52:55], v[172:175], v[188:191], v[52:55]
	v_mfma_f32_16x16x32_bf16 v[48:51], v[180:183], v[188:191], v[48:51]
	v_mfma_f32_16x16x32_bf16 v[36:39], v[172:175], v[196:199], v[36:39]
	v_mfma_f32_16x16x32_bf16 v[32:35], v[180:183], v[196:199], v[32:35]
	v_mfma_f32_16x16x32_bf16 v[20:23], v[172:175], v[204:207], v[20:23]
	v_mfma_f32_16x16x32_bf16 v[16:19], v[180:183], v[204:207], v[16:19]
	v_mfma_f32_16x16x32_bf16 v[4:7], v[172:175], v[212:215], v[4:7]
	v_mfma_f32_16x16x32_bf16 v[0:3], v[180:183], v[212:215], v[0:3]
	s_setprio 0
	s_barrier
	s_add_i32 s53, s53, 2
	s_add_u32 s22, s22, 0x100
	s_addc_u32 s23, s23, 0
	s_add_u32 s51, s51, 0x100
	s_addc_u32 s52, s52, 0
	s_cmp_gt_u32 s53, 41
	s_cbranch_scc0 .LBB0_1007
	s_and_b64 vcc, exec, s[10:11]
	s_cbranch_vccz .LBB0_1010
	s_barrier
